# V2: SGPR-base LDS-DMA, DMA interleaved with first ds_reads (no s_nop separators), redundant lgkmcnt(0) and m0 save/restore removed
# speedup vs baseline: 1.0040x; 1.0040x over previous
; #define PG8_STAGE(bufoff, gbase, voff) do { _Pragma("unroll") for (int _i = 0; _i < 2; ++_i) \
;         __builtin_amdgcn_global_load_lds((const unsigned*)((const char*)(gbase) + (voff)[_i]), (PG8_LAS unsigned*)(lds + (bufoff) + ldsw + _i * 8192), 16, 0, 0); } while (0)
; #define PG8_LDA(dst, b, h) do { _Pragma("unroll") for (int m = 0; m < 4; ++m) _Pragma("unroll") for (int k = 0; k < 2; ++k) dst[m][k] = *(const PG8_LAS bf16x8*)(lds + PG8_SA(b, h) + aoff + m * 2048 + k * 1024); } while (0)
; #define PG8_LDB(dst, b, h) do { _Pragma("unroll") for (int n = 0; n < 2; ++n) _Pragma("unroll") for (int k = 0; k < 2; ++k) dst[n][k] = *(const PG8_LAS bf16x8*)(lds + PG8_SB(b, h) + boff + n * 2048 + k * 1024); } while (0)
; #define PG8_MMA(ai, bj, At, Bt) do { __builtin_amdgcn_s_setprio(1); _Pragma("unroll") for (int m = 0; m < 4; ++m) _Pragma("unroll") for (int n = 0; n < 2; ++n) _Pragma("unroll") for (int k = 0; k < 2; ++k) \
;         acc[ai][bj][m][n] = __builtin_amdgcn_mfma_f32_16x16x32_bf16(Bt[n][k], At[m][k], acc[ai][bj][m][n], 0, 0, 0); __builtin_amdgcn_s_setprio(0); } while (0)
; #define PG8_WAIT_V(n) asm volatile("s_waitcnt vmcnt(" #n ")" ::: "memory")
; #define PG8_WAIT_L(n) asm volatile("s_waitcnt lgkmcnt(" #n ")" ::: "memory")
; template <class Epi, class Sched, bool ALIGN_EPI = false, bool SP2 = false>
; __device__ __forceinline__ void gemm_phase(PG8_LAS unsigned char* lds, const Gemm g, const Sched& S, const Epi& E, int tid_in) {
;     ...
;             const bool last = (t == nt - 2);
;             const char* a1 = cA + (size_t)(t + 1) * kstep;
;             const char* a2 = last ? nA : cA + (size_t)(t + 2) * kstep; const char* b2 = last ? nB : cB + (size_t)(t + 2) * kstep;
;             const char* a3 = a2 + kstep; const char* b3 = b2 + kstep;
;             if (last && has_next) S.a_ready(nxt);
;             if constexpr (SP2) {
;             PG8_LDB(B0, 0, 0); PG8_LDB(B1, 0, 1); PG8_SCHED; PG8_LDA(At, 0, 0); PG8_STAGE(PG8_SA(1, 1), a1 + hstep, voffA);
;             PG8_WAIT_V(8); PG8_WAIT_L(0); PG8_BAR; PG8_MMA(0, 0, At, B0); PG8_MMA(0, 1, At, B1); PG8_BAR; PG8_SCHED;
;             PG8_LDA(At, 0, 1); PG8_STAGE(PG8_SB(0, 0), b2, voffB); PG8_STAGE(PG8_SB(0, 1), b2 + hstep, voffB); PG8_STAGE(PG8_SA(0, 0), a2, voffA);
;             PG8_WAIT_V(8); PG8_WAIT_L(0); PG8_BAR; PG8_MMA(1, 0, At, B0); PG8_MMA(1, 1, At, B1); PG8_BAR; PG8_SCHED;
.LBB0_376:
	s_add_u32 s26, s24, 0xfffc0080
	s_addc_u32 s27, s25, -1
	s_cmp_eq_u32 s56, 12
	s_cselect_b32 s29, s17, s27
	s_cselect_b32 s28, s52, s26
	s_cselect_b32 s27, s15, s55
	s_cselect_b32 s26, s53, s54
	s_add_i32 m0, s23, 0xc000
	ds_read_b128 v[150:153], v147
	global_load_lds_dwordx4 v136, s[24:25]
	s_add_i32 m0, s23, 0xe000
	ds_read_b128 v[154:157], v147 offset:1024
	global_load_lds_dwordx4 v138, s[24:25]
	ds_read_b128 v[158:161], v147 offset:2048
	ds_read_b128 v[162:165], v147 offset:3072
	ds_read_b128 v[166:169], v148
	ds_read_b128 v[170:173], v148 offset:1024
	ds_read_b128 v[174:177], v148 offset:2048
	ds_read_b128 v[178:181], v148 offset:3072
	ds_read_b128 v[182:185], v149
	ds_read_b128 v[186:189], v149 offset:1024
	ds_read_b128 v[190:193], v149 offset:2048
	ds_read_b128 v[194:197], v149 offset:3072
	ds_read_b128 v[198:201], v149 offset:4096
	ds_read_b128 v[202:205], v149 offset:5120
	ds_read_b128 v[206:209], v149 offset:6144
	ds_read_b128 v[210:213], v149 offset:7168
	s_waitcnt vmcnt(8)
	s_waitcnt lgkmcnt(0)
	s_barrier
	s_setprio 1
	v_mfma_f32_16x16x32_bf16 v[124:127], v[150:153], v[182:185], v[124:127]
	v_mfma_f32_16x16x32_bf16 v[120:123], v[158:161], v[182:185], v[120:123]
	v_mfma_f32_16x16x32_bf16 v[108:111], v[150:153], v[190:193], v[108:111]
	v_mfma_f32_16x16x32_bf16 v[104:107], v[158:161], v[190:193], v[104:107]
	v_mfma_f32_16x16x32_bf16 v[92:95], v[150:153], v[198:201], v[92:95]
	v_mfma_f32_16x16x32_bf16 v[88:91], v[158:161], v[198:201], v[88:91]
	v_mfma_f32_16x16x32_bf16 v[76:79], v[150:153], v[206:209], v[76:79]
	v_mfma_f32_16x16x32_bf16 v[72:75], v[158:161], v[206:209], v[72:75]
	v_mfma_f32_16x16x32_bf16 v[124:127], v[154:157], v[186:189], v[124:127]
	v_mfma_f32_16x16x32_bf16 v[120:123], v[162:165], v[186:189], v[120:123]
	v_mfma_f32_16x16x32_bf16 v[108:111], v[154:157], v[194:197], v[108:111]
	v_mfma_f32_16x16x32_bf16 v[104:107], v[162:165], v[194:197], v[104:107]
	v_mfma_f32_16x16x32_bf16 v[92:95], v[154:157], v[202:205], v[92:95]
	v_mfma_f32_16x16x32_bf16 v[88:91], v[162:165], v[202:205], v[88:91]
	v_mfma_f32_16x16x32_bf16 v[76:79], v[154:157], v[210:213], v[76:79]
	v_mfma_f32_16x16x32_bf16 v[72:75], v[162:165], v[210:213], v[72:75]
	s_setprio 0
	s_setprio 1
	v_mfma_f32_16x16x32_bf16 v[116:119], v[166:169], v[182:185], v[116:119]
	v_mfma_f32_16x16x32_bf16 v[112:115], v[174:177], v[182:185], v[112:115]
	v_mfma_f32_16x16x32_bf16 v[100:103], v[166:169], v[190:193], v[100:103]
	v_mfma_f32_16x16x32_bf16 v[96:99], v[174:177], v[190:193], v[96:99]
	v_mfma_f32_16x16x32_bf16 v[84:87], v[166:169], v[198:201], v[84:87]
	v_mfma_f32_16x16x32_bf16 v[80:83], v[174:177], v[198:201], v[80:83]
	v_mfma_f32_16x16x32_bf16 v[68:71], v[166:169], v[206:209], v[68:71]
	v_mfma_f32_16x16x32_bf16 v[64:67], v[174:177], v[206:209], v[64:67]
	v_mfma_f32_16x16x32_bf16 v[116:119], v[170:173], v[186:189], v[116:119]
	v_mfma_f32_16x16x32_bf16 v[112:115], v[178:181], v[186:189], v[112:115]
	v_mfma_f32_16x16x32_bf16 v[100:103], v[170:173], v[194:197], v[100:103]
	v_mfma_f32_16x16x32_bf16 v[96:99], v[178:181], v[194:197], v[96:99]
	v_mfma_f32_16x16x32_bf16 v[84:87], v[170:173], v[202:205], v[84:87]
	v_mfma_f32_16x16x32_bf16 v[80:83], v[178:181], v[202:205], v[80:83]
	v_mfma_f32_16x16x32_bf16 v[68:71], v[170:173], v[210:213], v[68:71]
	v_mfma_f32_16x16x32_bf16 v[64:67], v[178:181], v[210:213], v[64:67]
	s_setprio 0
	s_barrier
	s_add_u32 s98, s26, s10
	s_addc_u32 s99, s27, s11
	s_add_u32 s100, s28, s10
	s_addc_u32 s101, s29, s11
	s_add_i32 s57, s48, s34
	s_mov_b32 m0, s57
	ds_read_b128 v[182:185], v149 offset:16384
	global_load_lds_dwordx4 v132, s[26:27]
	s_add_i32 m0, s57, 0x2000
	s_add_u32 s60, s26, 0x40000
	s_addc_u32 s61, s27, 0
	s_add_i32 s57, s49, s34
	global_load_lds_dwordx4 v128, s[26:27]
	s_mov_b32 m0, s57
	ds_read_b128 v[186:189], v149 offset:17408
	global_load_lds_dwordx4 v132, s[60:61]
	s_add_i32 m0, s57, 0x2000
	ds_read_b128 v[190:193], v149 offset:18432
	global_load_lds_dwordx4 v128, s[60:61]
	s_mov_b32 m0, s23
	ds_read_b128 v[194:197], v149 offset:19456
	global_load_lds_dwordx4 v134, s[28:29]
	s_mov_b32 m0, s37
	ds_read_b128 v[198:201], v149 offset:20480
	global_load_lds_dwordx4 v130, s[28:29]
	ds_read_b128 v[202:205], v149 offset:21504
	ds_read_b128 v[206:209], v149 offset:22528
	ds_read_b128 v[210:213], v149 offset:23552
	s_waitcnt vmcnt(8)
	s_waitcnt lgkmcnt(0)
	s_barrier
	s_setprio 1
	v_mfma_f32_16x16x32_bf16 v[60:63], v[150:153], v[182:185], v[60:63]
	v_mfma_f32_16x16x32_bf16 v[56:59], v[158:161], v[182:185], v[56:59]
	v_mfma_f32_16x16x32_bf16 v[44:47], v[150:153], v[190:193], v[44:47]
	v_mfma_f32_16x16x32_bf16 v[40:43], v[158:161], v[190:193], v[40:43]
	v_mfma_f32_16x16x32_bf16 v[28:31], v[150:153], v[198:201], v[28:31]
	v_mfma_f32_16x16x32_bf16 v[24:27], v[158:161], v[198:201], v[24:27]
	v_mfma_f32_16x16x32_bf16 v[12:15], v[150:153], v[206:209], v[12:15]
	v_mfma_f32_16x16x32_bf16 v[8:11], v[158:161], v[206:209], v[8:11]
	v_mfma_f32_16x16x32_bf16 v[60:63], v[154:157], v[186:189], v[60:63]
	v_mfma_f32_16x16x32_bf16 v[56:59], v[162:165], v[186:189], v[56:59]
	v_mfma_f32_16x16x32_bf16 v[44:47], v[154:157], v[194:197], v[44:47]
	v_mfma_f32_16x16x32_bf16 v[40:43], v[162:165], v[194:197], v[40:43]
	v_mfma_f32_16x16x32_bf16 v[28:31], v[154:157], v[202:205], v[28:31]
	v_mfma_f32_16x16x32_bf16 v[24:27], v[162:165], v[202:205], v[24:27]
	v_mfma_f32_16x16x32_bf16 v[12:15], v[154:157], v[210:213], v[12:15]
	v_mfma_f32_16x16x32_bf16 v[8:11], v[162:165], v[210:213], v[8:11]
	s_setprio 0
	s_setprio 1
	v_mfma_f32_16x16x32_bf16 v[52:55], v[166:169], v[182:185], v[52:55]
	v_mfma_f32_16x16x32_bf16 v[48:51], v[174:177], v[182:185], v[48:51]
	v_mfma_f32_16x16x32_bf16 v[36:39], v[166:169], v[190:193], v[36:39]
	v_mfma_f32_16x16x32_bf16 v[32:35], v[174:177], v[190:193], v[32:35]
	v_mfma_f32_16x16x32_bf16 v[20:23], v[166:169], v[198:201], v[20:23]
	v_mfma_f32_16x16x32_bf16 v[16:19], v[174:177], v[198:201], v[16:19]
	v_mfma_f32_16x16x32_bf16 v[4:7], v[166:169], v[206:209], v[4:7]
	v_mfma_f32_16x16x32_bf16 v[0:3], v[174:177], v[206:209], v[0:3]
	v_mfma_f32_16x16x32_bf16 v[52:55], v[170:173], v[186:189], v[52:55]
	v_mfma_f32_16x16x32_bf16 v[48:51], v[178:181], v[186:189], v[48:51]
	v_mfma_f32_16x16x32_bf16 v[36:39], v[170:173], v[194:197], v[36:39]
	v_mfma_f32_16x16x32_bf16 v[32:35], v[178:181], v[194:197], v[32:35]
	v_mfma_f32_16x16x32_bf16 v[20:23], v[170:173], v[202:205], v[20:23]
	v_mfma_f32_16x16x32_bf16 v[16:19], v[178:181], v[202:205], v[16:19]
	v_mfma_f32_16x16x32_bf16 v[4:7], v[170:173], v[210:213], v[4:7]
	v_mfma_f32_16x16x32_bf16 v[0:3], v[178:181], v[210:213], v[0:3]
	s_setprio 0
	s_barrier
; #define PG8_STAGE(bufoff, gbase, voff) do { _Pragma("unroll") for (int _i = 0; _i < 2; ++_i) \
;         __builtin_amdgcn_global_load_lds((const unsigned*)((const char*)(gbase) + (voff)[_i]), (PG8_LAS unsigned*)(lds + (bufoff) + ldsw + _i * 8192), 16, 0, 0); } while (0)
; #define PG8_LDA(dst, b, h) do { _Pragma("unroll") for (int m = 0; m < 4; ++m) _Pragma("unroll") for (int k = 0; k < 2; ++k) dst[m][k] = *(const PG8_LAS bf16x8*)(lds + PG8_SA(b, h) + aoff + m * 2048 + k * 1024); } while (0)
; #define PG8_LDB(dst, b, h) do { _Pragma("unroll") for (int n = 0; n < 2; ++n) _Pragma("unroll") for (int k = 0; k < 2; ++k) dst[n][k] = *(const PG8_LAS bf16x8*)(lds + PG8_SB(b, h) + boff + n * 2048 + k * 1024); } while (0)
; #define PG8_MMA(ai, bj, At, Bt) do { __builtin_amdgcn_s_setprio(1); _Pragma("unroll") for (int m = 0; m < 4; ++m) _Pragma("unroll") for (int n = 0; n < 2; ++n) _Pragma("unroll") for (int k = 0; k < 2; ++k) \
;         acc[ai][bj][m][n] = __builtin_amdgcn_mfma_f32_16x16x32_bf16(Bt[n][k], At[m][k], acc[ai][bj][m][n], 0, 0, 0); __builtin_amdgcn_s_setprio(0); } while (0)
; #define PG8_WAIT_V(n) asm volatile("s_waitcnt vmcnt(" #n ")" ::: "memory")
; #define PG8_WAIT_L(n) asm volatile("s_waitcnt lgkmcnt(" #n ")" ::: "memory")
; #define PG8_BAR __builtin_amdgcn_s_barrier()
; #define PG8_SCHED __builtin_amdgcn_sched_barrier(0)
; template <class Epi, class Sched, bool ALIGN_EPI = false, bool SP2 = false>
; __device__ __forceinline__ void gemm_phase(PG8_LAS unsigned char* lds, const Gemm g, const Sched& S, const Epi& E, int tid_in) {
;     ...
;             PG8_LDB(B0, 1, 0); PG8_LDB(B1, 1, 1); PG8_SCHED; PG8_LDA(At, 1, 0); PG8_STAGE(PG8_SA(0, 1), a2 + hstep, voffA);
;             PG8_WAIT_V(8); PG8_WAIT_L(0); PG8_BAR; PG8_MMA(0, 0, At, B0); PG8_MMA(0, 1, At, B1); PG8_BAR; PG8_SCHED;
;             PG8_LDA(At, 1, 1); PG8_STAGE(PG8_SB(1, 0), b3, voffB); PG8_STAGE(PG8_SB(1, 1), b3 + hstep, voffB); PG8_STAGE(PG8_SA(1, 0), a3, voffA);
;             PG8_WAIT_V(8); PG8_WAIT_L(0); PG8_BAR; PG8_MMA(1, 0, At, B0); PG8_MMA(1, 1, At, B1); PG8_BAR; PG8_SCHED;
	s_add_i32 s57, 0, 0x18000
	s_add_i32 s59, 0, 0x1c000
	s_add_u32 s28, s28, 0x40000
	s_addc_u32 s29, s29, 0
	s_mov_b32 m0, s38
	s_nop 0
	global_load_lds_dwordx4 v134, s[28:29]
	s_mov_b32 m0, s39
	s_nop 0
	global_load_lds_dwordx4 v130, s[28:29]
	v_add_u32_e32 v162, s57, v145
	v_add_u32_e32 v178, s59, v145
	ds_read_b128 v[150:153], v162
	ds_read_b128 v[154:157], v162 offset:1024
	ds_read_b128 v[158:161], v162 offset:2048
	ds_read_b128 v[162:165], v162 offset:3072
	ds_read_b128 v[166:169], v178
	ds_read_b128 v[170:173], v178 offset:1024
	ds_read_b128 v[174:177], v178 offset:2048
	ds_read_b128 v[178:181], v178 offset:3072
	ds_read_b128 v[182:185], v149 offset:32768
	ds_read_b128 v[186:189], v149 offset:33792
	ds_read_b128 v[190:193], v149 offset:34816
	ds_read_b128 v[194:197], v149 offset:35840
	ds_read_b128 v[198:201], v149 offset:36864
	ds_read_b128 v[202:205], v149 offset:37888
	ds_read_b128 v[206:209], v149 offset:38912
	ds_read_b128 v[210:213], v149 offset:39936
	s_waitcnt vmcnt(8)
	s_waitcnt lgkmcnt(0)
	s_barrier
	s_setprio 1
	v_mfma_f32_16x16x32_bf16 v[124:127], v[150:153], v[182:185], v[124:127]
	v_mfma_f32_16x16x32_bf16 v[120:123], v[158:161], v[182:185], v[120:123]
	v_mfma_f32_16x16x32_bf16 v[108:111], v[150:153], v[190:193], v[108:111]
	v_mfma_f32_16x16x32_bf16 v[104:107], v[158:161], v[190:193], v[104:107]
	v_mfma_f32_16x16x32_bf16 v[92:95], v[150:153], v[198:201], v[92:95]
	v_mfma_f32_16x16x32_bf16 v[88:91], v[158:161], v[198:201], v[88:91]
	v_mfma_f32_16x16x32_bf16 v[76:79], v[150:153], v[206:209], v[76:79]
	v_mfma_f32_16x16x32_bf16 v[72:75], v[158:161], v[206:209], v[72:75]
	v_mfma_f32_16x16x32_bf16 v[124:127], v[154:157], v[186:189], v[124:127]
	v_mfma_f32_16x16x32_bf16 v[120:123], v[162:165], v[186:189], v[120:123]
	v_mfma_f32_16x16x32_bf16 v[108:111], v[154:157], v[194:197], v[108:111]
	v_mfma_f32_16x16x32_bf16 v[104:107], v[162:165], v[194:197], v[104:107]
	v_mfma_f32_16x16x32_bf16 v[92:95], v[154:157], v[202:205], v[92:95]
	v_mfma_f32_16x16x32_bf16 v[88:91], v[162:165], v[202:205], v[88:91]
	v_mfma_f32_16x16x32_bf16 v[76:79], v[154:157], v[210:213], v[76:79]
	v_mfma_f32_16x16x32_bf16 v[72:75], v[162:165], v[210:213], v[72:75]
	s_setprio 0
	s_setprio 1
	v_mfma_f32_16x16x32_bf16 v[116:119], v[166:169], v[182:185], v[116:119]
	v_mfma_f32_16x16x32_bf16 v[112:115], v[174:177], v[182:185], v[112:115]
	v_mfma_f32_16x16x32_bf16 v[100:103], v[166:169], v[190:193], v[100:103]
	v_mfma_f32_16x16x32_bf16 v[96:99], v[174:177], v[190:193], v[96:99]
	v_mfma_f32_16x16x32_bf16 v[84:87], v[166:169], v[198:201], v[84:87]
	v_mfma_f32_16x16x32_bf16 v[80:83], v[174:177], v[198:201], v[80:83]
	v_mfma_f32_16x16x32_bf16 v[68:71], v[166:169], v[206:209], v[68:71]
	v_mfma_f32_16x16x32_bf16 v[64:67], v[174:177], v[206:209], v[64:67]
	v_mfma_f32_16x16x32_bf16 v[116:119], v[170:173], v[186:189], v[116:119]
	v_mfma_f32_16x16x32_bf16 v[112:115], v[178:181], v[186:189], v[112:115]
	v_mfma_f32_16x16x32_bf16 v[100:103], v[170:173], v[194:197], v[100:103]
	v_mfma_f32_16x16x32_bf16 v[96:99], v[178:181], v[194:197], v[96:99]
	v_mfma_f32_16x16x32_bf16 v[84:87], v[170:173], v[202:205], v[84:87]
	v_mfma_f32_16x16x32_bf16 v[80:83], v[178:181], v[202:205], v[80:83]
	v_mfma_f32_16x16x32_bf16 v[68:71], v[170:173], v[210:213], v[68:71]
	v_mfma_f32_16x16x32_bf16 v[64:67], v[178:181], v[210:213], v[64:67]
	s_setprio 0
	s_barrier
	s_add_i32 s28, s57, s34
	s_mov_b32 m0, s28
	ds_read_b128 v[182:185], v149 offset:49152
	global_load_lds_dwordx4 v132, s[98:99]
	s_add_i32 m0, s28, 0x2000
	s_add_u32 s26, s26, 0x40080
	s_addc_u32 s27, s27, 0
	s_add_i32 s28, s59, s34
	global_load_lds_dwordx4 v128, s[98:99]
	s_mov_b32 m0, s28
	ds_read_b128 v[186:189], v149 offset:50176
	global_load_lds_dwordx4 v132, s[26:27]
	s_add_i32 m0, s28, 0x2000
	ds_read_b128 v[190:193], v149 offset:51200
	global_load_lds_dwordx4 v128, s[26:27]
	s_mov_b32 m0, s44
	ds_read_b128 v[194:197], v149 offset:52224
	global_load_lds_dwordx4 v134, s[100:101]
	s_mov_b32 m0, s45
	ds_read_b128 v[198:201], v149 offset:53248
	global_load_lds_dwordx4 v130, s[100:101]
	ds_read_b128 v[202:205], v149 offset:54272
	ds_read_b128 v[206:209], v149 offset:55296
	ds_read_b128 v[210:213], v149 offset:56320
	s_waitcnt vmcnt(8)
	s_waitcnt lgkmcnt(0)
	s_barrier
	s_setprio 1
	v_mfma_f32_16x16x32_bf16 v[60:63], v[150:153], v[182:185], v[60:63]
	v_mfma_f32_16x16x32_bf16 v[56:59], v[158:161], v[182:185], v[56:59]
	v_mfma_f32_16x16x32_bf16 v[44:47], v[150:153], v[190:193], v[44:47]
	v_mfma_f32_16x16x32_bf16 v[40:43], v[158:161], v[190:193], v[40:43]
	v_mfma_f32_16x16x32_bf16 v[28:31], v[150:153], v[198:201], v[28:31]
	v_mfma_f32_16x16x32_bf16 v[24:27], v[158:161], v[198:201], v[24:27]
	v_mfma_f32_16x16x32_bf16 v[12:15], v[150:153], v[206:209], v[12:15]
	v_mfma_f32_16x16x32_bf16 v[8:11], v[158:161], v[206:209], v[8:11]
	v_mfma_f32_16x16x32_bf16 v[60:63], v[154:157], v[186:189], v[60:63]
	v_mfma_f32_16x16x32_bf16 v[56:59], v[162:165], v[186:189], v[56:59]
	v_mfma_f32_16x16x32_bf16 v[44:47], v[154:157], v[194:197], v[44:47]
	v_mfma_f32_16x16x32_bf16 v[40:43], v[162:165], v[194:197], v[40:43]
	v_mfma_f32_16x16x32_bf16 v[28:31], v[154:157], v[202:205], v[28:31]
	v_mfma_f32_16x16x32_bf16 v[24:27], v[162:165], v[202:205], v[24:27]
	v_mfma_f32_16x16x32_bf16 v[12:15], v[154:157], v[210:213], v[12:15]
	v_mfma_f32_16x16x32_bf16 v[8:11], v[162:165], v[210:213], v[8:11]
	s_setprio 0
	s_setprio 1
	v_mfma_f32_16x16x32_bf16 v[52:55], v[166:169], v[182:185], v[52:55]
	v_mfma_f32_16x16x32_bf16 v[48:51], v[174:177], v[182:185], v[48:51]
	v_mfma_f32_16x16x32_bf16 v[36:39], v[166:169], v[190:193], v[36:39]
	v_mfma_f32_16x16x32_bf16 v[32:35], v[174:177], v[190:193], v[32:35]
	v_mfma_f32_16x16x32_bf16 v[20:23], v[166:169], v[198:201], v[20:23]
	v_mfma_f32_16x16x32_bf16 v[16:19], v[174:177], v[198:201], v[16:19]
	v_mfma_f32_16x16x32_bf16 v[4:7], v[166:169], v[206:209], v[4:7]
	v_mfma_f32_16x16x32_bf16 v[0:3], v[174:177], v[206:209], v[0:3]
	v_mfma_f32_16x16x32_bf16 v[52:55], v[170:173], v[186:189], v[52:55]
	v_mfma_f32_16x16x32_bf16 v[48:51], v[178:181], v[186:189], v[48:51]
	v_mfma_f32_16x16x32_bf16 v[36:39], v[170:173], v[194:197], v[36:39]
	v_mfma_f32_16x16x32_bf16 v[32:35], v[178:181], v[194:197], v[32:35]
	v_mfma_f32_16x16x32_bf16 v[20:23], v[170:173], v[202:205], v[20:23]
	v_mfma_f32_16x16x32_bf16 v[16:19], v[178:181], v[202:205], v[16:19]
	v_mfma_f32_16x16x32_bf16 v[4:7], v[170:173], v[210:213], v[4:7]
	v_mfma_f32_16x16x32_bf16 v[0:3], v[178:181], v[210:213], v[0:3]
	s_setprio 0
	s_barrier
	s_add_i32 s56, s56, 2
	s_add_u32 s24, s24, 0x100
	s_addc_u32 s25, s25, 0
	s_add_u32 s54, s54, 0x100
	s_addc_u32 s55, s55, 0
	s_cmp_gt_u32 s56, 13
	s_cbranch_scc0 .LBB0_376
	s_and_b64 vcc, exec, s[12:13]
	s_cbranch_vccz .LBB0_379
	s_barrier

; #define PG8_STAGE(bufoff, gbase, voff) do { _Pragma("unroll") for (int _i = 0; _i < 2; ++_i) \
;         __builtin_amdgcn_global_load_lds((const unsigned*)((const char*)(gbase) + (voff)[_i]), (PG8_LAS unsigned*)(lds + (bufoff) + ldsw + _i * 8192), 16, 0, 0); } while (0)
; #define PG8_LDA(dst, b, h) do { _Pragma("unroll") for (int m = 0; m < 4; ++m) _Pragma("unroll") for (int k = 0; k < 2; ++k) dst[m][k] = *(const PG8_LAS bf16x8*)(lds + PG8_SA(b, h) + aoff + m * 2048 + k * 1024); } while (0)
; #define PG8_LDB(dst, b, h) do { _Pragma("unroll") for (int n = 0; n < 2; ++n) _Pragma("unroll") for (int k = 0; k < 2; ++k) dst[n][k] = *(const PG8_LAS bf16x8*)(lds + PG8_SB(b, h) + boff + n * 2048 + k * 1024); } while (0)
; #define PG8_MMA(ai, bj, At, Bt) do { __builtin_amdgcn_s_setprio(1); _Pragma("unroll") for (int m = 0; m < 4; ++m) _Pragma("unroll") for (int n = 0; n < 2; ++n) _Pragma("unroll") for (int k = 0; k < 2; ++k) \
;         acc[ai][bj][m][n] = __builtin_amdgcn_mfma_f32_16x16x32_bf16(Bt[n][k], At[m][k], acc[ai][bj][m][n], 0, 0, 0); __builtin_amdgcn_s_setprio(0); } while (0)
; #define PG8_WAIT_V(n) asm volatile("s_waitcnt vmcnt(" #n ")" ::: "memory")
; #define PG8_WAIT_L(n) asm volatile("s_waitcnt lgkmcnt(" #n ")" ::: "memory")
; template <class Epi, class Sched, bool ALIGN_EPI = false, bool SP2 = false>
; __device__ __forceinline__ void gemm_phase(PG8_LAS unsigned char* lds, const Gemm g, const Sched& S, const Epi& E, int tid_in) {
;     ...
;             const bool last = (t == nt - 2);
;             const char* a1 = cA + (size_t)(t + 1) * kstep;
;             const char* a2 = last ? nA : cA + (size_t)(t + 2) * kstep; const char* b2 = last ? nB : cB + (size_t)(t + 2) * kstep;
;             const char* a3 = a2 + kstep; const char* b3 = b2 + kstep;
;             if (last && has_next) S.a_ready(nxt);
;             if constexpr (SP2) {
;             PG8_LDB(B0, 0, 0); PG8_LDB(B1, 0, 1); PG8_SCHED; PG8_LDA(At, 0, 0); PG8_STAGE(PG8_SA(1, 1), a1 + hstep, voffA);
;             PG8_WAIT_V(8); PG8_WAIT_L(0); PG8_BAR; PG8_MMA(0, 0, At, B0); PG8_MMA(0, 1, At, B1); PG8_BAR; PG8_SCHED;
;             PG8_LDA(At, 0, 1); PG8_STAGE(PG8_SB(0, 0), b2, voffB); PG8_STAGE(PG8_SB(0, 1), b2 + hstep, voffB); PG8_STAGE(PG8_SA(0, 0), a2, voffA);
;             PG8_WAIT_V(8); PG8_WAIT_L(0); PG8_BAR; PG8_MMA(1, 0, At, B0); PG8_MMA(1, 1, At, B1); PG8_BAR; PG8_SCHED;
.LBB0_461:
	s_add_u32 s6, s48, 0x100
	s_addc_u32 s7, s49, 0
	s_cmp_eq_u32 s76, 40
	s_cselect_b32 s53, s45, s7
	s_cselect_b32 s52, s44, s6
	s_cselect_b32 s51, s47, s75
	s_cselect_b32 s50, s46, s12
	s_add_i32 m0, s60, 0xc000
	ds_read_b128 v[128:131], v236
	global_load_lds_dwordx4 v200, s[48:49]
	s_add_i32 m0, s60, 0xe000
	ds_read_b128 v[132:135], v236 offset:1024
	global_load_lds_dwordx4 v202, s[48:49]
	ds_read_b128 v[136:139], v236 offset:2048
	ds_read_b128 v[140:143], v236 offset:3072
	ds_read_b128 v[144:147], v237
	ds_read_b128 v[148:151], v237 offset:1024
	ds_read_b128 v[152:155], v237 offset:2048
	ds_read_b128 v[156:159], v237 offset:3072
	ds_read_b128 v[160:163], v238
	ds_read_b128 v[164:167], v238 offset:1024
	ds_read_b128 v[168:171], v238 offset:2048
	ds_read_b128 v[172:175], v238 offset:3072
	ds_read_b128 v[176:179], v238 offset:4096
	ds_read_b128 v[180:183], v238 offset:5120
	ds_read_b128 v[184:187], v238 offset:6144
	ds_read_b128 v[188:191], v238 offset:7168
	s_waitcnt vmcnt(8)
	s_waitcnt lgkmcnt(0)
	s_barrier
	s_setprio 1
	v_mfma_f32_16x16x32_bf16 v[124:127], v[128:131], v[160:163], v[124:127]
	v_mfma_f32_16x16x32_bf16 v[120:123], v[136:139], v[160:163], v[120:123]
	v_mfma_f32_16x16x32_bf16 v[108:111], v[128:131], v[168:171], v[108:111]
	v_mfma_f32_16x16x32_bf16 v[104:107], v[136:139], v[168:171], v[104:107]
	v_mfma_f32_16x16x32_bf16 v[92:95], v[128:131], v[176:179], v[92:95]
	v_mfma_f32_16x16x32_bf16 v[88:91], v[136:139], v[176:179], v[88:91]
	v_mfma_f32_16x16x32_bf16 v[76:79], v[128:131], v[184:187], v[76:79]
	v_mfma_f32_16x16x32_bf16 v[72:75], v[136:139], v[184:187], v[72:75]
	v_mfma_f32_16x16x32_bf16 v[124:127], v[132:135], v[164:167], v[124:127]
	v_mfma_f32_16x16x32_bf16 v[120:123], v[140:143], v[164:167], v[120:123]
	v_mfma_f32_16x16x32_bf16 v[108:111], v[132:135], v[172:175], v[108:111]
	v_mfma_f32_16x16x32_bf16 v[104:107], v[140:143], v[172:175], v[104:107]
	v_mfma_f32_16x16x32_bf16 v[92:95], v[132:135], v[180:183], v[92:95]
	v_mfma_f32_16x16x32_bf16 v[88:91], v[140:143], v[180:183], v[88:91]
	v_mfma_f32_16x16x32_bf16 v[76:79], v[132:135], v[188:191], v[76:79]
	v_mfma_f32_16x16x32_bf16 v[72:75], v[140:143], v[188:191], v[72:75]
	s_setprio 0
	s_setprio 1
	v_mfma_f32_16x16x32_bf16 v[116:119], v[144:147], v[160:163], v[116:119]
	v_mfma_f32_16x16x32_bf16 v[112:115], v[152:155], v[160:163], v[112:115]
	v_mfma_f32_16x16x32_bf16 v[100:103], v[144:147], v[168:171], v[100:103]
	v_mfma_f32_16x16x32_bf16 v[96:99], v[152:155], v[168:171], v[96:99]
	v_mfma_f32_16x16x32_bf16 v[84:87], v[144:147], v[176:179], v[84:87]
	v_mfma_f32_16x16x32_bf16 v[80:83], v[152:155], v[176:179], v[80:83]
	v_mfma_f32_16x16x32_bf16 v[68:71], v[144:147], v[184:187], v[68:71]
	v_mfma_f32_16x16x32_bf16 v[64:67], v[152:155], v[184:187], v[64:67]
	v_mfma_f32_16x16x32_bf16 v[116:119], v[148:151], v[164:167], v[116:119]
	v_mfma_f32_16x16x32_bf16 v[112:115], v[156:159], v[164:167], v[112:115]
	v_mfma_f32_16x16x32_bf16 v[100:103], v[148:151], v[172:175], v[100:103]
	v_mfma_f32_16x16x32_bf16 v[96:99], v[156:159], v[172:175], v[96:99]
	v_mfma_f32_16x16x32_bf16 v[84:87], v[148:151], v[180:183], v[84:87]
	v_mfma_f32_16x16x32_bf16 v[80:83], v[156:159], v[180:183], v[80:83]
	v_mfma_f32_16x16x32_bf16 v[68:71], v[148:151], v[188:191], v[68:71]
	v_mfma_f32_16x16x32_bf16 v[64:67], v[156:159], v[188:191], v[64:67]
	s_setprio 0
	s_barrier
	s_add_u32 s98, s50, s22
	s_addc_u32 s99, s51, s23
	s_add_u32 s100, s52, s22
	s_addc_u32 s101, s53, s23
	s_add_i32 s48, s70, s59
	s_mov_b32 m0, s48
	ds_read_b128 v[160:163], v238 offset:16384
	global_load_lds_dwordx4 v194, s[50:51]
	s_add_i32 m0, s48, 0x2000
	s_add_u32 s48, s50, 0xb0000
	s_addc_u32 s49, s51, 0
	s_add_i32 s77, s71, s59
	global_load_lds_dwordx4 v198, s[50:51]
	s_mov_b32 m0, s77
	ds_read_b128 v[164:167], v238 offset:17408
	global_load_lds_dwordx4 v194, s[48:49]
	s_add_i32 m0, s77, 0x2000
	ds_read_b128 v[168:171], v238 offset:18432
	global_load_lds_dwordx4 v198, s[48:49]
	s_mov_b32 m0, s60
	ds_read_b128 v[172:175], v238 offset:19456
	global_load_lds_dwordx4 v192, s[52:53]
	s_mov_b32 m0, s61
	ds_read_b128 v[176:179], v238 offset:20480
	global_load_lds_dwordx4 v196, s[52:53]
	ds_read_b128 v[180:183], v238 offset:21504
	ds_read_b128 v[184:187], v238 offset:22528
	ds_read_b128 v[188:191], v238 offset:23552
	s_waitcnt vmcnt(8)
	s_waitcnt lgkmcnt(0)
	s_barrier
	s_setprio 1
	v_mfma_f32_16x16x32_bf16 v[60:63], v[128:131], v[160:163], v[60:63]
	v_mfma_f32_16x16x32_bf16 v[56:59], v[136:139], v[160:163], v[56:59]
	v_mfma_f32_16x16x32_bf16 v[44:47], v[128:131], v[168:171], v[44:47]
	v_mfma_f32_16x16x32_bf16 v[40:43], v[136:139], v[168:171], v[40:43]
	v_mfma_f32_16x16x32_bf16 v[28:31], v[128:131], v[176:179], v[28:31]
	v_mfma_f32_16x16x32_bf16 v[24:27], v[136:139], v[176:179], v[24:27]
	v_mfma_f32_16x16x32_bf16 v[12:15], v[128:131], v[184:187], v[12:15]
	v_mfma_f32_16x16x32_bf16 v[8:11], v[136:139], v[184:187], v[8:11]
	v_mfma_f32_16x16x32_bf16 v[60:63], v[132:135], v[164:167], v[60:63]
	v_mfma_f32_16x16x32_bf16 v[56:59], v[140:143], v[164:167], v[56:59]
	v_mfma_f32_16x16x32_bf16 v[44:47], v[132:135], v[172:175], v[44:47]
	v_mfma_f32_16x16x32_bf16 v[40:43], v[140:143], v[172:175], v[40:43]
	v_mfma_f32_16x16x32_bf16 v[28:31], v[132:135], v[180:183], v[28:31]
	v_mfma_f32_16x16x32_bf16 v[24:27], v[140:143], v[180:183], v[24:27]
	v_mfma_f32_16x16x32_bf16 v[12:15], v[132:135], v[188:191], v[12:15]
	v_mfma_f32_16x16x32_bf16 v[8:11], v[140:143], v[188:191], v[8:11]
	s_setprio 0
	s_setprio 1
	v_mfma_f32_16x16x32_bf16 v[52:55], v[144:147], v[160:163], v[52:55]
	v_mfma_f32_16x16x32_bf16 v[48:51], v[152:155], v[160:163], v[48:51]
	v_mfma_f32_16x16x32_bf16 v[36:39], v[144:147], v[168:171], v[36:39]
	v_mfma_f32_16x16x32_bf16 v[32:35], v[152:155], v[168:171], v[32:35]
	v_mfma_f32_16x16x32_bf16 v[20:23], v[144:147], v[176:179], v[20:23]
	v_mfma_f32_16x16x32_bf16 v[16:19], v[152:155], v[176:179], v[16:19]
	v_mfma_f32_16x16x32_bf16 v[4:7], v[144:147], v[184:187], v[4:7]
	v_mfma_f32_16x16x32_bf16 v[0:3], v[152:155], v[184:187], v[0:3]
	v_mfma_f32_16x16x32_bf16 v[52:55], v[148:151], v[164:167], v[52:55]
	v_mfma_f32_16x16x32_bf16 v[48:51], v[156:159], v[164:167], v[48:51]
	v_mfma_f32_16x16x32_bf16 v[36:39], v[148:151], v[172:175], v[36:39]
	v_mfma_f32_16x16x32_bf16 v[32:35], v[156:159], v[172:175], v[32:35]
	v_mfma_f32_16x16x32_bf16 v[20:23], v[148:151], v[180:183], v[20:23]
	v_mfma_f32_16x16x32_bf16 v[16:19], v[156:159], v[180:183], v[16:19]
	v_mfma_f32_16x16x32_bf16 v[4:7], v[148:151], v[188:191], v[4:7]
	v_mfma_f32_16x16x32_bf16 v[0:3], v[156:159], v[188:191], v[0:3]
	s_setprio 0
	s_barrier
; #define PG8_STAGE(bufoff, gbase, voff) do { _Pragma("unroll") for (int _i = 0; _i < 2; ++_i) \
;         __builtin_amdgcn_global_load_lds((const unsigned*)((const char*)(gbase) + (voff)[_i]), (PG8_LAS unsigned*)(lds + (bufoff) + ldsw + _i * 8192), 16, 0, 0); } while (0)
; #define PG8_LDA(dst, b, h) do { _Pragma("unroll") for (int m = 0; m < 4; ++m) _Pragma("unroll") for (int k = 0; k < 2; ++k) dst[m][k] = *(const PG8_LAS bf16x8*)(lds + PG8_SA(b, h) + aoff + m * 2048 + k * 1024); } while (0)
; #define PG8_LDB(dst, b, h) do { _Pragma("unroll") for (int n = 0; n < 2; ++n) _Pragma("unroll") for (int k = 0; k < 2; ++k) dst[n][k] = *(const PG8_LAS bf16x8*)(lds + PG8_SB(b, h) + boff + n * 2048 + k * 1024); } while (0)
; #define PG8_MMA(ai, bj, At, Bt) do { __builtin_amdgcn_s_setprio(1); _Pragma("unroll") for (int m = 0; m < 4; ++m) _Pragma("unroll") for (int n = 0; n < 2; ++n) _Pragma("unroll") for (int k = 0; k < 2; ++k) \
;         acc[ai][bj][m][n] = __builtin_amdgcn_mfma_f32_16x16x32_bf16(Bt[n][k], At[m][k], acc[ai][bj][m][n], 0, 0, 0); __builtin_amdgcn_s_setprio(0); } while (0)
; #define PG8_WAIT_V(n) asm volatile("s_waitcnt vmcnt(" #n ")" ::: "memory")
; #define PG8_WAIT_L(n) asm volatile("s_waitcnt lgkmcnt(" #n ")" ::: "memory")
; #define PG8_BAR __builtin_amdgcn_s_barrier()
; #define PG8_SCHED __builtin_amdgcn_sched_barrier(0)
; template <class Epi, class Sched, bool ALIGN_EPI = false, bool SP2 = false>
; __device__ __forceinline__ void gemm_phase(PG8_LAS unsigned char* lds, const Gemm g, const Sched& S, const Epi& E, int tid_in) {
;     ...
;             PG8_LDB(B0, 1, 0); PG8_LDB(B1, 1, 1); PG8_SCHED; PG8_LDA(At, 1, 0); PG8_STAGE(PG8_SA(0, 1), a2 + hstep, voffA);
;             PG8_WAIT_V(8); PG8_WAIT_L(0); PG8_BAR; PG8_MMA(0, 0, At, B0); PG8_MMA(0, 1, At, B1); PG8_BAR; PG8_SCHED;
;             PG8_LDA(At, 1, 1); PG8_STAGE(PG8_SB(1, 0), b3, voffB); PG8_STAGE(PG8_SB(1, 1), b3 + hstep, voffB); PG8_STAGE(PG8_SA(1, 0), a3, voffA);
;             PG8_WAIT_V(8); PG8_WAIT_L(0); PG8_BAR; PG8_MMA(1, 0, At, B0); PG8_MMA(1, 1, At, B1); PG8_BAR; PG8_SCHED;
	s_add_i32 s77, 0, 0x18000
	s_add_i32 s78, 0, 0x1c000
	s_add_u32 s48, s52, 0xb0000
	s_addc_u32 s49, s53, 0
	s_mov_b32 m0, s62
	s_nop 0
	global_load_lds_dwordx4 v192, s[48:49]
	s_mov_b32 m0, s63
	s_nop 0
	global_load_lds_dwordx4 v196, s[48:49]
	v_add_u32_e32 v140, s77, v232
	v_add_u32_e32 v156, s78, v232
	ds_read_b128 v[128:131], v140
	ds_read_b128 v[132:135], v140 offset:1024
	ds_read_b128 v[136:139], v140 offset:2048
	ds_read_b128 v[140:143], v140 offset:3072
	ds_read_b128 v[144:147], v156
	ds_read_b128 v[148:151], v156 offset:1024
	ds_read_b128 v[152:155], v156 offset:2048
	ds_read_b128 v[156:159], v156 offset:3072
	ds_read_b128 v[160:163], v238 offset:32768
	ds_read_b128 v[164:167], v238 offset:33792
	ds_read_b128 v[168:171], v238 offset:34816
	ds_read_b128 v[172:175], v238 offset:35840
	ds_read_b128 v[176:179], v238 offset:36864
	ds_read_b128 v[180:183], v238 offset:37888
	ds_read_b128 v[184:187], v238 offset:38912
	ds_read_b128 v[188:191], v238 offset:39936
	s_waitcnt vmcnt(8)
	s_waitcnt lgkmcnt(0)
	s_barrier
	s_setprio 1
	v_mfma_f32_16x16x32_bf16 v[124:127], v[128:131], v[160:163], v[124:127]
	v_mfma_f32_16x16x32_bf16 v[120:123], v[136:139], v[160:163], v[120:123]
	v_mfma_f32_16x16x32_bf16 v[108:111], v[128:131], v[168:171], v[108:111]
	v_mfma_f32_16x16x32_bf16 v[104:107], v[136:139], v[168:171], v[104:107]
	v_mfma_f32_16x16x32_bf16 v[92:95], v[128:131], v[176:179], v[92:95]
	v_mfma_f32_16x16x32_bf16 v[88:91], v[136:139], v[176:179], v[88:91]
	v_mfma_f32_16x16x32_bf16 v[76:79], v[128:131], v[184:187], v[76:79]
	v_mfma_f32_16x16x32_bf16 v[72:75], v[136:139], v[184:187], v[72:75]
	v_mfma_f32_16x16x32_bf16 v[124:127], v[132:135], v[164:167], v[124:127]
	v_mfma_f32_16x16x32_bf16 v[120:123], v[140:143], v[164:167], v[120:123]
	v_mfma_f32_16x16x32_bf16 v[108:111], v[132:135], v[172:175], v[108:111]
	v_mfma_f32_16x16x32_bf16 v[104:107], v[140:143], v[172:175], v[104:107]
	v_mfma_f32_16x16x32_bf16 v[92:95], v[132:135], v[180:183], v[92:95]
	v_mfma_f32_16x16x32_bf16 v[88:91], v[140:143], v[180:183], v[88:91]
	v_mfma_f32_16x16x32_bf16 v[76:79], v[132:135], v[188:191], v[76:79]
	v_mfma_f32_16x16x32_bf16 v[72:75], v[140:143], v[188:191], v[72:75]
	s_setprio 0
	s_setprio 1
	v_mfma_f32_16x16x32_bf16 v[116:119], v[144:147], v[160:163], v[116:119]
	v_mfma_f32_16x16x32_bf16 v[112:115], v[152:155], v[160:163], v[112:115]
	v_mfma_f32_16x16x32_bf16 v[100:103], v[144:147], v[168:171], v[100:103]
	v_mfma_f32_16x16x32_bf16 v[96:99], v[152:155], v[168:171], v[96:99]
	v_mfma_f32_16x16x32_bf16 v[84:87], v[144:147], v[176:179], v[84:87]
	v_mfma_f32_16x16x32_bf16 v[80:83], v[152:155], v[176:179], v[80:83]
	v_mfma_f32_16x16x32_bf16 v[68:71], v[144:147], v[184:187], v[68:71]
	v_mfma_f32_16x16x32_bf16 v[64:67], v[152:155], v[184:187], v[64:67]
	v_mfma_f32_16x16x32_bf16 v[116:119], v[148:151], v[164:167], v[116:119]
	v_mfma_f32_16x16x32_bf16 v[112:115], v[156:159], v[164:167], v[112:115]
	v_mfma_f32_16x16x32_bf16 v[100:103], v[148:151], v[172:175], v[100:103]
	v_mfma_f32_16x16x32_bf16 v[96:99], v[156:159], v[172:175], v[96:99]
	v_mfma_f32_16x16x32_bf16 v[84:87], v[148:151], v[180:183], v[84:87]
	v_mfma_f32_16x16x32_bf16 v[80:83], v[156:159], v[180:183], v[80:83]
	v_mfma_f32_16x16x32_bf16 v[68:71], v[148:151], v[188:191], v[68:71]
	v_mfma_f32_16x16x32_bf16 v[64:67], v[156:159], v[188:191], v[64:67]
	s_setprio 0
	s_barrier
	s_add_i32 s48, s77, s59
	s_mov_b32 m0, s48
	ds_read_b128 v[160:163], v238 offset:49152
	global_load_lds_dwordx4 v194, s[98:99]
	s_add_i32 m0, s48, 0x2000
	s_add_u32 s48, s50, 0xb0080
	s_addc_u32 s49, s51, 0
	s_add_i32 s50, s78, s59
	global_load_lds_dwordx4 v198, s[98:99]
	s_mov_b32 m0, s50
	ds_read_b128 v[164:167], v238 offset:50176
	global_load_lds_dwordx4 v194, s[48:49]
	s_add_i32 m0, s50, 0x2000
	ds_read_b128 v[168:171], v238 offset:51200
	global_load_lds_dwordx4 v198, s[48:49]
	s_mov_b32 m0, s65
	ds_read_b128 v[172:175], v238 offset:52224
	global_load_lds_dwordx4 v192, s[100:101]
	s_mov_b32 m0, s67
	ds_read_b128 v[176:179], v238 offset:53248
	global_load_lds_dwordx4 v196, s[100:101]
	ds_read_b128 v[180:183], v238 offset:54272
	ds_read_b128 v[184:187], v238 offset:55296
	ds_read_b128 v[188:191], v238 offset:56320
	s_waitcnt vmcnt(8)
	s_waitcnt lgkmcnt(0)
	s_barrier
	s_setprio 1
	v_mfma_f32_16x16x32_bf16 v[60:63], v[128:131], v[160:163], v[60:63]
	v_mfma_f32_16x16x32_bf16 v[56:59], v[136:139], v[160:163], v[56:59]
	v_mfma_f32_16x16x32_bf16 v[44:47], v[128:131], v[168:171], v[44:47]
	v_mfma_f32_16x16x32_bf16 v[40:43], v[136:139], v[168:171], v[40:43]
	v_mfma_f32_16x16x32_bf16 v[28:31], v[128:131], v[176:179], v[28:31]
	v_mfma_f32_16x16x32_bf16 v[24:27], v[136:139], v[176:179], v[24:27]
	v_mfma_f32_16x16x32_bf16 v[12:15], v[128:131], v[184:187], v[12:15]
	v_mfma_f32_16x16x32_bf16 v[8:11], v[136:139], v[184:187], v[8:11]
	v_mfma_f32_16x16x32_bf16 v[60:63], v[132:135], v[164:167], v[60:63]
	v_mfma_f32_16x16x32_bf16 v[56:59], v[140:143], v[164:167], v[56:59]
	v_mfma_f32_16x16x32_bf16 v[44:47], v[132:135], v[172:175], v[44:47]
	v_mfma_f32_16x16x32_bf16 v[40:43], v[140:143], v[172:175], v[40:43]
	v_mfma_f32_16x16x32_bf16 v[28:31], v[132:135], v[180:183], v[28:31]
	v_mfma_f32_16x16x32_bf16 v[24:27], v[140:143], v[180:183], v[24:27]
	v_mfma_f32_16x16x32_bf16 v[12:15], v[132:135], v[188:191], v[12:15]
	v_mfma_f32_16x16x32_bf16 v[8:11], v[140:143], v[188:191], v[8:11]
	s_setprio 0
	s_setprio 1
	v_mfma_f32_16x16x32_bf16 v[52:55], v[144:147], v[160:163], v[52:55]
	v_mfma_f32_16x16x32_bf16 v[48:51], v[152:155], v[160:163], v[48:51]
	v_mfma_f32_16x16x32_bf16 v[36:39], v[144:147], v[168:171], v[36:39]
	v_mfma_f32_16x16x32_bf16 v[32:35], v[152:155], v[168:171], v[32:35]
	v_mfma_f32_16x16x32_bf16 v[20:23], v[144:147], v[176:179], v[20:23]
	v_mfma_f32_16x16x32_bf16 v[16:19], v[152:155], v[176:179], v[16:19]
	v_mfma_f32_16x16x32_bf16 v[4:7], v[144:147], v[184:187], v[4:7]
	v_mfma_f32_16x16x32_bf16 v[0:3], v[152:155], v[184:187], v[0:3]
	v_mfma_f32_16x16x32_bf16 v[52:55], v[148:151], v[164:167], v[52:55]
	v_mfma_f32_16x16x32_bf16 v[48:51], v[156:159], v[164:167], v[48:51]
	v_mfma_f32_16x16x32_bf16 v[36:39], v[148:151], v[172:175], v[36:39]
	v_mfma_f32_16x16x32_bf16 v[32:35], v[156:159], v[172:175], v[32:35]
	v_mfma_f32_16x16x32_bf16 v[20:23], v[148:151], v[180:183], v[20:23]
	v_mfma_f32_16x16x32_bf16 v[16:19], v[156:159], v[180:183], v[16:19]
	v_mfma_f32_16x16x32_bf16 v[4:7], v[148:151], v[188:191], v[4:7]
	v_mfma_f32_16x16x32_bf16 v[0:3], v[156:159], v[188:191], v[0:3]
	s_setprio 0
	s_barrier
	s_add_i32 s76, s76, 2
	s_add_u32 s12, s12, 0x100
	s_addc_u32 s75, s75, 0
	s_cmp_gt_u32 s76, 41
	s_mov_b64 s[48:49], s[6:7]
	s_cbranch_scc0 .LBB0_461
	s_and_b64 vcc, exec, s[24:25]
	s_cbranch_vccz .LBB0_464
	s_barrier

; #define PG8_STAGE(bufoff, gbase, voff) do { _Pragma("unroll") for (int _i = 0; _i < 2; ++_i) \
;         __builtin_amdgcn_global_load_lds((const unsigned*)((const char*)(gbase) + (voff)[_i]), (PG8_LAS unsigned*)(lds + (bufoff) + ldsw + _i * 8192), 16, 0, 0); } while (0)
; #define PG8_LDA(dst, b, h) do { _Pragma("unroll") for (int m = 0; m < 4; ++m) _Pragma("unroll") for (int k = 0; k < 2; ++k) dst[m][k] = *(const PG8_LAS bf16x8*)(lds + PG8_SA(b, h) + aoff + m * 2048 + k * 1024); } while (0)
; #define PG8_LDB(dst, b, h) do { _Pragma("unroll") for (int n = 0; n < 2; ++n) _Pragma("unroll") for (int k = 0; k < 2; ++k) dst[n][k] = *(const PG8_LAS bf16x8*)(lds + PG8_SB(b, h) + boff + n * 2048 + k * 1024); } while (0)
; #define PG8_MMA(ai, bj, At, Bt) do { __builtin_amdgcn_s_setprio(1); _Pragma("unroll") for (int m = 0; m < 4; ++m) _Pragma("unroll") for (int n = 0; n < 2; ++n) _Pragma("unroll") for (int k = 0; k < 2; ++k) \
;         acc[ai][bj][m][n] = __builtin_amdgcn_mfma_f32_16x16x32_bf16(Bt[n][k], At[m][k], acc[ai][bj][m][n], 0, 0, 0); __builtin_amdgcn_s_setprio(0); } while (0)
; #define PG8_WAIT_V(n) asm volatile("s_waitcnt vmcnt(" #n ")" ::: "memory")
; #define PG8_WAIT_L(n) asm volatile("s_waitcnt lgkmcnt(" #n ")" ::: "memory")
; template <class Epi, class Sched, bool ALIGN_EPI = false, bool SP2 = false>
; __device__ __forceinline__ void gemm_phase(PG8_LAS unsigned char* lds, const Gemm g, const Sched& S, const Epi& E, int tid_in) {
;     ...
;             const bool last = (t == nt - 2);
;             const char* a1 = cA + (size_t)(t + 1) * kstep;
;             const char* a2 = last ? nA : cA + (size_t)(t + 2) * kstep; const char* b2 = last ? nB : cB + (size_t)(t + 2) * kstep;
;             const char* a3 = a2 + kstep; const char* b3 = b2 + kstep;
;             if (last && has_next) S.a_ready(nxt);
;             if constexpr (SP2) {
;             PG8_LDB(B0, 0, 0); PG8_LDB(B1, 0, 1); PG8_SCHED; PG8_LDA(At, 0, 0); PG8_STAGE(PG8_SA(1, 1), a1 + hstep, voffA);
;             PG8_WAIT_V(8); PG8_WAIT_L(0); PG8_BAR; PG8_MMA(0, 0, At, B0); PG8_MMA(0, 1, At, B1); PG8_BAR; PG8_SCHED;
;             PG8_LDA(At, 0, 1); PG8_STAGE(PG8_SB(0, 0), b2, voffB); PG8_STAGE(PG8_SB(0, 1), b2 + hstep, voffB); PG8_STAGE(PG8_SA(0, 0), a2, voffA);
;             PG8_WAIT_V(8); PG8_WAIT_L(0); PG8_BAR; PG8_MMA(1, 0, At, B0); PG8_MMA(1, 1, At, B1); PG8_BAR; PG8_SCHED;
.LBB0_564:
	s_add_u32 s48, s46, 0xfffc0080
	s_addc_u32 s49, s47, -1
	s_cmp_eq_u32 s52, 12
	s_cselect_b32 s51, s0, s49
	s_cselect_b32 s50, s1, s48
	s_cselect_b32 s49, s7, s45
	s_cselect_b32 s48, s31, s35
	s_add_i32 m0, s59, 0xc000
	ds_read_b128 v[128:131], v180
	global_load_lds_dwordx4 v158, s[46:47]
	s_add_i32 m0, s59, 0xe000
	ds_read_b128 v[132:135], v180 offset:1024
	global_load_lds_dwordx4 v160, s[46:47]
	ds_read_b128 v[136:139], v180 offset:2048
	ds_read_b128 v[140:143], v180 offset:3072
	ds_read_b128 v[166:169], v181
	ds_read_b128 v[170:173], v181 offset:1024
	ds_read_b128 v[174:177], v181 offset:2048
	ds_read_b128 v[184:187], v181 offset:3072
	ds_read_b128 v[188:191], v182
	ds_read_b128 v[192:195], v182 offset:1024
	ds_read_b128 v[196:199], v182 offset:2048
	ds_read_b128 v[200:203], v182 offset:3072
	ds_read_b128 v[204:207], v182 offset:4096
	ds_read_b128 v[208:211], v182 offset:5120
	ds_read_b128 v[212:215], v182 offset:6144
	ds_read_b128 v[216:219], v182 offset:7168
	s_waitcnt vmcnt(8)
	s_waitcnt lgkmcnt(0)
	s_barrier
	s_setprio 1
	v_mfma_f32_16x16x32_bf16 v[68:71], v[128:131], v[188:191], v[68:71]
	v_mfma_f32_16x16x32_bf16 v[56:59], v[136:139], v[188:191], v[56:59]
	v_mfma_f32_16x16x32_bf16 v[52:55], v[128:131], v[196:199], v[52:55]
	v_mfma_f32_16x16x32_bf16 v[48:51], v[136:139], v[196:199], v[48:51]
	v_mfma_f32_16x16x32_bf16 v[44:47], v[128:131], v[204:207], v[44:47]
	v_mfma_f32_16x16x32_bf16 v[40:43], v[136:139], v[204:207], v[40:43]
	v_mfma_f32_16x16x32_bf16 v[36:39], v[128:131], v[212:215], v[36:39]
	v_mfma_f32_16x16x32_bf16 v[32:35], v[136:139], v[212:215], v[32:35]
	v_mfma_f32_16x16x32_bf16 v[68:71], v[132:135], v[192:195], v[68:71]
	v_mfma_f32_16x16x32_bf16 v[56:59], v[140:143], v[192:195], v[56:59]
	v_mfma_f32_16x16x32_bf16 v[52:55], v[132:135], v[200:203], v[52:55]
	v_mfma_f32_16x16x32_bf16 v[48:51], v[140:143], v[200:203], v[48:51]
	v_mfma_f32_16x16x32_bf16 v[44:47], v[132:135], v[208:211], v[44:47]
	v_mfma_f32_16x16x32_bf16 v[40:43], v[140:143], v[208:211], v[40:43]
	v_mfma_f32_16x16x32_bf16 v[36:39], v[132:135], v[216:219], v[36:39]
	v_mfma_f32_16x16x32_bf16 v[32:35], v[140:143], v[216:219], v[32:35]
	s_setprio 0
	s_setprio 1
	v_mfma_f32_16x16x32_bf16 v[124:127], v[166:169], v[188:191], v[124:127]
	v_mfma_f32_16x16x32_bf16 v[120:123], v[174:177], v[188:191], v[120:123]
	v_mfma_f32_16x16x32_bf16 v[116:119], v[166:169], v[196:199], v[116:119]
	v_mfma_f32_16x16x32_bf16 v[112:115], v[174:177], v[196:199], v[112:115]
	v_mfma_f32_16x16x32_bf16 v[108:111], v[166:169], v[204:207], v[108:111]
	v_mfma_f32_16x16x32_bf16 v[104:107], v[174:177], v[204:207], v[104:107]
	v_mfma_f32_16x16x32_bf16 v[100:103], v[166:169], v[212:215], v[100:103]
	v_mfma_f32_16x16x32_bf16 v[96:99], v[174:177], v[212:215], v[96:99]
	v_mfma_f32_16x16x32_bf16 v[124:127], v[170:173], v[192:195], v[124:127]
	v_mfma_f32_16x16x32_bf16 v[120:123], v[184:187], v[192:195], v[120:123]
	v_mfma_f32_16x16x32_bf16 v[116:119], v[170:173], v[200:203], v[116:119]
	v_mfma_f32_16x16x32_bf16 v[112:115], v[184:187], v[200:203], v[112:115]
	v_mfma_f32_16x16x32_bf16 v[108:111], v[170:173], v[208:211], v[108:111]
	v_mfma_f32_16x16x32_bf16 v[104:107], v[184:187], v[208:211], v[104:107]
	v_mfma_f32_16x16x32_bf16 v[100:103], v[170:173], v[216:219], v[100:103]
	v_mfma_f32_16x16x32_bf16 v[96:99], v[184:187], v[216:219], v[96:99]
	s_setprio 0
	s_barrier
	s_add_u32 s98, s48, s14
	s_addc_u32 s99, s49, s15
	s_add_u32 s100, s50, s14
	s_addc_u32 s101, s51, s15
	s_add_i32 s53, s77, s29
	s_mov_b32 m0, s53
	ds_read_b128 v[188:191], v182 offset:16384
	global_load_lds_dwordx4 v146, s[48:49]
	s_add_i32 m0, s53, 0x2000
	s_add_u32 s88, s48, 0x40000
	s_addc_u32 s89, s49, 0
	s_add_i32 s53, s78, s29
	global_load_lds_dwordx4 v150, s[48:49]
	s_mov_b32 m0, s53
	ds_read_b128 v[192:195], v182 offset:17408
	global_load_lds_dwordx4 v146, s[88:89]
	s_add_i32 m0, s53, 0x2000
	ds_read_b128 v[196:199], v182 offset:18432
	global_load_lds_dwordx4 v150, s[88:89]
	s_mov_b32 m0, s59
	ds_read_b128 v[200:203], v182 offset:19456
	global_load_lds_dwordx4 v144, s[50:51]
	s_mov_b32 m0, s60
	ds_read_b128 v[204:207], v182 offset:20480
	global_load_lds_dwordx4 v148, s[50:51]
	ds_read_b128 v[208:211], v182 offset:21504
	ds_read_b128 v[212:215], v182 offset:22528
	ds_read_b128 v[216:219], v182 offset:23552
	s_waitcnt vmcnt(8)
	s_waitcnt lgkmcnt(0)
	s_barrier
	s_setprio 1
	v_mfma_f32_16x16x32_bf16 v[28:31], v[128:131], v[188:191], v[28:31]
	v_mfma_f32_16x16x32_bf16 v[24:27], v[136:139], v[188:191], v[24:27]
	v_mfma_f32_16x16x32_bf16 v[20:23], v[128:131], v[196:199], v[20:23]
	v_mfma_f32_16x16x32_bf16 v[16:19], v[136:139], v[196:199], v[16:19]
	v_mfma_f32_16x16x32_bf16 v[12:15], v[128:131], v[204:207], v[12:15]
	v_mfma_f32_16x16x32_bf16 v[8:11], v[136:139], v[204:207], v[8:11]
	v_mfma_f32_16x16x32_bf16 v[4:7], v[128:131], v[212:215], v[4:7]
	v_mfma_f32_16x16x32_bf16 v[0:3], v[136:139], v[212:215], v[0:3]
	v_mfma_f32_16x16x32_bf16 v[28:31], v[132:135], v[192:195], v[28:31]
	v_mfma_f32_16x16x32_bf16 v[24:27], v[140:143], v[192:195], v[24:27]
	v_mfma_f32_16x16x32_bf16 v[20:23], v[132:135], v[200:203], v[20:23]
	v_mfma_f32_16x16x32_bf16 v[16:19], v[140:143], v[200:203], v[16:19]
	v_mfma_f32_16x16x32_bf16 v[12:15], v[132:135], v[208:211], v[12:15]
	v_mfma_f32_16x16x32_bf16 v[8:11], v[140:143], v[208:211], v[8:11]
	v_mfma_f32_16x16x32_bf16 v[4:7], v[132:135], v[216:219], v[4:7]
	v_mfma_f32_16x16x32_bf16 v[0:3], v[140:143], v[216:219], v[0:3]
	s_setprio 0
	s_setprio 1
	v_mfma_f32_16x16x32_bf16 v[92:95], v[166:169], v[188:191], v[92:95]
	v_mfma_f32_16x16x32_bf16 v[88:91], v[174:177], v[188:191], v[88:91]
	v_mfma_f32_16x16x32_bf16 v[84:87], v[166:169], v[196:199], v[84:87]
	v_mfma_f32_16x16x32_bf16 v[80:83], v[174:177], v[196:199], v[80:83]
	v_mfma_f32_16x16x32_bf16 v[76:79], v[166:169], v[204:207], v[76:79]
	v_mfma_f32_16x16x32_bf16 v[72:75], v[174:177], v[204:207], v[72:75]
	v_mfma_f32_16x16x32_bf16 v[64:67], v[166:169], v[212:215], v[64:67]
	v_mfma_f32_16x16x32_bf16 v[60:63], v[174:177], v[212:215], v[60:63]
	v_mfma_f32_16x16x32_bf16 v[92:95], v[170:173], v[192:195], v[92:95]
	v_mfma_f32_16x16x32_bf16 v[88:91], v[184:187], v[192:195], v[88:91]
	v_mfma_f32_16x16x32_bf16 v[84:87], v[170:173], v[200:203], v[84:87]
	v_mfma_f32_16x16x32_bf16 v[80:83], v[184:187], v[200:203], v[80:83]
	v_mfma_f32_16x16x32_bf16 v[76:79], v[170:173], v[208:211], v[76:79]
	v_mfma_f32_16x16x32_bf16 v[72:75], v[184:187], v[208:211], v[72:75]
	v_mfma_f32_16x16x32_bf16 v[64:67], v[170:173], v[216:219], v[64:67]
	v_mfma_f32_16x16x32_bf16 v[60:63], v[184:187], v[216:219], v[60:63]
	s_setprio 0
	s_barrier
; #define PG8_STAGE(bufoff, gbase, voff) do { _Pragma("unroll") for (int _i = 0; _i < 2; ++_i) \
;         __builtin_amdgcn_global_load_lds((const unsigned*)((const char*)(gbase) + (voff)[_i]), (PG8_LAS unsigned*)(lds + (bufoff) + ldsw + _i * 8192), 16, 0, 0); } while (0)
; #define PG8_LDA(dst, b, h) do { _Pragma("unroll") for (int m = 0; m < 4; ++m) _Pragma("unroll") for (int k = 0; k < 2; ++k) dst[m][k] = *(const PG8_LAS bf16x8*)(lds + PG8_SA(b, h) + aoff + m * 2048 + k * 1024); } while (0)
; #define PG8_LDB(dst, b, h) do { _Pragma("unroll") for (int n = 0; n < 2; ++n) _Pragma("unroll") for (int k = 0; k < 2; ++k) dst[n][k] = *(const PG8_LAS bf16x8*)(lds + PG8_SB(b, h) + boff + n * 2048 + k * 1024); } while (0)
; #define PG8_MMA(ai, bj, At, Bt) do { __builtin_amdgcn_s_setprio(1); _Pragma("unroll") for (int m = 0; m < 4; ++m) _Pragma("unroll") for (int n = 0; n < 2; ++n) _Pragma("unroll") for (int k = 0; k < 2; ++k) \
;         acc[ai][bj][m][n] = __builtin_amdgcn_mfma_f32_16x16x32_bf16(Bt[n][k], At[m][k], acc[ai][bj][m][n], 0, 0, 0); __builtin_amdgcn_s_setprio(0); } while (0)
; #define PG8_WAIT_V(n) asm volatile("s_waitcnt vmcnt(" #n ")" ::: "memory")
; #define PG8_WAIT_L(n) asm volatile("s_waitcnt lgkmcnt(" #n ")" ::: "memory")
; #define PG8_BAR __builtin_amdgcn_s_barrier()
; #define PG8_SCHED __builtin_amdgcn_sched_barrier(0)
; template <class Epi, class Sched, bool ALIGN_EPI = false, bool SP2 = false>
; __device__ __forceinline__ void gemm_phase(PG8_LAS unsigned char* lds, const Gemm g, const Sched& S, const Epi& E, int tid_in) {
;     ...
;             PG8_LDB(B0, 1, 0); PG8_LDB(B1, 1, 1); PG8_SCHED; PG8_LDA(At, 1, 0); PG8_STAGE(PG8_SA(0, 1), a2 + hstep, voffA);
;             PG8_WAIT_V(8); PG8_WAIT_L(0); PG8_BAR; PG8_MMA(0, 0, At, B0); PG8_MMA(0, 1, At, B1); PG8_BAR; PG8_SCHED;
;             PG8_LDA(At, 1, 1); PG8_STAGE(PG8_SB(1, 0), b3, voffB); PG8_STAGE(PG8_SB(1, 1), b3 + hstep, voffB); PG8_STAGE(PG8_SA(1, 0), a3, voffA);
;             PG8_WAIT_V(8); PG8_WAIT_L(0); PG8_BAR; PG8_MMA(1, 0, At, B0); PG8_MMA(1, 1, At, B1); PG8_BAR; PG8_SCHED;
	s_add_i32 s53, 0, 0x18000
	s_add_i32 s88, 0, 0x1c000
	s_add_u32 s50, s50, 0x40000
	s_addc_u32 s51, s51, 0
	s_mov_b32 m0, s61
	s_nop 0
	global_load_lds_dwordx4 v144, s[50:51]
	s_mov_b32 m0, s62
	s_nop 0
	global_load_lds_dwordx4 v148, s[50:51]
	v_add_u32_e32 v140, s53, v179
	v_add_u32_e32 v184, s88, v179
	ds_read_b128 v[128:131], v140
	ds_read_b128 v[132:135], v140 offset:1024
	ds_read_b128 v[136:139], v140 offset:2048
	ds_read_b128 v[140:143], v140 offset:3072
	ds_read_b128 v[166:169], v184
	ds_read_b128 v[170:173], v184 offset:1024
	ds_read_b128 v[174:177], v184 offset:2048
	ds_read_b128 v[184:187], v184 offset:3072
	ds_read_b128 v[188:191], v182 offset:32768
	ds_read_b128 v[192:195], v182 offset:33792
	ds_read_b128 v[196:199], v182 offset:34816
	ds_read_b128 v[200:203], v182 offset:35840
	ds_read_b128 v[204:207], v182 offset:36864
	ds_read_b128 v[208:211], v182 offset:37888
	ds_read_b128 v[212:215], v182 offset:38912
	ds_read_b128 v[216:219], v182 offset:39936
	s_waitcnt vmcnt(8)
	s_waitcnt lgkmcnt(0)
	s_barrier
	s_setprio 1
	v_mfma_f32_16x16x32_bf16 v[68:71], v[128:131], v[188:191], v[68:71]
	v_mfma_f32_16x16x32_bf16 v[56:59], v[136:139], v[188:191], v[56:59]
	v_mfma_f32_16x16x32_bf16 v[52:55], v[128:131], v[196:199], v[52:55]
	v_mfma_f32_16x16x32_bf16 v[48:51], v[136:139], v[196:199], v[48:51]
	v_mfma_f32_16x16x32_bf16 v[44:47], v[128:131], v[204:207], v[44:47]
	v_mfma_f32_16x16x32_bf16 v[40:43], v[136:139], v[204:207], v[40:43]
	v_mfma_f32_16x16x32_bf16 v[36:39], v[128:131], v[212:215], v[36:39]
	v_mfma_f32_16x16x32_bf16 v[32:35], v[136:139], v[212:215], v[32:35]
	v_mfma_f32_16x16x32_bf16 v[68:71], v[132:135], v[192:195], v[68:71]
	v_mfma_f32_16x16x32_bf16 v[56:59], v[140:143], v[192:195], v[56:59]
	v_mfma_f32_16x16x32_bf16 v[52:55], v[132:135], v[200:203], v[52:55]
	v_mfma_f32_16x16x32_bf16 v[48:51], v[140:143], v[200:203], v[48:51]
	v_mfma_f32_16x16x32_bf16 v[44:47], v[132:135], v[208:211], v[44:47]
	v_mfma_f32_16x16x32_bf16 v[40:43], v[140:143], v[208:211], v[40:43]
	v_mfma_f32_16x16x32_bf16 v[36:39], v[132:135], v[216:219], v[36:39]
	v_mfma_f32_16x16x32_bf16 v[32:35], v[140:143], v[216:219], v[32:35]
	s_setprio 0
	s_setprio 1
	v_mfma_f32_16x16x32_bf16 v[124:127], v[166:169], v[188:191], v[124:127]
	v_mfma_f32_16x16x32_bf16 v[120:123], v[174:177], v[188:191], v[120:123]
	v_mfma_f32_16x16x32_bf16 v[116:119], v[166:169], v[196:199], v[116:119]
	v_mfma_f32_16x16x32_bf16 v[112:115], v[174:177], v[196:199], v[112:115]
	v_mfma_f32_16x16x32_bf16 v[108:111], v[166:169], v[204:207], v[108:111]
	v_mfma_f32_16x16x32_bf16 v[104:107], v[174:177], v[204:207], v[104:107]
	v_mfma_f32_16x16x32_bf16 v[100:103], v[166:169], v[212:215], v[100:103]
	v_mfma_f32_16x16x32_bf16 v[96:99], v[174:177], v[212:215], v[96:99]
	v_mfma_f32_16x16x32_bf16 v[124:127], v[170:173], v[192:195], v[124:127]
	v_mfma_f32_16x16x32_bf16 v[120:123], v[184:187], v[192:195], v[120:123]
	v_mfma_f32_16x16x32_bf16 v[116:119], v[170:173], v[200:203], v[116:119]
	v_mfma_f32_16x16x32_bf16 v[112:115], v[184:187], v[200:203], v[112:115]
	v_mfma_f32_16x16x32_bf16 v[108:111], v[170:173], v[208:211], v[108:111]
	v_mfma_f32_16x16x32_bf16 v[104:107], v[184:187], v[208:211], v[104:107]
	v_mfma_f32_16x16x32_bf16 v[100:103], v[170:173], v[216:219], v[100:103]
	v_mfma_f32_16x16x32_bf16 v[96:99], v[184:187], v[216:219], v[96:99]
	s_setprio 0
	s_barrier
	s_add_i32 s50, s53, s29
	s_mov_b32 m0, s50
	ds_read_b128 v[188:191], v182 offset:49152
	global_load_lds_dwordx4 v146, s[98:99]
	s_add_i32 m0, s50, 0x2000
	s_add_u32 s48, s48, 0x40080
	s_addc_u32 s49, s49, 0
	s_add_i32 s50, s88, s29
	global_load_lds_dwordx4 v150, s[98:99]
	s_mov_b32 m0, s50
	ds_read_b128 v[192:195], v182 offset:50176
	global_load_lds_dwordx4 v146, s[48:49]
	s_add_i32 m0, s50, 0x2000
	ds_read_b128 v[196:199], v182 offset:51200
	global_load_lds_dwordx4 v150, s[48:49]
	s_mov_b32 m0, s63
	ds_read_b128 v[200:203], v182 offset:52224
	global_load_lds_dwordx4 v144, s[100:101]
	s_mov_b32 m0, s64
	ds_read_b128 v[204:207], v182 offset:53248
	global_load_lds_dwordx4 v148, s[100:101]
	ds_read_b128 v[208:211], v182 offset:54272
	ds_read_b128 v[212:215], v182 offset:55296
	ds_read_b128 v[216:219], v182 offset:56320
	s_waitcnt vmcnt(8)
	s_waitcnt lgkmcnt(0)
	s_barrier
	s_setprio 1
	v_mfma_f32_16x16x32_bf16 v[28:31], v[128:131], v[188:191], v[28:31]
	v_mfma_f32_16x16x32_bf16 v[24:27], v[136:139], v[188:191], v[24:27]
	v_mfma_f32_16x16x32_bf16 v[20:23], v[128:131], v[196:199], v[20:23]
	v_mfma_f32_16x16x32_bf16 v[16:19], v[136:139], v[196:199], v[16:19]
	v_mfma_f32_16x16x32_bf16 v[12:15], v[128:131], v[204:207], v[12:15]
	v_mfma_f32_16x16x32_bf16 v[8:11], v[136:139], v[204:207], v[8:11]
	v_mfma_f32_16x16x32_bf16 v[4:7], v[128:131], v[212:215], v[4:7]
	v_mfma_f32_16x16x32_bf16 v[0:3], v[136:139], v[212:215], v[0:3]
	v_mfma_f32_16x16x32_bf16 v[28:31], v[132:135], v[192:195], v[28:31]
	v_mfma_f32_16x16x32_bf16 v[24:27], v[140:143], v[192:195], v[24:27]
	v_mfma_f32_16x16x32_bf16 v[20:23], v[132:135], v[200:203], v[20:23]
	v_mfma_f32_16x16x32_bf16 v[16:19], v[140:143], v[200:203], v[16:19]
	v_mfma_f32_16x16x32_bf16 v[12:15], v[132:135], v[208:211], v[12:15]
	v_mfma_f32_16x16x32_bf16 v[8:11], v[140:143], v[208:211], v[8:11]
	v_mfma_f32_16x16x32_bf16 v[4:7], v[132:135], v[216:219], v[4:7]
	v_mfma_f32_16x16x32_bf16 v[0:3], v[140:143], v[216:219], v[0:3]
	s_setprio 0
	s_setprio 1
	v_mfma_f32_16x16x32_bf16 v[92:95], v[166:169], v[188:191], v[92:95]
	v_mfma_f32_16x16x32_bf16 v[88:91], v[174:177], v[188:191], v[88:91]
	v_mfma_f32_16x16x32_bf16 v[84:87], v[166:169], v[196:199], v[84:87]
	v_mfma_f32_16x16x32_bf16 v[80:83], v[174:177], v[196:199], v[80:83]
	v_mfma_f32_16x16x32_bf16 v[76:79], v[166:169], v[204:207], v[76:79]
	v_mfma_f32_16x16x32_bf16 v[72:75], v[174:177], v[204:207], v[72:75]
	v_mfma_f32_16x16x32_bf16 v[64:67], v[166:169], v[212:215], v[64:67]
	v_mfma_f32_16x16x32_bf16 v[60:63], v[174:177], v[212:215], v[60:63]
	v_mfma_f32_16x16x32_bf16 v[92:95], v[170:173], v[192:195], v[92:95]
	v_mfma_f32_16x16x32_bf16 v[88:91], v[184:187], v[192:195], v[88:91]
	v_mfma_f32_16x16x32_bf16 v[84:87], v[170:173], v[200:203], v[84:87]
	v_mfma_f32_16x16x32_bf16 v[80:83], v[184:187], v[200:203], v[80:83]
	v_mfma_f32_16x16x32_bf16 v[76:79], v[170:173], v[208:211], v[76:79]
	v_mfma_f32_16x16x32_bf16 v[72:75], v[184:187], v[208:211], v[72:75]
	v_mfma_f32_16x16x32_bf16 v[64:67], v[170:173], v[216:219], v[64:67]
	v_mfma_f32_16x16x32_bf16 v[60:63], v[184:187], v[216:219], v[60:63]
	s_setprio 0
	s_barrier
	s_add_i32 s52, s52, 2
	s_add_u32 s46, s46, 0x100
	s_addc_u32 s47, s47, 0
	s_add_u32 s35, s35, 0x100
	s_addc_u32 s45, s45, 0
	s_cmp_gt_u32 s52, 13
	s_cbranch_scc0 .LBB0_564
	s_and_b64 vcc, exec, s[16:17]
	s_cbranch_vccnz .LBB0_568
	v_lshl_add_u32 v166, s44, 8, v178
	s_cmp_lg_u32 s6, 19
	s_mov_b64 s[44:45], -1
	s_cbranch_scc1 .LBB0_569

; #define WAIT_BAR(N) asm volatile("s_waitcnt vmcnt(" #N ") lgkmcnt(0)\n\ts_barrier":::"memory")
;   #define BIAS(P0,P1,t) do{ const __attribute__((address_space(3))) f32x4v*nbp_=(const __attribute__((address_space(3))) f32x4v*)(nb+64*(t)+4*hi); \
;     _Pragma("unroll") for(int g_=0;g_<4;++g_){ const f32x4v c0_=nbp_[2*g_],c1_=nbp_[2*g_+8]; _Pragma("unroll") for(int i_=0;i_<4;++i_){P0[4*g_+i_]+=c0_[i_];P1[4*g_+i_]+=c1_[i_];} SBAR(); } }while(0)
;   #define DMA_K(t,slot) glds16(ksrc+(long)(t)*KVBLK*DM,(unsigned)__builtin_amdgcn_readfirstlane(kdst+(slot)))
;   #define DMA_V(t,slot) glds16(vsrc+(long)(t)*KVBLK*DM,(unsigned)__builtin_amdgcn_readfirstlane(vdst+(slot)))
;   #define CMASK(P0,P1,t) do{int jb_=(t)-(NT-4); if(jb_>=0)cmask(P0,P1,jb_,qrel,hi);}while(0)
;   #define CMASK(P0,P1,t) do{}while(0)
;   #define CMASK(P0,P1,t) do{int jb_=(t)-(NT-4); if(jb_>=0)cmask(P0,P1,jb_,qrel,hi);}while(0)
; template<int THRL> __device__ __forceinline__ void attn_unit(int b,int h,int qb,const bf16*Q,const bf16*__restrict__ K,const bf16*__restrict__ V,bf16*O,char*shm,int tid,const __attribute__((address_space(3))) float*nb){
;     ...
;   float*wsf=(float*)(shm+LDS_WS)+wid*64;
;   const bf16*ksrc=Kh+(long)lane*DM+wid*8;
;   const bf16*vsrc=Vh+(long)(16*(wid&3)+(lane>>2))*DM+(wid>>2)*32+(lane&3)*8;
;   const unsigned kdst=lds0+LDS_K+wid*1024, vdst=lds0+LDS_V+wid*1024;
;     ...
;   const int vb0=(int)(lds0+LDS_V)+((lane>>4)&1)*32+(lane&3)*8+(4*hi+((lane&15)>>2))*64;
;   const char*Kbase=shm+LDS_K; bf16x8 kf[8];
;   const lds_cptr shm3=(lds_cptr)shm; const lds_cptr kp0=shm3+LDS_K+hi*1024+r32*16; const lds_cptr vp0=shm3+LDS_V+((lane>>4)&1)*32+(lane&3)*8+(4*hi+((lane&15)>>2))*64;
;   const int NT=(q0+QB)/KVBLK;
;   DMA_K(0,0);DMA_V(0,0);DMA_K(1,SLOTB);
;   bf16x8 qr[4];
;   #pragma unroll
;   for(int d0=0;d0<4;++d0)qr[d0]=*reinterpret_cast<const bf16x8*>(&Qw[(long)r32*DM+d0*16+hi*8]);
;   float mhat=0.f,l_reg=0.f;f32x16 o[2];float zf_=0.f;asm volatile("":"+v"(zf_));f32x16 negm;_Pragma("unroll") for(int r=0;r<16;++r)negm[r]=zf_;asm volatile("":"+v"(negm));o[0]=negm;o[1]=negm;
;   const int qrel=wid*QBLK+r32;
;     ...
;   bool resc=false;
;     ...
;   f32x16 pA0,pA1,pB0,pB1;
;   int sl_prev=0,sl_cur=0,sl_next=SLOTB;
;     ...
;   DMA_K(2,2*SLOTB);
;   WAIT_BAR(3);
;   qkt(pA0,pA1,Kbase,qr,negm,r32,hi);asm volatile("s_nop 15\n\ts_nop 7":"+v"(pA0),"+v"(pA1));BIAS(pA0,pA1,0);CMASK(pA0,pA1,0);
.LBB0_783:
	s_lshr_b32 s9, s1, 3
	v_readfirstlane_b32 s1, v56
	s_ashr_i32 s64, s1, 6
	s_lshl_b32 s8, s9, 11
	s_lshl_b32 s35, s34, 8
	s_add_i32 s10, s35, s8
	s_lshl_b32 s8, s64, 5
	s_lshr_b32 s0, s58, 1
	s_ashr_i32 s11, s8, 31
	s_add_u32 s28, s8, s10
	s_addc_u32 s29, s11, 0
	s_lshl_b64 s[10:11], s[28:29], 10
	s_add_u32 s10, s48, s10
	s_addc_u32 s11, s49, s11
	s_lshl_b32 s0, s0, 6
	s_and_b32 s0, s0, 0x1c0
	s_lshl_b32 s63, s0, 1
	s_add_u32 s10, s10, s63
	s_addc_u32 s11, s11, 0
	s_lshl_b32 s0, s9, 21
	s_add_u32 s9, s50, s0
	s_addc_u32 s12, s51, 0
	s_add_u32 s30, s9, s63
	s_addc_u32 s31, s12, 0
	s_add_u32 s0, s52, s0
	s_addc_u32 s9, s53, 0
	s_add_u32 s36, s0, s63
	v_lshlrev_b32_e32 v208, 10, v217
	s_addc_u32 s37, s9, 0
	v_lshl_add_u64 v[0:1], s[30:31], 0, v[208:209]
	s_lshl_b32 s30, s64, 3
	s_ashr_i32 s31, s30, 31
	v_lshl_add_u64 v[188:189], s[30:31], 1, v[0:1]
	s_lshl_b32 s0, s64, 4
	v_lshrrev_b32_e32 v0, 2, v217
	v_and_or_b32 v0, s0, 48, v0
	s_ashr_i32 s0, s1, 3
	s_and_b32 s30, s0, 0xffffffe0
	s_ashr_i32 s31, s30, 31
	s_lshl_b32 s0, s64, 10
	v_lshlrev_b32_e32 v208, 10, v0
	v_lshlrev_b32_e32 v218, 3, v56
	s_cmp_lg_u32 0, -1
	v_lshl_add_u64 v[0:1], s[36:37], 0, v[208:209]
	v_and_b32_e32 v221, 24, v218
	s_cselect_b32 s9, 0, 0
	v_lshrrev_b32_e32 v220, 5, v217
	v_lshl_add_u64 v[0:1], s[30:31], 1, v[0:1]
	v_lshlrev_b32_e32 v208, 1, v221
	s_add_i32 s65, s0, s9
	s_mov_b32 m0, s65
	s_nop 0
	global_load_lds_dwordx4 v[188:189], off
	v_and_b32_e32 v219, 31, v56
	v_lshl_add_u64 v[80:81], v[0:1], 0, v[208:209]
	s_add_i32 s68, s65, 0x6000
	s_mov_b32 m0, s68
	s_nop 0
	global_load_lds_dwordx4 v[80:81], off
	v_lshl_add_u64 v[0:1], v[188:189], 0, s[16:17]
	v_lshlrev_b32_e32 v52, 4, v220
	s_add_i32 s9, s65, 0x2000
	s_mov_b32 m0, s9
	s_nop 0
	global_load_lds_dwordx4 v[0:1], off
	v_lshl_or_b32 v1, v219, 10, v52
	global_load_dwordx4 v[128:131], v1, s[10:11]
	global_load_dwordx4 v[120:123], v1, s[10:11] offset:32
	global_load_dwordx4 v[116:119], v1, s[10:11] offset:64
	global_load_dwordx4 v[112:115], v1, s[10:11] offset:96
	v_mov_b32_e32 v0, v209
	v_lshlrev_b32_e32 v2, 10, v220
	v_lshlrev_b32_e32 v3, 4, v219
	v_add3_u32 v228, 0, v2, v3
	v_lshl_add_u64 v[16:17], v[188:189], 0, s[18:19]
	v_mov_b32_e32 v1, v0
	v_mov_b32_e32 v2, v0
	v_mov_b32_e32 v3, v0
	v_mov_b32_e32 v4, v0
	v_mov_b32_e32 v5, v0
	v_mov_b32_e32 v6, v0
	v_mov_b32_e32 v7, v0
	v_mov_b32_e32 v8, v0
	v_mov_b32_e32 v9, v0
	v_mov_b32_e32 v10, v0
	v_mov_b32_e32 v11, v0
	v_mov_b32_e32 v12, v0
	v_mov_b32_e32 v13, v0
	v_mov_b32_e32 v14, v0
	v_mov_b32_e32 v15, v0
	s_add_i32 s9, s65, 0x4000
	s_mov_b32 m0, s9
	s_nop 0
	global_load_lds_dwordx4 v[16:17], off
	s_waitcnt vmcnt(3) lgkmcnt(0)
	s_barrier
	ds_read_b128 v[16:19], v228
	ds_read_b128 v[48:51], v228 offset:512
	v_lshlrev_b32_e32 v225, 2, v220
	s_waitcnt vmcnt(0) lgkmcnt(0)
	v_mfma_f32_32x32x16_bf16 v[32:47], v[16:19], v[128:131], v[0:15]
	v_mfma_f32_32x32x16_bf16 v[16:31], v[48:51], v[128:131], v[0:15]
	ds_read_b128 v[48:51], v228 offset:2048
	s_waitcnt lgkmcnt(0)
	v_mfma_f32_32x32x16_bf16 v[32:47], v[48:51], v[120:123], v[32:47]
	ds_read_b128 v[48:51], v228 offset:2560
	s_waitcnt lgkmcnt(0)
	v_mfma_f32_32x32x16_bf16 v[16:31], v[48:51], v[120:123], v[16:31]
	ds_read_b128 v[48:51], v228 offset:4096
	s_waitcnt lgkmcnt(0)
	v_mfma_f32_32x32x16_bf16 v[32:47], v[48:51], v[116:119], v[32:47]
	ds_read_b128 v[48:51], v228 offset:4608
	s_waitcnt lgkmcnt(0)
	v_mfma_f32_32x32x16_bf16 v[16:31], v[48:51], v[116:119], v[16:31]
	ds_read_b128 v[48:51], v228 offset:6144
	s_waitcnt lgkmcnt(0)
	v_mfma_f32_32x32x16_bf16 v[32:47], v[48:51], v[112:115], v[32:47]
	ds_read_b128 v[48:51], v228 offset:6656
	s_waitcnt lgkmcnt(0)
	v_mfma_f32_32x32x16_bf16 v[16:31], v[48:51], v[112:115], v[16:31]
	v_add_u32_e32 v48, 0, v52
	v_add_u32_e32 v54, 0x15000, v48
	s_nop 15
	s_nop 7
	ds_read_b128 v[48:51], v54
	ds_read_b128 v[58:61], v54 offset:128
	s_waitcnt lgkmcnt(1)
	s_nop 3
	v_pk_add_f32 v[52:53], v[48:49], v[32:33]
	v_pk_add_f32 v[48:49], v[50:51], v[34:35]
	ds_read_b128 v[32:35], v54 offset:32
	ds_read_b128 v[62:65], v54 offset:160
	s_waitcnt lgkmcnt(1)
	v_pk_add_f32 v[50:51], v[36:37], v[32:33]
	v_pk_add_f32 v[34:35], v[38:39], v[34:35]
	ds_read_b128 v[36:39], v54 offset:64
	ds_read_b128 v[66:69], v54 offset:192
	s_waitcnt lgkmcnt(1)
	v_pk_add_f32 v[36:37], v[40:41], v[36:37]
	v_pk_add_f32 v[32:33], v[42:43], v[38:39]
	ds_read_b128 v[70:73], v54 offset:96
	ds_read_b128 v[74:77], v54 offset:224
	v_pk_add_f32 v[54:55], v[18:19], v[60:61]
	v_pk_add_f32 v[40:41], v[20:21], v[62:63]
	v_pk_add_f32 v[42:43], v[22:23], v[64:65]
	s_waitcnt lgkmcnt(1)
	v_pk_add_f32 v[20:21], v[44:45], v[70:71]
	v_pk_add_f32 v[18:19], v[46:47], v[72:73]
	v_pk_add_f32 v[38:39], v[24:25], v[66:67]
	v_pk_add_f32 v[26:27], v[26:27], v[68:69]
	s_waitcnt lgkmcnt(0)
	v_pk_add_f32 v[24:25], v[28:29], v[74:75]
	v_pk_add_f32 v[22:23], v[30:31], v[76:77]
	v_pk_add_f32 v[16:17], v[16:17], v[58:59]
	s_cmp_lg_u32 s34, 0
	v_or_b32_e32 v226, s8, v219
	s_cselect_b64 s[8:9], -1, 0
	s_and_b64 vcc, exec, s[8:9]
	s_cbranch_vccnz .LBB0_785
; __device__ __forceinline__ void cmask(f32x16&p0,f32x16&p1,int jb,int qrel,int hi){
;   const float NEG=-INFINITY; int kb=64*jb+4*hi;
;   #pragma unroll
;   for(int r=0;r<16;++r){int kv=kb+(r&3)+8*(r>>2); if(kv>qrel)p0[r]=NEG; if(kv+32>qrel)p1[r]=NEG;}
; }
	v_or_b32_e32 v28, 32, v225
	v_cmp_le_i32_e32 vcc, v28, v226
	v_or_b32_e32 v28, 33, v225
	s_nop 0
	v_cndmask_b32_e32 v16, v216, v16, vcc
	v_cmp_le_i32_e32 vcc, v225, v226
	s_nop 1
	v_cndmask_b32_e32 v52, v216, v52, vcc
	v_cmp_lt_i32_e32 vcc, v225, v226
	s_nop 1
	v_cndmask_b32_e32 v53, v216, v53, vcc
	v_cmp_le_i32_e32 vcc, v28, v226
	v_or_b32_e32 v28, 2, v225
	s_nop 0
	v_cndmask_b32_e32 v17, v216, v17, vcc
	v_cmp_le_i32_e32 vcc, v28, v226
	v_or_b32_e32 v28, 34, v225
	s_nop 0
	v_cndmask_b32_e32 v48, v216, v48, vcc
	v_cmp_le_i32_e32 vcc, v28, v226
	v_or_b32_e32 v28, 3, v225
	s_nop 0
	v_cndmask_b32_e32 v54, v216, v54, vcc
	v_cmp_le_i32_e32 vcc, v28, v226
	v_or_b32_e32 v28, 35, v225
	s_nop 0
	v_cndmask_b32_e32 v49, v216, v49, vcc
	v_cmp_le_i32_e32 vcc, v28, v226
	v_or_b32_e32 v28, 8, v225
	s_nop 0
	v_cndmask_b32_e32 v55, v216, v55, vcc
	v_cmp_le_i32_e32 vcc, v28, v226
	v_or_b32_e32 v28, 40, v225
	s_nop 0
	v_cndmask_b32_e32 v50, v216, v50, vcc
	v_cmp_le_i32_e32 vcc, v28, v226
	v_or_b32_e32 v28, 9, v225
	s_nop 0
	v_cndmask_b32_e32 v40, v216, v40, vcc
	v_cmp_le_i32_e32 vcc, v28, v226
	v_or_b32_e32 v28, 41, v225
	s_nop 0
	v_cndmask_b32_e32 v51, v216, v51, vcc
	v_cmp_le_i32_e32 vcc, v28, v226
	v_or_b32_e32 v28, 10, v225
	s_nop 0
	v_cndmask_b32_e32 v41, v216, v41, vcc
	v_cmp_le_i32_e32 vcc, v28, v226
	v_or_b32_e32 v28, 42, v225
	s_nop 0
	v_cndmask_b32_e32 v34, v216, v34, vcc
	v_cmp_le_i32_e32 vcc, v28, v226
	v_or_b32_e32 v28, 11, v225
	s_nop 0
	v_cndmask_b32_e32 v42, v216, v42, vcc
	v_cmp_le_i32_e32 vcc, v28, v226
	v_or_b32_e32 v28, 43, v225
	s_nop 0
	v_cndmask_b32_e32 v35, v216, v35, vcc
	v_cmp_le_i32_e32 vcc, v28, v226
	v_or_b32_e32 v28, 16, v225
	s_nop 0
	v_cndmask_b32_e32 v43, v216, v43, vcc
	v_cmp_le_i32_e32 vcc, v28, v226
	v_or_b32_e32 v28, 48, v225
	s_nop 0
	v_cndmask_b32_e32 v36, v216, v36, vcc
	v_cmp_le_i32_e32 vcc, v28, v226
	v_or_b32_e32 v28, 17, v225
	s_nop 0
	v_cndmask_b32_e32 v38, v216, v38, vcc
	v_cmp_le_i32_e32 vcc, v28, v226
	v_or_b32_e32 v28, 49, v225
	s_nop 0
	v_cndmask_b32_e32 v37, v216, v37, vcc
	v_cmp_le_i32_e32 vcc, v28, v226
	v_or_b32_e32 v28, 18, v225
	s_nop 0
	v_cndmask_b32_e32 v39, v216, v39, vcc
	v_cmp_le_i32_e32 vcc, v28, v226
	v_or_b32_e32 v28, 50, v225
	s_nop 0
	v_cndmask_b32_e32 v32, v216, v32, vcc
	v_cmp_le_i32_e32 vcc, v28, v226
	v_or_b32_e32 v28, 19, v225
	s_nop 0
	v_cndmask_b32_e32 v26, v216, v26, vcc
	v_cmp_le_i32_e32 vcc, v28, v226
	v_or_b32_e32 v28, 51, v225
	s_nop 0
	v_cndmask_b32_e32 v33, v216, v33, vcc
	v_cmp_le_i32_e32 vcc, v28, v226
	v_or_b32_e32 v28, 24, v225
	s_nop 0
	v_cndmask_b32_e32 v27, v216, v27, vcc
	v_cmp_le_i32_e32 vcc, v28, v226
	v_or_b32_e32 v28, 56, v225
	s_nop 0
	v_cndmask_b32_e32 v20, v216, v20, vcc
	v_cmp_le_i32_e32 vcc, v28, v226
	v_or_b32_e32 v28, 25, v225
	s_nop 0
	v_cndmask_b32_e32 v24, v216, v24, vcc
	v_cmp_le_i32_e32 vcc, v28, v226
	v_or_b32_e32 v28, 57, v225
	s_nop 0
	v_cndmask_b32_e32 v21, v216, v21, vcc
	v_cmp_le_i32_e32 vcc, v28, v226
	v_or_b32_e32 v28, 26, v225
	s_nop 0
	v_cndmask_b32_e32 v25, v216, v25, vcc
	v_cmp_le_i32_e32 vcc, v28, v226
	v_or_b32_e32 v28, 58, v225
	s_nop 0
	v_cndmask_b32_e32 v18, v216, v18, vcc
	v_cmp_le_i32_e32 vcc, v28, v226
	v_or_b32_e32 v28, 27, v225
	s_nop 0
	v_cndmask_b32_e32 v22, v216, v22, vcc
	v_cmp_le_i32_e32 vcc, v28, v226
	v_or_b32_e32 v28, 59, v225
	s_nop 0
	v_cndmask_b32_e32 v19, v216, v19, vcc
	v_cmp_le_i32_e32 vcc, v28, v226
	s_nop 1
	v_cndmask_b32_e32 v23, v216, v23, vcc
.LBB0_785:
	v_lshlrev_b32_e32 v28, 1, v56
	v_and_b32_e32 v222, 32, v28
	v_lshrrev_b32_e32 v28, 2, v56
	v_and_or_b32 v28, v28, 3, v225
	v_lshlrev_b32_e32 v208, 6, v28
	v_add_u32_e32 v28, 0, v222
	v_add3_u32 v229, v28, v221, v208
	v_max3_f32 v28, v52, v53, v16
	v_max3_f32 v29, v48, v49, v17
	s_and_b32 s1, s1, 0x3fffffc0
	v_max3_f32 v28, v28, v54, v55
	v_max3_f32 v29, v29, v34, v35
	s_add_i32 s69, s35, 0x100
	v_max3_f32 v28, v28, v50, v51
	v_max3_f32 v29, v29, v42, v43
	s_lshl_b32 s1, s1, 2
	v_max3_f32 v28, v28, v40, v41
	v_max3_f32 v29, v29, v32, v33
	s_add_i32 s10, s1, 0
	v_max3_f32 v28, v28, v36, v37
	v_max3_f32 v29, v29, v26, v27
	s_lshr_b32 s70, s69, 6
	v_max3_f32 v28, v28, v38, v39
	v_max3_f32 v29, v29, v18, v19
	s_cmp_lg_u32 0, -1
	v_max3_f32 v28, v28, v20, v21
	v_max3_f32 v29, v29, v22, v23
	v_lshl_add_u64 v[190:191], v[80:81], 0, s[16:17]
	v_max3_f32 v28, v28, v24, v25
	s_mov_b32 s12, 1
	v_max_f32_e32 v28, v28, v29
	s_mov_b32 s1, 0
	v_mov_b32_e32 v29, v28
	s_nop 1
	v_permlane32_swap_b32_e32 v28, v29
	v_max_f32_e32 v28, v28, v29
	v_lshl_add_u32 v224, v219, 2, s10
	v_add_f32_e32 v227, v209, v28
	v_sub_f32_e32 v63, v32, v28
	v_sub_f32_e32 v29, v52, v28
	v_sub_f32_e32 v30, v53, v28
	v_sub_f32_e32 v31, v48, v28
	v_sub_f32_e32 v52, v54, v28
	s_nop 0
	v_xor_b32_e32 v32, 0x80000000, v227
	v_sub_f32_e32 v48, v49, v28
	v_sub_f32_e32 v53, v55, v28
	v_sub_f32_e32 v49, v50, v28
	v_sub_f32_e32 v54, v40, v28
	v_sub_f32_e32 v50, v51, v28
	v_sub_f32_e32 v55, v41, v28
	v_sub_f32_e32 v51, v34, v28
	v_sub_f32_e32 v56, v42, v28
	v_sub_f32_e32 v57, v35, v28
	v_sub_f32_e32 v58, v43, v28
	v_sub_f32_e32 v59, v36, v28
	v_sub_f32_e32 v60, v38, v28
	v_sub_f32_e32 v61, v37, v28
	v_sub_f32_e32 v62, v39, v28
	v_sub_f32_e32 v75, v33, v28
	v_mov_b32_e32 v33, v32
	v_mov_b32_e32 v34, v32
	v_mov_b32_e32 v35, v32
	v_mov_b32_e32 v36, v32
	v_mov_b32_e32 v37, v32
	v_mov_b32_e32 v38, v32
	v_mov_b32_e32 v39, v32
	v_mov_b32_e32 v40, v32
	v_mov_b32_e32 v41, v32
	v_mov_b32_e32 v42, v32
	v_mov_b32_e32 v43, v32
	v_mov_b32_e32 v44, v32
	v_mov_b32_e32 v45, v32
	v_mov_b32_e32 v46, v32
	v_mov_b32_e32 v47, v32
	v_sub_f32_e32 v16, v16, v28
	v_sub_f32_e32 v17, v17, v28
	s_waitcnt vmcnt(0) lgkmcnt(0)
	s_barrier
; #define WAIT_BAR(N) asm volatile("s_waitcnt vmcnt(" #N ") lgkmcnt(0)\n\ts_barrier":::"memory")
;   #define BIAS(P0,P1,t) do{ const __attribute__((address_space(3))) f32x4v*nbp_=(const __attribute__((address_space(3))) f32x4v*)(nb+64*(t)+4*hi); \
;     _Pragma("unroll") for(int g_=0;g_<4;++g_){ const f32x4v c0_=nbp_[2*g_],c1_=nbp_[2*g_+8]; _Pragma("unroll") for(int i_=0;i_<4;++i_){P0[4*g_+i_]+=c0_[i_];P1[4*g_+i_]+=c1_[i_];} SBAR(); } }while(0)
;   #define DMA_K(t,slot) glds16(ksrc+(long)(t)*KVBLK*DM,(unsigned)__builtin_amdgcn_readfirstlane(kdst+(slot)))
;   #define DMA_V(t,slot) glds16(vsrc+(long)(t)*KVBLK*DM,(unsigned)__builtin_amdgcn_readfirstlane(vdst+(slot)))
;   #define CMASK(P0,P1,t) do{int jb_=(t)-(NT-4); if(jb_>=0)cmask(P0,P1,jb_,qrel,hi);}while(0)
;   #define START(P0,P1) do{ const float rm=rowmax(P0,P1); resc=false; \
;     { const float dl=rm; mhat=fadd_s(mhat,dl); \
;       _Pragma("unroll") for(int r=0;r<16;++r){P0[r]=fsub_s(P0[r],dl);P1[r]=fsub_s(P1[r],dl);} \
;       _Pragma("unroll") for(int r=0;r<16;++r)negm[r]=-mhat; asm volatile("":"+v"(negm)); } \
;     _Pragma("unroll") for(int r=0;r<16;++r)P0[r]=__builtin_amdgcn_exp2f(P0[r]); }while(0)
;   #define ROT() do{sl_prev=sl_cur;sl_cur=sl_next;sl_next=(sl_next==(NSLOT-1)*SLOTB)?0:sl_next+SLOTB;}while(0)
;   #define CMASK(P0,P1,t) do{}while(0)
;   #define CMASK(P0,P1,t) do{int jb_=(t)-(NT-4); if(jb_>=0)cmask(P0,P1,jb_,qrel,hi);}while(0)
; template<int THRL> __device__ __forceinline__ void attn_unit(int b,int h,int qb,const bf16*Q,const bf16*__restrict__ K,const bf16*__restrict__ V,bf16*O,char*shm,int tid,const __attribute__((address_space(3))) float*nb){
;     ...
;   f32x16 pA0,pA1,pB0,pB1;
;   int sl_prev=0,sl_cur=0,sl_next=SLOTB;
;     ...
;   DMA_K(2,2*SLOTB);
;   WAIT_BAR(3);
;   qkt(pA0,pA1,Kbase,qr,negm,r32,hi);asm volatile("s_nop 15\n\ts_nop 7":"+v"(pA0),"+v"(pA1));BIAS(pA0,pA1,0);CMASK(pA0,pA1,0);
;   START(pA0,pA1);
;   _Pragma("unroll") for(int r=0;r<16;++r)pA1[r]=__builtin_amdgcn_exp2f(pA1[r]);
;   WAIT_BAR(0);
;   DMA_K(3,0);DMA_V(1,SLOTB);
;   ROT();
;   kload8(kf,kp0+sl_cur);
;   WAIT_BAR(2);
	v_exp_f32_e32 v67, v48
	v_exp_f32_e32 v68, v49
	v_exp_f32_e32 v48, v16
	v_exp_f32_e32 v49, v17
	v_lshl_add_u64 v[16:17], v[188:189], 0, s[20:21]
	s_mov_b32 m0, s65
	s_nop 0
	global_load_lds_dwordx4 v[16:17], off
	s_cselect_b32 s11, 0, 0
	s_add_i32 s0, s11, s0
	s_add_i32 s0, s0, 0x8000
	s_mov_b32 m0, s0
	s_nop 0
	global_load_lds_dwordx4 v[190:191], off
	ds_read_b128 v[172:175], v228 offset:8192
	ds_read_b128 v[168:171], v228 offset:8704
	ds_read_b128 v[164:167], v228 offset:10240
	ds_read_b128 v[160:163], v228 offset:10752
	ds_read_b128 v[156:159], v228 offset:12288
	ds_read_b128 v[152:155], v228 offset:12800
	ds_read_b128 v[148:151], v228 offset:14336
	ds_read_b128 v[144:147], v228 offset:14848
	v_sub_f32_e32 v26, v26, v28
	v_sub_f32_e32 v27, v27, v28
	v_sub_f32_e32 v20, v20, v28
	v_sub_f32_e32 v24, v24, v28
	v_sub_f32_e32 v21, v21, v28
	v_sub_f32_e32 v25, v25, v28
	v_sub_f32_e32 v18, v18, v28
	v_sub_f32_e32 v22, v22, v28
	v_sub_f32_e32 v19, v19, v28
	v_sub_f32_e32 v23, v23, v28
	v_exp_f32_e32 v64, v29
	v_exp_f32_e32 v65, v30
	v_exp_f32_e32 v66, v31
	v_exp_f32_e32 v69, v50
	v_exp_f32_e32 v70, v51
	v_exp_f32_e32 v71, v57
	v_exp_f32_e32 v72, v59
	v_exp_f32_e32 v73, v61
	v_exp_f32_e32 v74, v63
	v_exp_f32_e32 v75, v75
	v_exp_f32_e32 v76, v20
	v_exp_f32_e32 v77, v21
	v_exp_f32_e32 v78, v18
	v_exp_f32_e32 v79, v19
	v_exp_f32_e32 v50, v52
	v_exp_f32_e32 v51, v53
	v_exp_f32_e32 v52, v54
	v_exp_f32_e32 v53, v55
	v_exp_f32_e32 v54, v56
	v_exp_f32_e32 v55, v58
	v_exp_f32_e32 v56, v60
	v_exp_f32_e32 v57, v62
	v_exp_f32_e32 v58, v26
	v_exp_f32_e32 v59, v27
	v_exp_f32_e32 v60, v24
	v_exp_f32_e32 v61, v25
	v_exp_f32_e32 v62, v22
	v_exp_f32_e32 v63, v23
	s_waitcnt vmcnt(2) lgkmcnt(0)
	s_barrier
	s_andn2_b64 vcc, exec, s[8:9]
	v_cmp_gt_u32_e64 s[8:9], 32, v217
	v_lshl_add_u32 v223, v225, 2, s10
	s_cbranch_vccnz .LBB0_801
	v_mov_b64_e32 v[30:31], v[14:15]
	v_lshl_add_u64 v[192:193], v[80:81], 0, s[20:21]
	v_lshl_add_u64 v[194:195], v[188:189], 0, s[22:23]
	v_lshl_add_u32 v196, v220, 4, s60
	s_movk_i32 s1, 0x4000
	s_movk_i32 s36, 0x2000
	s_mov_b32 s10, 0
	v_mov_b32_e32 v231, 0
	s_mov_b32 s12, 6
	v_mov_b64_e32 v[28:29], v[12:13]
	v_mov_b64_e32 v[26:27], v[10:11]
	v_mov_b64_e32 v[24:25], v[8:9]
	v_mov_b64_e32 v[22:23], v[6:7]
	v_mov_b64_e32 v[20:21], v[4:5]
	v_mov_b64_e32 v[18:19], v[2:3]
	v_mov_b64_e32 v[16:17], v[0:1]
.LBB0_787:
	v_add_u32_e32 v180, s10, v229
	ds_read_b64_tr_b16 v[176:177], v180 offset:24576
	ds_read_b64_tr_b16 v[178:179], v180 offset:25088
	v_add_f32_e32 v80, v64, v65
	v_add_f32_e32 v80, v66, v80
	v_add_f32_e32 v80, v67, v80
	v_add_f32_e32 v80, v68, v80
	v_add_f32_e32 v96, v69, v80
	s_waitcnt lgkmcnt(9)
	v_mfma_f32_32x32x16_bf16 v[80:95], v[172:175], v[128:131], v[32:47]
	v_cvt_pk_bf16_f32 v140, v64, v65
	v_cvt_pk_bf16_f32 v141, v66, v67
	ds_read_b64_tr_b16 v[172:173], v180 offset:28672
	ds_read_b64_tr_b16 v[174:175], v180 offset:29184
	v_add_f32_e32 v64, v70, v96
	v_add_f32_e32 v64, v71, v64
	v_add_f32_e32 v64, v72, v64
	v_add_f32_e32 v64, v73, v64
	v_cvt_pk_bf16_f32 v142, v68, v69
	v_cvt_pk_bf16_f32 v143, v70, v71
	s_waitcnt lgkmcnt(10)
	v_mfma_f32_32x32x16_bf16 v[96:111], v[168:171], v[128:131], v[32:47]
	ds_read_b64_tr_b16 v[168:169], v180 offset:25600
	ds_read_b64_tr_b16 v[170:171], v180 offset:26112
	s_waitcnt lgkmcnt(11)
	v_mfma_f32_32x32x16_bf16 v[80:95], v[164:167], v[120:123], v[80:95]
	v_add_f32_e32 v64, v74, v64
	v_add_f32_e32 v64, v75, v64
	v_add_f32_e32 v64, v76, v64
	v_add_f32_e32 v64, v77, v64
	v_cvt_pk_bf16_f32 v136, v72, v73
	v_cvt_pk_bf16_f32 v137, v74, v75
	ds_read_b64_tr_b16 v[164:165], v180 offset:29696
	ds_read_b64_tr_b16 v[166:167], v180 offset:30208
	v_add_f32_e32 v64, v78, v64
	v_add_f32_e32 v64, v79, v64
	v_add_f32_e32 v64, v48, v64
	v_add_f32_e32 v64, v49, v64
	v_cvt_pk_bf16_f32 v138, v76, v77
	v_cvt_pk_bf16_f32 v139, v78, v79
	s_waitcnt lgkmcnt(12)
	v_mfma_f32_32x32x16_bf16 v[96:111], v[160:163], v[120:123], v[96:111]
	ds_read_b64_tr_b16 v[160:161], v180 offset:26624
	ds_read_b64_tr_b16 v[162:163], v180 offset:27136
	s_waitcnt lgkmcnt(13)
	v_mfma_f32_32x32x16_bf16 v[80:95], v[156:159], v[116:119], v[80:95]
	v_add_f32_e32 v64, v50, v64
	v_add_f32_e32 v64, v51, v64
	v_add_f32_e32 v64, v52, v64
	v_add_f32_e32 v64, v53, v64
	v_cvt_pk_bf16_f32 v132, v48, v49
	v_cvt_pk_bf16_f32 v133, v50, v51
	ds_read_b64_tr_b16 v[156:157], v180 offset:30720
	ds_read_b64_tr_b16 v[158:159], v180 offset:31232
	v_add_f32_e32 v48, v54, v64
	v_add_f32_e32 v48, v55, v48
	v_add_f32_e32 v48, v56, v48
	v_add_f32_e32 v48, v57, v48
	v_cvt_pk_bf16_f32 v134, v52, v53
	v_cvt_pk_bf16_f32 v135, v54, v55
	s_waitcnt lgkmcnt(14)
	v_mfma_f32_32x32x16_bf16 v[96:111], v[152:155], v[116:119], v[96:111]
	ds_read_b64_tr_b16 v[152:153], v180 offset:27648
	ds_read_b64_tr_b16 v[154:155], v180 offset:28160
	s_waitcnt lgkmcnt(14)
	v_mfma_f32_32x32x16_bf16 v[80:95], v[148:151], v[112:115], v[80:95]
	v_add_f32_e32 v48, v58, v48
	v_add_f32_e32 v48, v59, v48
	v_add_f32_e32 v48, v60, v48
	v_add_f32_e32 v48, v61, v48
	v_cvt_pk_bf16_f32 v124, v56, v57
	v_cvt_pk_bf16_f32 v125, v58, v59
	ds_read_b64_tr_b16 v[148:149], v180 offset:31744
	ds_read_b64_tr_b16 v[150:151], v180 offset:32256
	v_add_f32_e32 v48, v62, v48
	v_add_f32_e32 v48, v63, v48
	v_add_f32_e32 v180, 0, v48
	v_cvt_pk_bf16_f32 v126, v60, v61
	v_cvt_pk_bf16_f32 v127, v62, v63
	v_mfma_f32_32x32x16_bf16 v[96:111], v[144:147], v[112:115], v[96:111]
	v_lshl_add_u64 v[48:49], v[194:195], 0, s[24:25]
	s_add_i32 s0, s36, s65
	s_mov_b32 m0, s0
	s_nop 0
	global_load_lds_dwordx4 v[48:49], off
	v_lshl_add_u64 v[48:49], v[192:193], 0, s[24:25]
	s_add_i32 s0, s1, s68
	s_mov_b32 m0, s0
	s_nop 0
	global_load_lds_dwordx4 v[48:49], off
	ds_read_b128 v[48:51], v196
	ds_read_b128 v[52:55], v196 offset:128
	s_waitcnt lgkmcnt(1)
	v_pk_add_f32 v[64:65], v[80:81], v[48:49]
	s_waitcnt lgkmcnt(0)
	s_nop 2
	v_pk_add_f32 v[48:49], v[96:97], v[52:53]
	v_pk_add_f32 v[66:67], v[82:83], v[50:51]
	v_pk_add_f32 v[50:51], v[98:99], v[54:55]
	ds_read_b128 v[52:55], v196 offset:32
	ds_read_b128 v[56:59], v196 offset:160
	s_waitcnt lgkmcnt(1)
	v_pk_add_f32 v[68:69], v[84:85], v[52:53]
	s_waitcnt lgkmcnt(0)
	v_pk_add_f32 v[52:53], v[100:101], v[56:57]
	v_pk_add_f32 v[70:71], v[86:87], v[54:55]
	v_pk_add_f32 v[54:55], v[102:103], v[58:59]
	ds_read_b128 v[56:59], v196 offset:64
	ds_read_b128 v[60:63], v196 offset:192
	s_waitcnt lgkmcnt(1)
	v_pk_add_f32 v[72:73], v[88:89], v[56:57]
	s_waitcnt lgkmcnt(0)
	v_pk_add_f32 v[56:57], v[104:105], v[60:61]
	v_pk_add_f32 v[74:75], v[90:91], v[58:59]
	v_pk_add_f32 v[58:59], v[106:107], v[62:63]
	ds_read_b128 v[60:63], v196 offset:96
	ds_read_b128 v[78:81], v196 offset:224
	s_waitcnt lgkmcnt(1)
	v_pk_add_f32 v[76:77], v[92:93], v[60:61]
	s_waitcnt lgkmcnt(0)
	v_pk_add_f32 v[60:61], v[108:109], v[78:79]
	v_pk_add_f32 v[78:79], v[94:95], v[62:63]
	v_pk_add_f32 v[62:63], v[110:111], v[80:81]
	v_max_f32_e32 v80, v64, v65
	v_max3_f32 v81, v66, v67, v49
	v_max3_f32 v80, v80, v48, v50
	v_max3_f32 v80, v80, v51, v68
	v_max3_f32 v81, v81, v70, v71
	v_max3_f32 v80, v80, v69, v52
	v_max3_f32 v81, v81, v54, v55
	v_max3_f32 v80, v80, v53, v72
	v_max3_f32 v81, v81, v74, v75
	v_max3_f32 v80, v80, v73, v56
	v_max3_f32 v81, v81, v58, v59
	v_max3_f32 v80, v80, v57, v76
	v_max3_f32 v81, v81, v78, v79
	v_max3_f32 v80, v80, v77, v60
	v_max3_f32 v81, v81, v62, v63
	v_max3_f32 v80, v80, v61, v81
	v_mov_b32_e32 v81, v80
	s_nop 1
	v_permlane32_swap_b32_e32 v80, v81
	v_max_f32_e32 v81, v81, v81
	v_max_f32_e32 v80, v80, v80
	v_max_f32_e32 v80, v80, v81
	v_cmp_lt_f32_e32 vcc, s61, v80
	s_cmp_lg_u64 vcc, 0
	v_add_f32_e32 v197, v231, v180
	s_cselect_b64 s[10:11], -1, 0
	s_cbranch_vccnz .LBB0_795

.LBB0_790:
	s_add_i32 s0, s1, 0x2000
	s_cmpk_lg_i32 s1, 0x4000
	s_cselect_b32 s71, s0, 0
	v_add_u32_e32 v198, s36, v229
	ds_read_b64_tr_b16 v[160:161], v198 offset:24576
	ds_read_b64_tr_b16 v[162:163], v198 offset:25088
	v_add_f32_e32 v80, v64, v65
	v_add_f32_e32 v80, v66, v80
	v_add_f32_e32 v80, v67, v80
	v_add_f32_e32 v80, v68, v80
	v_add_f32_e32 v100, v69, v80
	s_waitcnt lgkmcnt(9)
	v_mfma_f32_32x32x16_bf16 v[80:95], v[96:99], v[128:131], v[32:47]
	v_cvt_pk_bf16_f32 v140, v64, v65
	v_cvt_pk_bf16_f32 v141, v66, v67
	ds_read_b64_tr_b16 v[156:157], v198 offset:28672
	ds_read_b64_tr_b16 v[158:159], v198 offset:29184
	v_add_f32_e32 v64, v70, v100
	v_add_f32_e32 v64, v71, v64
	v_add_f32_e32 v64, v72, v64
	v_add_f32_e32 v64, v73, v64
	v_cvt_pk_bf16_f32 v142, v68, v69
	v_cvt_pk_bf16_f32 v143, v70, v71
	s_waitcnt lgkmcnt(10)
	v_mfma_f32_32x32x16_bf16 v[96:111], v[180:183], v[128:131], v[32:47]
	ds_read_b64_tr_b16 v[152:153], v198 offset:25600
	ds_read_b64_tr_b16 v[154:155], v198 offset:26112
	s_waitcnt lgkmcnt(11)
	v_mfma_f32_32x32x16_bf16 v[80:95], v[184:187], v[120:123], v[80:95]
	v_add_f32_e32 v64, v74, v64
	v_add_f32_e32 v64, v75, v64
	v_add_f32_e32 v64, v76, v64
	v_add_f32_e32 v64, v77, v64
	v_cvt_pk_bf16_f32 v136, v72, v73
	v_cvt_pk_bf16_f32 v137, v74, v75
	ds_read_b64_tr_b16 v[148:149], v198 offset:29696
	ds_read_b64_tr_b16 v[150:151], v198 offset:30208
	v_add_f32_e32 v64, v78, v64
	v_add_f32_e32 v64, v79, v64
	v_add_f32_e32 v64, v48, v64
	v_add_f32_e32 v64, v49, v64
	v_cvt_pk_bf16_f32 v138, v76, v77
	v_cvt_pk_bf16_f32 v139, v78, v79
	s_waitcnt lgkmcnt(12)
	v_mfma_f32_32x32x16_bf16 v[96:111], v[144:147], v[120:123], v[96:111]
	ds_read_b64_tr_b16 v[144:145], v198 offset:26624
	ds_read_b64_tr_b16 v[146:147], v198 offset:27136
	s_waitcnt lgkmcnt(13)
	v_mfma_f32_32x32x16_bf16 v[80:95], v[176:179], v[116:119], v[80:95]
	v_add_f32_e32 v64, v50, v64
	v_add_f32_e32 v64, v51, v64
	v_add_f32_e32 v64, v52, v64
	v_add_f32_e32 v64, v53, v64
	v_cvt_pk_bf16_f32 v132, v48, v49
	v_cvt_pk_bf16_f32 v133, v50, v51
	ds_read_b64_tr_b16 v[184:185], v198 offset:30720
	ds_read_b64_tr_b16 v[186:187], v198 offset:31232
	v_add_f32_e32 v48, v54, v64
	v_add_f32_e32 v48, v55, v48
	v_add_f32_e32 v48, v56, v48
	v_add_f32_e32 v48, v57, v48
	v_cvt_pk_bf16_f32 v134, v52, v53
	v_cvt_pk_bf16_f32 v135, v54, v55
	s_waitcnt lgkmcnt(14)
	v_mfma_f32_32x32x16_bf16 v[96:111], v[168:171], v[116:119], v[96:111]
	ds_read_b64_tr_b16 v[180:181], v198 offset:27648
	ds_read_b64_tr_b16 v[182:183], v198 offset:28160
	s_waitcnt lgkmcnt(14)
	v_mfma_f32_32x32x16_bf16 v[80:95], v[172:175], v[112:115], v[80:95]
	v_add_f32_e32 v48, v58, v48
	v_add_f32_e32 v48, v59, v48
	v_add_f32_e32 v48, v60, v48
	v_add_f32_e32 v48, v61, v48
	v_cvt_pk_bf16_f32 v124, v56, v57
	v_cvt_pk_bf16_f32 v125, v58, v59
	ds_read_b64_tr_b16 v[176:177], v198 offset:31744
	ds_read_b64_tr_b16 v[178:179], v198 offset:32256
	v_add_f32_e32 v48, v62, v48
	v_add_f32_e32 v48, v63, v48
	v_add_f32_e32 v168, 0, v48
	v_cvt_pk_bf16_f32 v126, v60, v61
	v_cvt_pk_bf16_f32 v127, v62, v63
	v_mfma_f32_32x32x16_bf16 v[96:111], v[164:167], v[112:115], v[96:111]
	s_add_i32 s0, s1, s65
	s_mov_b32 m0, s0
	s_nop 0
	global_load_lds_dwordx4 v[194:195], off
	s_add_i32 s0, s71, s68
	s_mov_b32 m0, s0
	s_nop 0
	global_load_lds_dwordx4 v[192:193], off
	ds_read_b128 v[48:51], v196 offset:256
	ds_read_b128 v[52:55], v196 offset:384
	s_waitcnt lgkmcnt(1)
	v_pk_add_f32 v[64:65], v[80:81], v[48:49]
	s_waitcnt lgkmcnt(0)
	s_nop 4
	v_pk_add_f32 v[48:49], v[96:97], v[52:53]
	v_pk_add_f32 v[66:67], v[82:83], v[50:51]
	v_pk_add_f32 v[50:51], v[98:99], v[54:55]
	ds_read_b128 v[52:55], v196 offset:288
	ds_read_b128 v[56:59], v196 offset:416
	s_waitcnt lgkmcnt(1)
	v_pk_add_f32 v[68:69], v[84:85], v[52:53]
	s_waitcnt lgkmcnt(0)
	v_pk_add_f32 v[52:53], v[100:101], v[56:57]
	v_pk_add_f32 v[70:71], v[86:87], v[54:55]
	v_pk_add_f32 v[54:55], v[102:103], v[58:59]
	ds_read_b128 v[56:59], v196 offset:320
	ds_read_b128 v[60:63], v196 offset:448
	s_waitcnt lgkmcnt(1)
	v_pk_add_f32 v[72:73], v[88:89], v[56:57]
	s_waitcnt lgkmcnt(0)
	v_pk_add_f32 v[56:57], v[104:105], v[60:61]
	v_pk_add_f32 v[74:75], v[90:91], v[58:59]
	v_pk_add_f32 v[58:59], v[106:107], v[62:63]
	ds_read_b128 v[60:63], v196 offset:352
	ds_read_b128 v[78:81], v196 offset:480
	s_waitcnt lgkmcnt(1)
	v_pk_add_f32 v[76:77], v[92:93], v[60:61]
	s_waitcnt lgkmcnt(0)
	v_pk_add_f32 v[60:61], v[108:109], v[78:79]
	v_pk_add_f32 v[78:79], v[94:95], v[62:63]
	v_pk_add_f32 v[62:63], v[110:111], v[80:81]
	v_max_f32_e32 v80, v64, v65
	v_max3_f32 v81, v66, v67, v49
	v_max3_f32 v80, v80, v48, v50
	v_max3_f32 v80, v80, v51, v68
	v_max3_f32 v81, v81, v70, v71
	v_max3_f32 v80, v80, v69, v52
	v_max3_f32 v81, v81, v54, v55
	v_max3_f32 v80, v80, v53, v72
	v_max3_f32 v81, v81, v74, v75
	v_max3_f32 v80, v80, v73, v56
	v_max3_f32 v81, v81, v58, v59
	v_max3_f32 v80, v80, v57, v76
	v_max3_f32 v81, v81, v78, v79
	v_max3_f32 v80, v80, v77, v60
	v_max3_f32 v81, v81, v62, v63
	v_max3_f32 v80, v80, v61, v81
	v_mov_b32_e32 v81, v80
	s_nop 1
	v_permlane32_swap_b32_e32 v80, v81
	v_max_f32_e32 v81, v81, v81
	v_max_f32_e32 v80, v80, v80
	v_max_f32_e32 v80, v80, v81
	v_cmp_lt_f32_e32 vcc, s61, v80
	s_cmp_lg_u64 vcc, 0
	v_add_f32_e32 v231, v197, v168
	s_cselect_b64 s[10:11], -1, 0
	s_cbranch_vccnz .LBB0_798

.LBB0_810:
	v_add_u32_e32 v178, s1, v229
	ds_read_b64_tr_b16 v[200:201], v178 offset:24576
	ds_read_b64_tr_b16 v[202:203], v178 offset:25088
	s_waitcnt lgkmcnt(3)
	v_mfma_f32_32x32x16_bf16 v[96:111], v[172:175], v[128:131], v[32:47]
	v_add_f32_e32 v80, v64, v65
	v_add_f32_e32 v80, v66, v80
	v_add_f32_e32 v80, v67, v80
	v_add_f32_e32 v80, v68, v80
	v_add_f32_e32 v80, v69, v80
	v_cvt_pk_bf16_f32 v140, v64, v65
	v_cvt_pk_bf16_f32 v141, v66, v67
	ds_read_b64_tr_b16 v[172:173], v178 offset:28672
	ds_read_b64_tr_b16 v[174:175], v178 offset:29184
	v_add_f32_e32 v64, v70, v80
	s_waitcnt lgkmcnt(4)
	v_mfma_f32_32x32x16_bf16 v[80:95], v[168:171], v[128:131], v[32:47]
	v_add_f32_e32 v64, v71, v64
	v_add_f32_e32 v64, v72, v64
	v_add_f32_e32 v64, v73, v64
	v_cvt_pk_bf16_f32 v142, v68, v69
	v_cvt_pk_bf16_f32 v143, v70, v71
	ds_read_b64_tr_b16 v[196:197], v178 offset:25600
	ds_read_b64_tr_b16 v[198:199], v178 offset:26112
	s_waitcnt lgkmcnt(11)
	v_mfma_f32_32x32x16_bf16 v[96:111], v[164:167], v[120:123], v[96:111]
	v_add_f32_e32 v64, v74, v64
	v_add_f32_e32 v64, v75, v64
	v_add_f32_e32 v64, v76, v64
	v_add_f32_e32 v64, v77, v64
	v_cvt_pk_bf16_f32 v136, v72, v73
	v_cvt_pk_bf16_f32 v137, v74, v75
	ds_read_b64_tr_b16 v[192:193], v178 offset:29696
	ds_read_b64_tr_b16 v[194:195], v178 offset:30208
	s_waitcnt lgkmcnt(12)
	v_mfma_f32_32x32x16_bf16 v[80:95], v[160:163], v[120:123], v[80:95]
	v_add_f32_e32 v64, v78, v64
	v_add_f32_e32 v64, v79, v64
	v_add_f32_e32 v64, v48, v64
	v_add_f32_e32 v64, v49, v64
	v_cvt_pk_bf16_f32 v138, v76, v77
	v_cvt_pk_bf16_f32 v139, v78, v79
	ds_read_b64_tr_b16 v[188:189], v178 offset:26624
	ds_read_b64_tr_b16 v[190:191], v178 offset:27136
	s_waitcnt lgkmcnt(13)
	v_mfma_f32_32x32x16_bf16 v[96:111], v[156:159], v[116:119], v[96:111]
	v_add_f32_e32 v64, v50, v64
	v_add_f32_e32 v64, v51, v64
	v_add_f32_e32 v64, v52, v64
	v_add_f32_e32 v64, v53, v64
	v_cvt_pk_bf16_f32 v132, v48, v49
	v_cvt_pk_bf16_f32 v133, v50, v51
	ds_read_b64_tr_b16 v[184:185], v178 offset:30720
	ds_read_b64_tr_b16 v[186:187], v178 offset:31232
	s_waitcnt lgkmcnt(14)
	v_mfma_f32_32x32x16_bf16 v[80:95], v[152:155], v[116:119], v[80:95]
	v_add_f32_e32 v48, v54, v64
	v_add_f32_e32 v48, v55, v48
	v_add_f32_e32 v48, v56, v48
	v_add_f32_e32 v48, v57, v48
	v_cvt_pk_bf16_f32 v134, v52, v53
	v_cvt_pk_bf16_f32 v135, v54, v55
	ds_read_b64_tr_b16 v[180:181], v178 offset:27648
	ds_read_b64_tr_b16 v[182:183], v178 offset:28160
	s_waitcnt lgkmcnt(14)
	v_mfma_f32_32x32x16_bf16 v[96:111], v[148:151], v[112:115], v[96:111]
	v_add_f32_e32 v48, v58, v48
	v_add_f32_e32 v48, v59, v48
	v_add_f32_e32 v48, v60, v48
	v_add_f32_e32 v48, v61, v48
	v_cvt_pk_bf16_f32 v124, v56, v57
	v_cvt_pk_bf16_f32 v125, v58, v59
	ds_read_b64_tr_b16 v[176:177], v178 offset:31744
	ds_read_b64_tr_b16 v[178:179], v178 offset:32256
	v_mfma_f32_32x32x16_bf16 v[80:95], v[144:147], v[112:115], v[80:95]
	v_add_f32_e32 v48, v62, v48
	v_add_f32_e32 v48, v63, v48
	v_add_f32_e32 v148, 0, v48
	v_cvt_pk_bf16_f32 v126, v60, v61
	v_cvt_pk_bf16_f32 v127, v62, v63
	s_add_i32 s1, s39, 1
	s_cmp_ge_u32 s1, s70
	s_cselect_b64 s[30:31], -1, 0
	s_and_b64 vcc, exec, s[30:31]
	s_cbranch_vccnz .LBB0_812
	s_add_i32 s1, s71, s65
	v_lshl_add_u64 v[48:49], v[212:213], 0, s[24:25]
	s_mov_b32 m0, s1
	s_nop 0
	global_load_lds_dwordx4 v[48:49], off
; __device__ __forceinline__ void cmask(f32x16&p0,f32x16&p1,int jb,int qrel,int hi){
;   const float NEG=-INFINITY; int kb=64*jb+4*hi;
;   #pragma unroll
;   for(int r=0;r<16;++r){int kv=kb+(r&3)+8*(r>>2); if(kv>qrel)p0[r]=NEG; if(kv+32>qrel)p1[r]=NEG;}
; }
.LBB0_812:
	s_add_i32 s1, s0, s68
	s_mov_b32 m0, s1
	s_nop 0
	global_load_lds_dwordx4 v[210:211], off
	ds_read_b128 v[48:51], v233
	ds_read_b128 v[52:55], v233 offset:128
	ds_read_b128 v[56:59], v233 offset:32
	ds_read_b128 v[60:63], v233 offset:160
	ds_read_b128 v[72:75], v233 offset:64
	ds_read_b128 v[144:147], v233 offset:192
	ds_read_b128 v[76:79], v233 offset:96
	ds_read_b128 v[150:153], v233 offset:224
	s_waitcnt lgkmcnt(7)
	v_pk_add_f32 v[66:67], v[98:99], v[50:51]
	s_waitcnt lgkmcnt(5)
	v_pk_add_f32 v[70:71], v[102:103], v[58:59]
	s_waitcnt lgkmcnt(3)
	v_pk_add_f32 v[74:75], v[106:107], v[74:75]
	s_waitcnt lgkmcnt(1)
	v_pk_add_f32 v[78:79], v[110:111], v[78:79]
	v_pk_add_f32 v[64:65], v[96:97], v[48:49]
	v_pk_add_f32 v[68:69], v[100:101], v[56:57]
	v_pk_add_f32 v[72:73], v[104:105], v[72:73]
	v_pk_add_f32 v[76:77], v[108:109], v[76:77]
	v_pk_add_f32 v[50:51], v[82:83], v[54:55]
	v_pk_add_f32 v[54:55], v[86:87], v[62:63]
	v_pk_add_f32 v[58:59], v[90:91], v[146:147]
	s_waitcnt lgkmcnt(0)
	v_pk_add_f32 v[62:63], v[94:95], v[152:153]
	v_pk_add_f32 v[48:49], v[80:81], v[52:53]
	v_pk_add_f32 v[52:53], v[84:85], v[60:61]
	v_pk_add_f32 v[56:57], v[88:89], v[144:145]
	v_pk_add_f32 v[60:61], v[92:93], v[150:151]
	s_add_i32 s1, s38, s39
	s_add_i32 s10, s1, -2
	s_cmp_lt_i32 s10, 0
	s_cbranch_scc1 .LBB0_814
	v_add_u32_e32 v81, 0xffffffa5, v232
	v_add_u32_e32 v80, 0xffffff85, v232
	v_cmp_le_i32_e32 vcc, v81, v226
	s_nop 1
	v_cndmask_b32_e32 v48, v216, v48, vcc
	v_cmp_lt_i32_e32 vcc, v80, v226
	s_nop 1
	v_cndmask_b32_e32 v65, v216, v65, vcc
	v_cmp_le_i32_e32 vcc, v80, v226
	v_add_u32_e32 v80, 0xffffffa6, v232
	s_nop 0
	v_cndmask_b32_e32 v64, v216, v64, vcc
	v_cmp_le_i32_e32 vcc, v80, v226
	v_add_u32_e32 v80, 0xffffff87, v232
	s_nop 0
	v_cndmask_b32_e32 v49, v216, v49, vcc
	v_cmp_le_i32_e32 vcc, v80, v226
	v_add_u32_e32 v80, 0xffffffa7, v232
	s_nop 0
	v_cndmask_b32_e32 v66, v216, v66, vcc
	v_cmp_le_i32_e32 vcc, v80, v226
	v_add_u32_e32 v80, 0xffffff88, v232
	s_nop 0
	v_cndmask_b32_e32 v50, v216, v50, vcc
	v_cmp_le_i32_e32 vcc, v80, v226
	v_add_u32_e32 v80, 0xffffffa8, v232
	s_nop 0
	v_cndmask_b32_e32 v67, v216, v67, vcc
	v_cmp_le_i32_e32 vcc, v80, v226
	v_add_u32_e32 v80, 0xffffff8d, v232
	s_nop 0
	v_cndmask_b32_e32 v51, v216, v51, vcc
	v_cmp_le_i32_e32 vcc, v80, v226
	v_add_u32_e32 v80, 0xffffffad, v232
	s_nop 0
	v_cndmask_b32_e32 v68, v216, v68, vcc
	v_cmp_le_i32_e32 vcc, v80, v226
	v_add_u32_e32 v80, 0xffffff8e, v232
	s_nop 0
	v_cndmask_b32_e32 v52, v216, v52, vcc
	v_cmp_le_i32_e32 vcc, v80, v226
	v_add_u32_e32 v80, 0xffffffae, v232
	s_nop 0
	v_cndmask_b32_e32 v69, v216, v69, vcc
	v_cmp_le_i32_e32 vcc, v80, v226
	v_add_u32_e32 v80, 0xffffff8f, v232
	s_nop 0
	v_cndmask_b32_e32 v53, v216, v53, vcc
	v_cmp_le_i32_e32 vcc, v80, v226
	v_add_u32_e32 v80, 0xffffffaf, v232
	s_nop 0
	v_cndmask_b32_e32 v70, v216, v70, vcc
	v_cmp_le_i32_e32 vcc, v80, v226
	v_add_u32_e32 v80, 0xffffff90, v232
	s_nop 0
	v_cndmask_b32_e32 v54, v216, v54, vcc
	v_cmp_le_i32_e32 vcc, v80, v226
	v_add_u32_e32 v80, 0xffffffb0, v232
	s_nop 0
	v_cndmask_b32_e32 v71, v216, v71, vcc
	v_cmp_le_i32_e32 vcc, v80, v226
	v_add_u32_e32 v80, 0xffffff95, v232
	s_nop 0
	v_cndmask_b32_e32 v55, v216, v55, vcc
	v_cmp_le_i32_e32 vcc, v80, v226
	v_add_u32_e32 v80, 0xffffffb5, v232
	s_nop 0
	v_cndmask_b32_e32 v72, v216, v72, vcc
	v_cmp_le_i32_e32 vcc, v80, v226
	v_add_u32_e32 v80, 0xffffff96, v232
	s_nop 0
	v_cndmask_b32_e32 v56, v216, v56, vcc
	v_cmp_le_i32_e32 vcc, v80, v226
	v_add_u32_e32 v80, 0xffffffb6, v232
	s_nop 0
	v_cndmask_b32_e32 v73, v216, v73, vcc
	v_cmp_le_i32_e32 vcc, v80, v226
	v_add_u32_e32 v80, 0xffffff97, v232
	s_nop 0
	v_cndmask_b32_e32 v57, v216, v57, vcc
	v_cmp_le_i32_e32 vcc, v80, v226
	v_add_u32_e32 v80, 0xffffffb7, v232
	s_nop 0
	v_cndmask_b32_e32 v74, v216, v74, vcc
	v_cmp_le_i32_e32 vcc, v80, v226
	v_add_u32_e32 v80, 0xffffff98, v232
	s_nop 0
	v_cndmask_b32_e32 v58, v216, v58, vcc
	v_cmp_le_i32_e32 vcc, v80, v226
	v_add_u32_e32 v80, 0xffffffb8, v232
	s_nop 0
	v_cndmask_b32_e32 v75, v216, v75, vcc
	v_cmp_le_i32_e32 vcc, v80, v226
	v_add_u32_e32 v80, 0xffffff9d, v232
	s_nop 0
	v_cndmask_b32_e32 v59, v216, v59, vcc
	v_cmp_le_i32_e32 vcc, v80, v226
	v_add_u32_e32 v80, 0xffffffbd, v232
	s_nop 0
	v_cndmask_b32_e32 v76, v216, v76, vcc
	v_cmp_le_i32_e32 vcc, v80, v226
	v_add_u32_e32 v80, 0xffffff9e, v232
	s_nop 0
	v_cndmask_b32_e32 v60, v216, v60, vcc
	v_cmp_le_i32_e32 vcc, v80, v226
	v_add_u32_e32 v80, 0xffffffbe, v232
	s_nop 0
	v_cndmask_b32_e32 v77, v216, v77, vcc
	v_cmp_le_i32_e32 vcc, v80, v226
	v_add_u32_e32 v80, 0xffffff9f, v232
	s_nop 0
	v_cndmask_b32_e32 v61, v216, v61, vcc
	v_cmp_le_i32_e32 vcc, v80, v226
	v_add_u32_e32 v80, 0xffffffbf, v232
	s_nop 0
	v_cndmask_b32_e32 v78, v216, v78, vcc
	v_cmp_le_i32_e32 vcc, v80, v226
	v_add_u32_e32 v80, 0xffffffa0, v232
	s_nop 0
	v_cndmask_b32_e32 v62, v216, v62, vcc
	v_cmp_le_i32_e32 vcc, v80, v226
	v_subrev_u32_e32 v80, 64, v232
	s_nop 0
	v_cndmask_b32_e32 v79, v216, v79, vcc
	v_cmp_le_i32_e32 vcc, v80, v226
	s_nop 1
	v_cndmask_b32_e32 v63, v216, v63, vcc

.LBB0_819:
	v_add_u32_e32 v178, s71, v229
	ds_read_b64_tr_b16 v[204:205], v178 offset:24576
	ds_read_b64_tr_b16 v[206:207], v178 offset:25088
	s_waitcnt lgkmcnt(9)
	v_mfma_f32_32x32x16_bf16 v[96:111], v[172:175], v[128:131], v[32:47]
	v_add_f32_e32 v80, v64, v65
	v_add_f32_e32 v80, v66, v80
	v_add_f32_e32 v80, v67, v80
	v_add_f32_e32 v80, v68, v80
	v_add_f32_e32 v80, v69, v80
	v_cvt_pk_bf16_f32 v140, v64, v65
	v_cvt_pk_bf16_f32 v141, v66, v67
	ds_read_b64_tr_b16 v[200:201], v178 offset:28672
	ds_read_b64_tr_b16 v[202:203], v178 offset:29184
	v_add_f32_e32 v64, v70, v80
	s_waitcnt lgkmcnt(10)
	v_mfma_f32_32x32x16_bf16 v[80:95], v[168:171], v[128:131], v[32:47]
	v_add_f32_e32 v64, v71, v64
	v_add_f32_e32 v64, v72, v64
	v_add_f32_e32 v64, v73, v64
	v_cvt_pk_bf16_f32 v142, v68, v69
	v_cvt_pk_bf16_f32 v143, v70, v71
	ds_read_b64_tr_b16 v[196:197], v178 offset:25600
	ds_read_b64_tr_b16 v[198:199], v178 offset:26112
	s_waitcnt lgkmcnt(11)
	v_mfma_f32_32x32x16_bf16 v[96:111], v[164:167], v[120:123], v[96:111]
	v_add_f32_e32 v64, v74, v64
	v_add_f32_e32 v64, v75, v64
	v_add_f32_e32 v64, v76, v64
	v_add_f32_e32 v64, v77, v64
	v_cvt_pk_bf16_f32 v136, v72, v73
	v_cvt_pk_bf16_f32 v137, v74, v75
	ds_read_b64_tr_b16 v[192:193], v178 offset:29696
	ds_read_b64_tr_b16 v[194:195], v178 offset:30208
	s_waitcnt lgkmcnt(12)
	v_mfma_f32_32x32x16_bf16 v[80:95], v[160:163], v[120:123], v[80:95]
	v_add_f32_e32 v64, v78, v64
	v_add_f32_e32 v64, v79, v64
	v_add_f32_e32 v64, v48, v64
	v_add_f32_e32 v64, v49, v64
	v_cvt_pk_bf16_f32 v138, v76, v77
	v_cvt_pk_bf16_f32 v139, v78, v79
	ds_read_b64_tr_b16 v[188:189], v178 offset:26624
	ds_read_b64_tr_b16 v[190:191], v178 offset:27136
	s_waitcnt lgkmcnt(13)
	v_mfma_f32_32x32x16_bf16 v[96:111], v[156:159], v[116:119], v[96:111]
	v_add_f32_e32 v64, v50, v64
	v_add_f32_e32 v64, v51, v64
	v_add_f32_e32 v64, v52, v64
	v_add_f32_e32 v64, v53, v64
	v_cvt_pk_bf16_f32 v132, v48, v49
	v_cvt_pk_bf16_f32 v133, v50, v51
	ds_read_b64_tr_b16 v[184:185], v178 offset:30720
	ds_read_b64_tr_b16 v[186:187], v178 offset:31232
	s_waitcnt lgkmcnt(14)
	v_mfma_f32_32x32x16_bf16 v[80:95], v[152:155], v[116:119], v[80:95]
	v_add_f32_e32 v48, v54, v64
	v_add_f32_e32 v48, v55, v48
	v_add_f32_e32 v48, v56, v48
	v_add_f32_e32 v48, v57, v48
	v_cvt_pk_bf16_f32 v134, v52, v53
	v_cvt_pk_bf16_f32 v135, v54, v55
	ds_read_b64_tr_b16 v[180:181], v178 offset:27648
	ds_read_b64_tr_b16 v[182:183], v178 offset:28160
	s_waitcnt lgkmcnt(14)
	v_mfma_f32_32x32x16_bf16 v[96:111], v[148:151], v[112:115], v[96:111]
	v_add_f32_e32 v48, v58, v48
	v_add_f32_e32 v48, v59, v48
	v_add_f32_e32 v48, v60, v48
	v_add_f32_e32 v48, v61, v48
	v_cvt_pk_bf16_f32 v124, v56, v57
	v_cvt_pk_bf16_f32 v125, v58, v59
	ds_read_b64_tr_b16 v[176:177], v178 offset:31744
	ds_read_b64_tr_b16 v[178:179], v178 offset:32256
	v_mfma_f32_32x32x16_bf16 v[80:95], v[144:147], v[112:115], v[80:95]
	v_add_f32_e32 v48, v62, v48
	v_add_f32_e32 v48, v63, v48
	v_add_f32_e32 v234, 0, v48
	v_cvt_pk_bf16_f32 v126, v60, v61
	v_cvt_pk_bf16_f32 v127, v62, v63
	s_add_i32 s12, s39, 2
	s_cmp_ge_u32 s12, s70
	s_cselect_b64 s[34:35], -1, 0
	s_and_b64 vcc, exec, s[34:35]
	s_cbranch_vccnz .LBB0_821
	s_add_i32 s10, s0, s65
	s_mov_b32 m0, s10
	s_nop 0
	global_load_lds_dwordx4 v[212:213], off
.LBB0_821:
	s_add_i32 s10, s0, 0x2000
	s_cmpk_lg_i32 s0, 0x4000
	s_cselect_b32 s71, s10, 0
	s_cmp_lt_u32 s39, s70
	s_cselect_b64 s[36:37], -1, 0
	s_cmp_ge_u32 s39, s70
	s_cbranch_scc1 .LBB0_823
	s_add_i32 s10, s71, s68
	v_lshl_add_u64 v[48:49], v[210:211], 0, s[16:17]
	s_mov_b32 m0, s10
	s_nop 0
	global_load_lds_dwordx4 v[48:49], off

; #define LAS __attribute__((address_space(3)))
; template <int MODE> __device__ __forceinline__ int pop_tile(unsigned& tiles) { int j; if (MODE == 2) { j = 31 - __builtin_clz(tiles); tiles &= ~(1u << j); } else { j = __builtin_ctz(tiles); tiles &= tiles - 1u; } return j; }
; __device__ __forceinline__ void nsa_unit(int b, int g, int tq, const Args& a, LAS unsigned char* lds, int tid, int wave, int lane, int& nxt) {
;     ...
;     const int wv = __builtin_amdgcn_readfirstlane(tid >> 6);
;     const char* ksrc = (const char*)(KS + (size_t)b * SEQ * 128 + 64 * g) + ((size_t)(8 * wv + (lane >> 3)) * 128 + (((lane & 7) ^ (lane >> 3)) * 8)) * 2;
;     const char* vsrc = (const char*)(VS + (size_t)b * SEQ * 128 + 64 * g) + ((size_t)(8 * wv + (lane >> 3)) * 128 + (((lane & 7) ^ (4 * ((lane >> 4) & 1))) * 8)) * 2;
;     const unsigned kvb0 = (unsigned)(uintptr_t)lds;
;     ...
;     unsigned wt; { const int jlo = max(tq - 8, 0); const unsigned hi = (tq == 31) ? 0xffffffffu : ((1u << (tq + 1)) - 1u); wt = hi & ~((1u << jlo) - 1u); }
;     int j0 = pop_tile<2>(wt), m0 = 2, j1 = -1, m1 = 2;
;     NL_DMA(2, j0, 0);
;     if (wt) { j1 = pop_tile<2>(wt); NL_DMA(2, j1, FBUF); }
; __global__ void __launch_bounds__(NTHREADS, 2) fwd_kernel(Args a) {
;     ...
;         for (;;) {
;             volatile LAS int* tick = (volatile LAS int*)(lds + NL_UNI + 8);
;             if (tid == 0) tick[0] = nxt;
;             asm volatile("s_waitcnt lgkmcnt(0)" ::: "memory"); __builtin_amdgcn_s_barrier(); asm volatile("" ::: "memory");
;             const int tk = __builtin_amdgcn_readfirstlane(tick[0]);
;             if (tk >= 1024) break;
;             const int tq = 31 - (tk >> 5), bg = tk & 31;
;             int tu = tid; asm volatile("" : "+v"(tu)); nsa_unit(bg >> 1, bg & 1, tq, a, lds, tu, wave, tu & 63, nxt); }
.LBB0_886:
	s_and_saveexec_b64 s[4:5], s[2:3]
	v_mov_b32_e32 v0, s79
	ds_write_b32 v0, v168
	s_or_b64 exec, exec, s[4:5]
	s_waitcnt lgkmcnt(0)
	s_barrier
	ds_read_b32 v0, v169
	s_waitcnt lgkmcnt(0)
	v_readfirstlane_b32 s4, v0
	s_cmpk_gt_i32 s4, 0x3ff
	s_cselect_b64 s[56:57], -1, 0
	s_and_b64 vcc, exec, s[56:57]
	s_cbranch_vccnz .LBB0_885
	v_mov_b32_e32 v86, v214
	s_ashr_i32 s67, s4, 5
	s_bfe_u32 s0, s4, 0x40001
	v_readfirstlane_b32 s5, v86
	s_sub_i32 s38, 31, s67
	s_and_b32 s1, s4, 1
	s_ashr_i32 s5, s5, 6
	s_lshl_b32 s8, s0, 19
	v_bfe_u32 v34, v86, 3, 3
	s_add_u32 s6, s68, s8
	v_lshl_or_b32 v2, s5, 3, v34
	s_addc_u32 s7, s69, 0
	s_lshl_b32 s9, s1, 7
	v_ashrrev_i32_e32 v3, 31, v2
	s_add_u32 s6, s6, s9
	v_lshlrev_b64 v[2:3], 7, v[2:3]
	v_bitop3_b32 v0, v34, v86, 7 bitop3:0x78
	s_addc_u32 s7, s7, 0
	v_lshl_or_b32 v4, v0, 3, v2
	v_mov_b32_e32 v5, v3
	v_lshl_add_u64 v[160:161], v[4:5], 1, s[6:7]
	s_add_u32 s6, s70, s8
	v_and_b32_e32 v82, 7, v86
	s_addc_u32 s7, s71, 0
	v_bfe_u32 v35, v86, 2, 4
	s_add_u32 s6, s6, s9
	v_bitop3_b32 v0, v35, v82, 4 bitop3:0x6c
	s_addc_u32 s7, s7, 0
	v_lshl_or_b32 v2, v0, 3, v2
	v_lshl_add_u64 v[162:163], v[2:3], 1, s[6:7]
	s_lshl_b32 s6, 2, s38
	v_sub_u32_e64 v0, s38, 8 clamp
	s_add_i32 s6, s6, -1
	s_cmp_gt_u32 s4, 31
	v_readfirstlane_b32 s4, v0
	s_cselect_b32 s15, s6, -1
	s_lshl_b32 s4, -1, s4
	s_and_b32 s4, s15, s4
	s_flbit_i32_b32 s6, s4
	s_xor_b32 s14, s6, 31
	s_lshl_b32 s6, 1, s14
	s_andn2_b32 s4, s4, s6
	s_lshl_b32 s6, s14, 14
	s_or_b32 s44, s6, 0x1000000
	s_lshl_b32 s94, s5, 10
	v_lshl_add_u64 v[2:3], v[160:161], 0, s[44:45]
	s_add_i32 s94, s94, 0
	s_mov_b32 m0, s94
	s_nop 0
	global_load_lds_dwordx4 v[2:3], off
	v_lshl_add_u64 v[2:3], v[162:163], 0, s[44:45]
	s_add_i32 s95, s94, 0x2000
	s_mov_b32 m0, s95
	s_nop 0
	global_load_lds_dwordx4 v[2:3], off
	s_mov_b32 s97, -1
	s_cmp_eq_u32 s4, 0
	s_mov_b32 s39, 0
	s_cbranch_scc1 .LBB0_891
	s_flbit_i32_b32 s5, s4
	s_xor_b32 s97, s5, 31
	s_lshl_b32 s5, 1, s97
	s_andn2_b32 s39, s4, s5
	s_lshl_b32 s4, s97, 14
	s_or_b32 s44, s4, 0x1000000
	v_lshl_add_u64 v[2:3], v[160:161], 0, s[44:45]
	s_add_i32 s4, s94, 0x4000
	s_mov_b32 m0, s4
	s_nop 0
	global_load_lds_dwordx4 v[2:3], off
	v_lshl_add_u64 v[2:3], v[162:163], 0, s[44:45]
	s_add_i32 s4, s94, 0x6000
	s_mov_b32 m0, s4
	s_nop 0
	global_load_lds_dwordx4 v[2:3], off

; template <int MODE> __device__ __forceinline__ int pop_tile(unsigned& tiles) { int j; if (MODE == 2) { j = 31 - __builtin_clz(tiles); tiles &= ~(1u << j); } else { j = __builtin_ctz(tiles); tiles &= tiles - 1u; } return j; }
; __device__ __forceinline__ void nsa_unit(int b, int g, int tq, const Args& a, LAS unsigned char* lds, int tid, int wave, int lane, int& nxt) {
;     ...
;         if (part == 0) { selm[tok] = sel; atomicOr((unsigned*)uni, sel); }
;     }
;     __syncthreads();
;     const unsigned selbits = selm[tl]; unsigned ut = (unsigned)__builtin_amdgcn_readfirstlane((int)uni[0]);
;     if (j1 < 0) { j1 = pop_tile<1>(ut); m1 = 1; NL_DMA(1, j1, FBUF); }
.LBB0_943:
	s_or_b64 exec, exec, s[4:5]
	v_lshl_add_u32 v0, v85, 2, 0
	v_mov_b32_e32 v2, s83
	s_waitcnt lgkmcnt(0)
	s_barrier
	v_add_u32_e32 v0, 0x1d400, v0
	ds_read_b32 v2, v2
	ds_read_b32 v164, v0
	s_mov_b32 s54, 2
	s_cmp_gt_i32 s97, -1
	s_waitcnt lgkmcnt(1)
	v_readfirstlane_b32 s0, v2
	s_cbranch_scc1 .LBB0_945
	s_ff1_i32_b32 s97, s0
	s_add_i32 s1, s0, -1
	s_lshl_b32 s44, s97, 14
	s_and_b32 s0, s1, s0
	v_lshl_add_u64 v[2:3], v[160:161], 0, s[44:45]
	s_add_i32 s1, s94, 0x4000
	s_mov_b32 m0, s1
	s_nop 0
	global_load_lds_dwordx4 v[2:3], off
	v_lshl_add_u64 v[2:3], v[162:163], 0, s[44:45]
	s_add_i32 s1, s94, 0x6000
	s_mov_b32 m0, s1
	s_nop 0
	global_load_lds_dwordx4 v[2:3], off
	s_mov_b32 s54, 1

; template <int MODE> __device__ __forceinline__ int pop_tile(unsigned& tiles) { int j; if (MODE == 2) { j = 31 - __builtin_clz(tiles); tiles &= ~(1u << j); } else { j = __builtin_ctz(tiles); tiles &= tiles - 1u; } return j; }
; __device__ __forceinline__ void nsa_unit(int b, int g, int tq, const Args& a, LAS unsigned char* lds, int tid, int wave, int lane, int& nxt) {
;     ...
;                 int j2, m2; if (wt) { j2 = pop_tile<2>(wt); m2 = 2; } else if (ut) { j2 = pop_tile<1>(ut); m2 = 1; } else { j2 = -1; m2 = 2; }
;                 NL_DMA(m2, (j2 >= 0 ? j2 : j0), o2);
;                 NL_STEP(2, 0u);
.LBB0_953:
	s_cmp_gt_i32 s97, -1
	s_cselect_b64 s[60:61], -1, 0
	s_cmp_lt_i32 s97, 0
	s_cselect_b32 s6, s14, s97
	s_ashr_i32 s7, s6, 31
	s_lshl_b64 s[6:7], s[6:7], 14
	s_add_u32 s4, s6, s4
	s_addc_u32 s5, s7, s5
	v_lshl_add_u64 v[2:3], v[160:161], 0, s[4:5]
	s_add_i32 s6, s51, s94
	s_mov_b32 m0, s6
	s_nop 0
	global_load_lds_dwordx4 v[2:3], off
	v_lshl_add_u64 v[2:3], v[162:163], 0, s[4:5]
	s_add_i32 s4, s51, s95
	s_add_i32 s8, s14, 3
	s_cmp_gt_i32 s8, s38
	s_mov_b32 m0, s4
	s_nop 0
	global_load_lds_dwordx4 v[2:3], off
	s_cselect_b64 s[6:7], -1, 0
	s_add_i32 s4, s14, 8
	s_cmp_eq_u32 s4, s38
	s_cselect_b64 s[4:5], -1, 0
	s_or_b64 s[10:11], s[6:7], s[4:5]
	s_mov_b64 s[6:7], -1
	s_and_b64 vcc, exec, s[10:11]
	s_cbranch_vccnz .LBB0_955
	s_add_i32 s6, s50, 0
	v_add_u32_e32 v6, s6, v183
	ds_read_b128 v[2:5], v6
	ds_read_b128 v[6:9], v6 offset:4096
	v_sub_f32_e32 v80, v185, v0
	v_mov_b32_e32 v81, v80
	v_mov_b32_e32 v82, v80
	v_mov_b32_e32 v83, v80
	v_mov_b32_e32 v84, v80
	v_mov_b32_e32 v85, v80
	v_mov_b32_e32 v86, v80
	v_mov_b32_e32 v87, v80
	v_mov_b32_e32 v88, v80
	v_mov_b32_e32 v89, v80
	v_mov_b32_e32 v90, v80
	v_mov_b32_e32 v91, v80
	v_mov_b32_e32 v92, v80
	v_mov_b32_e32 v93, v80
	v_mov_b32_e32 v94, v80
	v_mov_b32_e32 v95, v80
	s_waitcnt lgkmcnt(1)
	s_nop 0
	v_mfma_f32_32x32x16_bf16 v[96:111], v[2:5], v[144:147], v[80:95]
	s_waitcnt lgkmcnt(0)
	v_mfma_f32_32x32x16_bf16 v[80:95], v[6:9], v[144:147], v[80:95]
	v_add_u32_e32 v6, s6, v184
	ds_read_b128 v[2:5], v6
	ds_read_b128 v[6:9], v6 offset:4096
	s_waitcnt lgkmcnt(1)
	v_mfma_f32_32x32x16_bf16 v[96:111], v[2:5], v[148:151], v[96:111]
	s_waitcnt lgkmcnt(0)
	v_mfma_f32_32x32x16_bf16 v[80:95], v[6:9], v[148:151], v[80:95]
	v_add_u32_e32 v6, s6, v186
	ds_read_b128 v[2:5], v6
	ds_read_b128 v[6:9], v6 offset:4096
	s_waitcnt lgkmcnt(1)
	v_mfma_f32_32x32x16_bf16 v[96:111], v[2:5], v[152:155], v[96:111]
	s_waitcnt lgkmcnt(0)
	v_mfma_f32_32x32x16_bf16 v[80:95], v[6:9], v[152:155], v[80:95]
	v_add_u32_e32 v6, s6, v187
	ds_read_b128 v[2:5], v6
	ds_read_b128 v[6:9], v6 offset:4096
	s_mov_b64 s[6:7], 0
	s_waitcnt lgkmcnt(1)
	v_mfma_f32_32x32x16_bf16 v[96:111], v[2:5], v[156:159], v[96:111]
	s_waitcnt lgkmcnt(0)
	v_mfma_f32_32x32x16_bf16 v[80:95], v[6:9], v[156:159], v[80:95]

; template <int MODE> __device__ __forceinline__ int pop_tile(unsigned& tiles) { int j; if (MODE == 2) { j = 31 - __builtin_clz(tiles); tiles &= ~(1u << j); } else { j = __builtin_ctz(tiles); tiles &= tiles - 1u; } return j; }
; __device__ __forceinline__ void nsa_unit(int b, int g, int tq, const Args& a, LAS unsigned char* lds, int tid, int wave, int lane, int& nxt) {
;     ...
;             for (;;) {
;                 const int j2 = ut ? pop_tile<1>(ut) : -1;
;                 NL_DMA(1, (j2 >= 0 ? j2 : j0), o2);
;                 NL_STEP(1, selbits);
.LBB0_975:
	s_sub_i32 s10, 28, s67
	v_sub_co_u32_e64 v0, s[6:7], s0, 1
	s_ff1_i32_b32 s11, s0
	s_and_b64 s[4:5], s[6:7], exec
	s_cselect_b32 s4, s44, s11
	s_ashr_i32 s5, s4, 31
	s_lshl_b64 s[4:5], s[4:5], 14
	v_lshl_add_u64 v[2:3], v[160:161], 0, s[4:5]
	s_add_i32 s8, s50, s94
	s_mov_b32 m0, s8
	s_nop 0
	global_load_lds_dwordx4 v[2:3], off
	v_lshl_add_u64 v[2:3], v[162:163], 0, s[4:5]
	s_add_i32 s4, s50, s95
	s_mov_b32 m0, s4
	s_nop 0
	global_load_lds_dwordx4 v[2:3], off
	v_readfirstlane_b32 s12, v0
	v_bfe_u32 v0, v164, s44, 1
	s_cmp_gt_i32 s44, s10
	v_cmp_eq_u32_e64 s[4:5], 0, v0
	s_mov_b64 s[8:9], -1
	s_cbranch_scc1 .LBB0_977
	s_add_i32 s8, s1, 0
	v_add_u32_e32 v0, s8, v183
	ds_read_b128 v[2:5], v0
	ds_read_b128 v[6:9], v0 offset:4096
	v_cndmask_b32_e64 v80, v185, v173, s[4:5]
	v_mov_b32_e32 v81, v80
	v_mov_b32_e32 v82, v80
	v_mov_b32_e32 v83, v80
	v_mov_b32_e32 v84, v80
	v_mov_b32_e32 v85, v80
	v_mov_b32_e32 v86, v80
	v_mov_b32_e32 v87, v80
	v_mov_b32_e32 v88, v80
	v_mov_b32_e32 v89, v80
	v_mov_b32_e32 v90, v80
	v_mov_b32_e32 v91, v80
	v_mov_b32_e32 v92, v80
	v_mov_b32_e32 v93, v80
	v_mov_b32_e32 v94, v80
	v_mov_b32_e32 v95, v80
	v_add_u32_e32 v0, s8, v184
	s_waitcnt lgkmcnt(1)
	v_mfma_f32_32x32x16_bf16 v[96:111], v[2:5], v[144:147], v[80:95]
	s_waitcnt lgkmcnt(0)
	v_mfma_f32_32x32x16_bf16 v[80:95], v[6:9], v[144:147], v[80:95]
	ds_read_b128 v[2:5], v0
	ds_read_b128 v[6:9], v0 offset:4096
	v_add_u32_e32 v0, s8, v186
	s_waitcnt lgkmcnt(1)
	v_mfma_f32_32x32x16_bf16 v[96:111], v[2:5], v[148:151], v[96:111]
	s_waitcnt lgkmcnt(0)
	v_mfma_f32_32x32x16_bf16 v[80:95], v[6:9], v[148:151], v[80:95]
	ds_read_b128 v[2:5], v0
	ds_read_b128 v[6:9], v0 offset:4096
	v_add_u32_e32 v0, s8, v187
	s_mov_b64 s[8:9], 0
	s_waitcnt lgkmcnt(1)
	v_mfma_f32_32x32x16_bf16 v[96:111], v[2:5], v[152:155], v[96:111]
	s_waitcnt lgkmcnt(0)
	v_mfma_f32_32x32x16_bf16 v[80:95], v[6:9], v[152:155], v[80:95]
	ds_read_b128 v[2:5], v0
	ds_read_b128 v[6:9], v0 offset:4096
	s_waitcnt lgkmcnt(1)
	v_mfma_f32_32x32x16_bf16 v[96:111], v[2:5], v[156:159], v[96:111]
	s_waitcnt lgkmcnt(0)
	v_mfma_f32_32x32x16_bf16 v[80:95], v[6:9], v[156:159], v[80:95]

; template <int MODE> __device__ __forceinline__ int pop_tile(unsigned& tiles) { int j; if (MODE == 2) { j = 31 - __builtin_clz(tiles); tiles &= ~(1u << j); } else { j = __builtin_ctz(tiles); tiles &= tiles - 1u; } return j; }
; __device__ __forceinline__ void nsa_unit(int b, int g, int tq, const Args& a, LAS unsigned char* lds, int tid, int wave, int lane, int& nxt) {
;     ...
;             for (;;) {
;                 const int j2 = ut ? pop_tile<1>(ut) : -1;
;                 NL_DMA(1, (j2 >= 0 ? j2 : j0), o2);
;                 NL_STEP(1, selbits);
.LBB0_981:
	v_sub_co_u32_e64 v2, s[6:7], s0, 1
	s_mov_b32 s11, s4
	s_mov_b32 s12, s50
	s_mov_b32 s50, s1
	s_ff1_i32_b32 s1, s0
	s_and_b64 s[4:5], s[6:7], exec
	s_cselect_b32 s44, s97, s1
	s_lshl_b64 s[4:5], s[44:45], 14
	v_readfirstlane_b32 s13, v2
	v_lshl_add_u64 v[2:3], v[160:161], 0, s[4:5]
	s_add_i32 s8, s50, s94
	s_mov_b32 m0, s8
	s_nop 0
	global_load_lds_dwordx4 v[2:3], off
	v_lshl_add_u64 v[2:3], v[162:163], 0, s[4:5]
	s_add_i32 s4, s50, s95
	s_mov_b32 m0, s4
	s_nop 0
	global_load_lds_dwordx4 v[2:3], off
	v_bfe_u32 v2, v164, s97, 1
	s_cmp_gt_i32 s97, s10
	v_cmp_eq_u32_e64 s[4:5], 0, v2
	s_mov_b64 s[8:9], -1
	s_cbranch_scc1 .LBB0_983
	s_add_i32 s8, s51, 0
	v_sub_f32_e32 v2, v185, v0
	v_add_u32_e32 v6, s8, v183
	v_cndmask_b32_e64 v112, v2, v173, s[4:5]
	ds_read_b128 v[2:5], v6
	ds_read_b128 v[6:9], v6 offset:4096
	v_mov_b32_e32 v113, v112
	v_mov_b32_e32 v114, v112
	v_mov_b32_e32 v115, v112
	v_mov_b32_e32 v116, v112
	v_mov_b32_e32 v117, v112
	v_mov_b32_e32 v118, v112
	v_mov_b32_e32 v119, v112
	v_mov_b32_e32 v120, v112
	v_mov_b32_e32 v121, v112
	v_mov_b32_e32 v122, v112
	v_mov_b32_e32 v123, v112
	v_mov_b32_e32 v124, v112
	v_mov_b32_e32 v125, v112
	v_mov_b32_e32 v126, v112
	v_mov_b32_e32 v127, v112
	s_waitcnt lgkmcnt(1)
	s_nop 0
	v_mfma_f32_32x32x16_bf16 v[128:143], v[2:5], v[144:147], v[112:127]
	s_waitcnt lgkmcnt(0)
	v_mfma_f32_32x32x16_bf16 v[112:127], v[6:9], v[144:147], v[112:127]
	v_add_u32_e32 v6, s8, v184
	ds_read_b128 v[2:5], v6
	ds_read_b128 v[6:9], v6 offset:4096
	s_waitcnt lgkmcnt(1)
	v_mfma_f32_32x32x16_bf16 v[128:143], v[2:5], v[148:151], v[128:143]
	s_waitcnt lgkmcnt(0)
	v_mfma_f32_32x32x16_bf16 v[112:127], v[6:9], v[148:151], v[112:127]
	v_add_u32_e32 v6, s8, v186
	ds_read_b128 v[2:5], v6
	ds_read_b128 v[6:9], v6 offset:4096
	s_waitcnt lgkmcnt(1)
	v_mfma_f32_32x32x16_bf16 v[128:143], v[2:5], v[152:155], v[128:143]
	s_waitcnt lgkmcnt(0)
	v_mfma_f32_32x32x16_bf16 v[112:127], v[6:9], v[152:155], v[112:127]
	v_add_u32_e32 v6, s8, v187
	ds_read_b128 v[2:5], v6
	ds_read_b128 v[6:9], v6 offset:4096
	s_mov_b64 s[8:9], 0
	s_waitcnt lgkmcnt(1)
	v_mfma_f32_32x32x16_bf16 v[128:143], v[2:5], v[156:159], v[128:143]
	s_waitcnt lgkmcnt(0)
	v_mfma_f32_32x32x16_bf16 v[112:127], v[6:9], v[156:159], v[112:127]

; #define PG8_STAGE(bufoff, gbase, voff) do { _Pragma("unroll") for (int _i = 0; _i < 2; ++_i) \
;         __builtin_amdgcn_global_load_lds((const unsigned*)((const char*)(gbase) + (voff)[_i]), (PG8_LAS unsigned*)(lds + (bufoff) + ldsw + _i * 8192), 16, 0, 0); } while (0)
; #define PG8_LDA(dst, b, h) do { _Pragma("unroll") for (int m = 0; m < 4; ++m) _Pragma("unroll") for (int k = 0; k < 2; ++k) dst[m][k] = *(const PG8_LAS bf16x8*)(lds + PG8_SA(b, h) + aoff + m * 2048 + k * 1024); } while (0)
; #define PG8_LDB(dst, b, h) do { _Pragma("unroll") for (int n = 0; n < 2; ++n) _Pragma("unroll") for (int k = 0; k < 2; ++k) dst[n][k] = *(const PG8_LAS bf16x8*)(lds + PG8_SB(b, h) + boff + n * 2048 + k * 1024); } while (0)
; #define PG8_MMA(ai, bj, At, Bt) do { __builtin_amdgcn_s_setprio(1); _Pragma("unroll") for (int m = 0; m < 4; ++m) _Pragma("unroll") for (int n = 0; n < 2; ++n) _Pragma("unroll") for (int k = 0; k < 2; ++k) \
;         acc[ai][bj][m][n] = __builtin_amdgcn_mfma_f32_16x16x32_bf16(Bt[n][k], At[m][k], acc[ai][bj][m][n], 0, 0, 0); __builtin_amdgcn_s_setprio(0); } while (0)
; #define PG8_WAIT_V(n) asm volatile("s_waitcnt vmcnt(" #n ")" ::: "memory")
; #define PG8_WAIT_L(n) asm volatile("s_waitcnt lgkmcnt(" #n ")" ::: "memory")
; template <class Epi, class Sched, bool ALIGN_EPI = false, bool SP2 = false>
; __device__ __forceinline__ void gemm_phase(PG8_LAS unsigned char* lds, const Gemm g, const Sched& S, const Epi& E, int tid_in) {
;     ...
;             const bool last = (t == nt - 2);
;             const char* a1 = cA + (size_t)(t + 1) * kstep;
;             const char* a2 = last ? nA : cA + (size_t)(t + 2) * kstep; const char* b2 = last ? nB : cB + (size_t)(t + 2) * kstep;
;             const char* a3 = a2 + kstep; const char* b3 = b2 + kstep;
;             if (last && has_next) S.a_ready(nxt);
;             if constexpr (SP2) {
;             PG8_LDB(B0, 0, 0); PG8_LDB(B1, 0, 1); PG8_SCHED; PG8_LDA(At, 0, 0); PG8_STAGE(PG8_SA(1, 1), a1 + hstep, voffA);
;             PG8_WAIT_V(8); PG8_WAIT_L(0); PG8_BAR; PG8_MMA(0, 0, At, B0); PG8_MMA(0, 1, At, B1); PG8_BAR; PG8_SCHED;
;             PG8_LDA(At, 0, 1); PG8_STAGE(PG8_SB(0, 0), b2, voffB); PG8_STAGE(PG8_SB(0, 1), b2 + hstep, voffB); PG8_STAGE(PG8_SA(0, 0), a2, voffA);
;             PG8_WAIT_V(8); PG8_WAIT_L(0); PG8_BAR; PG8_MMA(1, 0, At, B0); PG8_MMA(1, 1, At, B1); PG8_BAR; PG8_SCHED;
.LBB0_1062:
	s_add_u32 s0, s44, s46
	s_addc_u32 s1, s45, s47
	s_add_u32 s0, s0, 0x100
	s_addc_u32 s1, s1, 0
	s_add_u32 s48, s78, s46
	s_addc_u32 s49, s79, s47
	s_add_i32 s81, 0, 0x10000
	v_add_u32_e32 v1, s81, v214
	ds_read_b128 v[132:135], v1
	ds_read_b128 v[136:139], v1 offset:1024
	ds_read_b128 v[140:143], v1 offset:2048
	ds_read_b128 v[144:147], v1 offset:3072
	v_add_u32_e32 v1, s74, v214
	ds_read_b128 v[148:151], v1
	ds_read_b128 v[152:155], v1 offset:1024
	ds_read_b128 v[156:159], v1 offset:2048
	ds_read_b128 v[160:163], v1 offset:3072
	s_cmpk_eq_i32 s46, 0x700
	s_cselect_b32 s51, s35, s1
	s_cselect_b32 s50, s67, s0
	s_cselect_b32 s49, s75, s49
	s_cselect_b32 s48, s76, s48
	v_lshl_add_u64 v[2:3], v[208:209], 0, s[46:47]
	s_add_i32 m0, s58, 0xc000
	ds_read_b128 v[164:167], v216
	ds_read_b128 v[168:171], v216 offset:1024
	ds_read_b128 v[172:175], v216 offset:2048
	ds_read_b128 v[176:179], v216 offset:3072
	ds_read_b128 v[180:183], v216 offset:4096
	ds_read_b128 v[184:187], v216 offset:5120
	ds_read_b128 v[218:221], v216 offset:6144
	ds_read_b128 v[222:225], v216 offset:7168
	global_load_lds_dwordx4 v[2:3], off
	v_lshl_add_u64 v[2:3], v[210:211], 0, s[46:47]
	s_add_i32 m0, s58, 0xe000
	s_nop 0
	global_load_lds_dwordx4 v[2:3], off
	s_waitcnt vmcnt(8)
	s_waitcnt lgkmcnt(0)
	s_barrier
	s_setprio 1
	v_mfma_f32_16x16x32_bf16 v[128:131], v[132:135], v[164:167], v[128:131]
	v_mfma_f32_16x16x32_bf16 v[124:127], v[140:143], v[164:167], v[124:127]
	v_mfma_f32_16x16x32_bf16 v[112:115], v[132:135], v[172:175], v[112:115]
	v_mfma_f32_16x16x32_bf16 v[108:111], v[140:143], v[172:175], v[108:111]
	v_mfma_f32_16x16x32_bf16 v[96:99], v[132:135], v[180:183], v[96:99]
	v_mfma_f32_16x16x32_bf16 v[92:95], v[140:143], v[180:183], v[92:95]
	v_mfma_f32_16x16x32_bf16 v[80:83], v[132:135], v[218:221], v[80:83]
	v_mfma_f32_16x16x32_bf16 v[76:79], v[140:143], v[218:221], v[76:79]
	v_mfma_f32_16x16x32_bf16 v[128:131], v[136:139], v[168:171], v[128:131]
	v_mfma_f32_16x16x32_bf16 v[124:127], v[144:147], v[168:171], v[124:127]
	v_mfma_f32_16x16x32_bf16 v[112:115], v[136:139], v[176:179], v[112:115]
	v_mfma_f32_16x16x32_bf16 v[108:111], v[144:147], v[176:179], v[108:111]
	v_mfma_f32_16x16x32_bf16 v[96:99], v[136:139], v[184:187], v[96:99]
	v_mfma_f32_16x16x32_bf16 v[92:95], v[144:147], v[184:187], v[92:95]
	v_mfma_f32_16x16x32_bf16 v[80:83], v[136:139], v[222:225], v[80:83]
	v_mfma_f32_16x16x32_bf16 v[76:79], v[144:147], v[222:225], v[76:79]
	s_setprio 0
	s_setprio 1
	v_mfma_f32_16x16x32_bf16 v[120:123], v[148:151], v[164:167], v[120:123]
	v_mfma_f32_16x16x32_bf16 v[116:119], v[156:159], v[164:167], v[116:119]
	v_mfma_f32_16x16x32_bf16 v[104:107], v[148:151], v[172:175], v[104:107]
	v_mfma_f32_16x16x32_bf16 v[100:103], v[156:159], v[172:175], v[100:103]
	v_mfma_f32_16x16x32_bf16 v[88:91], v[148:151], v[180:183], v[88:91]
	v_mfma_f32_16x16x32_bf16 v[84:87], v[156:159], v[180:183], v[84:87]
	v_mfma_f32_16x16x32_bf16 v[72:75], v[148:151], v[218:221], v[72:75]
	v_mfma_f32_16x16x32_bf16 v[68:71], v[156:159], v[218:221], v[68:71]
	v_mfma_f32_16x16x32_bf16 v[120:123], v[152:155], v[168:171], v[120:123]
	v_mfma_f32_16x16x32_bf16 v[116:119], v[160:163], v[168:171], v[116:119]
	v_mfma_f32_16x16x32_bf16 v[104:107], v[152:155], v[176:179], v[104:107]
	v_mfma_f32_16x16x32_bf16 v[100:103], v[160:163], v[176:179], v[100:103]
	v_mfma_f32_16x16x32_bf16 v[88:91], v[152:155], v[184:187], v[88:91]
	v_mfma_f32_16x16x32_bf16 v[84:87], v[160:163], v[184:187], v[84:87]
	v_mfma_f32_16x16x32_bf16 v[72:75], v[152:155], v[222:225], v[72:75]
	v_mfma_f32_16x16x32_bf16 v[68:71], v[160:163], v[222:225], v[68:71]
	s_setprio 0
	s_barrier
	s_add_i32 s0, s81, s57
	v_lshl_add_u64 v[226:227], s[48:49], 0, v[190:191]
	s_mov_b32 m0, s0
	ds_read_b128 v[164:167], v216 offset:16384
	ds_read_b128 v[168:171], v216 offset:17408
	ds_read_b128 v[172:175], v216 offset:18432
	ds_read_b128 v[176:179], v216 offset:19456
	ds_read_b128 v[180:183], v216 offset:20480
	ds_read_b128 v[184:187], v216 offset:21504
	ds_read_b128 v[218:221], v216 offset:22528
	ds_read_b128 v[222:225], v216 offset:23552
	global_load_lds_dwordx4 v[226:227], off
	s_add_i32 m0, s0, 0x2000
	s_add_u32 s0, s48, 0x40000
	v_lshl_add_u64 v[228:229], s[48:49], 0, v[194:195]
	s_addc_u32 s1, s49, 0
	s_add_i32 s81, s74, s57
	global_load_lds_dwordx4 v[228:229], off
	v_lshl_add_u64 v[2:3], s[0:1], 0, v[190:191]
	s_mov_b32 m0, s81
	v_lshl_add_u64 v[232:233], s[50:51], 0, v[188:189]
	global_load_lds_dwordx4 v[2:3], off
	v_lshl_add_u64 v[2:3], s[0:1], 0, v[194:195]
	s_add_i32 m0, s81, 0x2000
	v_lshl_add_u64 v[234:235], s[50:51], 0, v[192:193]
	global_load_lds_dwordx4 v[2:3], off
	s_mov_b32 m0, s58
	s_nop 0
	global_load_lds_dwordx4 v[232:233], off
	s_mov_b32 m0, s59
	s_nop 0
	global_load_lds_dwordx4 v[234:235], off
	s_waitcnt vmcnt(8)
	s_waitcnt lgkmcnt(0)
	s_barrier
; #define PG8_STAGE(bufoff, gbase, voff) do { _Pragma("unroll") for (int _i = 0; _i < 2; ++_i) \
;         __builtin_amdgcn_global_load_lds((const unsigned*)((const char*)(gbase) + (voff)[_i]), (PG8_LAS unsigned*)(lds + (bufoff) + ldsw + _i * 8192), 16, 0, 0); } while (0)
; #define PG8_LDA(dst, b, h) do { _Pragma("unroll") for (int m = 0; m < 4; ++m) _Pragma("unroll") for (int k = 0; k < 2; ++k) dst[m][k] = *(const PG8_LAS bf16x8*)(lds + PG8_SA(b, h) + aoff + m * 2048 + k * 1024); } while (0)
; #define PG8_LDB(dst, b, h) do { _Pragma("unroll") for (int n = 0; n < 2; ++n) _Pragma("unroll") for (int k = 0; k < 2; ++k) dst[n][k] = *(const PG8_LAS bf16x8*)(lds + PG8_SB(b, h) + boff + n * 2048 + k * 1024); } while (0)
; #define PG8_MMA(ai, bj, At, Bt) do { __builtin_amdgcn_s_setprio(1); _Pragma("unroll") for (int m = 0; m < 4; ++m) _Pragma("unroll") for (int n = 0; n < 2; ++n) _Pragma("unroll") for (int k = 0; k < 2; ++k) \
;         acc[ai][bj][m][n] = __builtin_amdgcn_mfma_f32_16x16x32_bf16(Bt[n][k], At[m][k], acc[ai][bj][m][n], 0, 0, 0); __builtin_amdgcn_s_setprio(0); } while (0)
; #define PG8_WAIT_V(n) asm volatile("s_waitcnt vmcnt(" #n ")" ::: "memory")
; #define PG8_WAIT_L(n) asm volatile("s_waitcnt lgkmcnt(" #n ")" ::: "memory")
; #define PG8_BAR __builtin_amdgcn_s_barrier()
; #define PG8_SCHED __builtin_amdgcn_sched_barrier(0)
; template <class Epi, class Sched, bool ALIGN_EPI = false, bool SP2 = false>
; __device__ __forceinline__ void gemm_phase(PG8_LAS unsigned char* lds, const Gemm g, const Sched& S, const Epi& E, int tid_in) {
;     ...
;             PG8_WAIT_V(8); PG8_WAIT_L(0); PG8_BAR; PG8_MMA(1, 0, At, B0); PG8_MMA(1, 1, At, B1); PG8_BAR; PG8_SCHED;
;             PG8_LDB(B0, 1, 0); PG8_LDB(B1, 1, 1); PG8_SCHED; PG8_LDA(At, 1, 0); PG8_STAGE(PG8_SA(0, 1), a2 + hstep, voffA);
;             PG8_WAIT_V(8); PG8_WAIT_L(0); PG8_BAR; PG8_MMA(0, 0, At, B0); PG8_MMA(0, 1, At, B1); PG8_BAR; PG8_SCHED;
;             PG8_LDA(At, 1, 1); PG8_STAGE(PG8_SB(1, 0), b3, voffB); PG8_STAGE(PG8_SB(1, 1), b3 + hstep, voffB); PG8_STAGE(PG8_SA(1, 0), a3, voffA);
	s_setprio 1
	v_mfma_f32_16x16x32_bf16 v[64:67], v[132:135], v[164:167], v[64:67]
	v_mfma_f32_16x16x32_bf16 v[60:63], v[140:143], v[164:167], v[60:63]
	v_mfma_f32_16x16x32_bf16 v[48:51], v[132:135], v[172:175], v[48:51]
	v_mfma_f32_16x16x32_bf16 v[44:47], v[140:143], v[172:175], v[44:47]
	v_mfma_f32_16x16x32_bf16 v[32:35], v[132:135], v[180:183], v[32:35]
	v_mfma_f32_16x16x32_bf16 v[28:31], v[140:143], v[180:183], v[28:31]
	v_mfma_f32_16x16x32_bf16 v[16:19], v[132:135], v[218:221], v[16:19]
	v_mfma_f32_16x16x32_bf16 v[12:15], v[140:143], v[218:221], v[12:15]
	v_mfma_f32_16x16x32_bf16 v[64:67], v[136:139], v[168:171], v[64:67]
	v_mfma_f32_16x16x32_bf16 v[60:63], v[144:147], v[168:171], v[60:63]
	v_mfma_f32_16x16x32_bf16 v[48:51], v[136:139], v[176:179], v[48:51]
	v_mfma_f32_16x16x32_bf16 v[44:47], v[144:147], v[176:179], v[44:47]
	v_mfma_f32_16x16x32_bf16 v[32:35], v[136:139], v[184:187], v[32:35]
	v_mfma_f32_16x16x32_bf16 v[28:31], v[144:147], v[184:187], v[28:31]
	v_mfma_f32_16x16x32_bf16 v[16:19], v[136:139], v[222:225], v[16:19]
	v_mfma_f32_16x16x32_bf16 v[12:15], v[144:147], v[222:225], v[12:15]
	s_setprio 0
	s_setprio 1
	v_mfma_f32_16x16x32_bf16 v[56:59], v[148:151], v[164:167], v[56:59]
	v_mfma_f32_16x16x32_bf16 v[52:55], v[156:159], v[164:167], v[52:55]
	v_mfma_f32_16x16x32_bf16 v[40:43], v[148:151], v[172:175], v[40:43]
	v_mfma_f32_16x16x32_bf16 v[36:39], v[156:159], v[172:175], v[36:39]
	v_mfma_f32_16x16x32_bf16 v[24:27], v[148:151], v[180:183], v[24:27]
	v_mfma_f32_16x16x32_bf16 v[20:23], v[156:159], v[180:183], v[20:23]
	v_mfma_f32_16x16x32_bf16 v[8:11], v[148:151], v[218:221], v[8:11]
	v_mfma_f32_16x16x32_bf16 v[2:5], v[156:159], v[218:221], v[4:7]
	v_mfma_f32_16x16x32_bf16 v[56:59], v[152:155], v[168:171], v[56:59]
	v_mfma_f32_16x16x32_bf16 v[52:55], v[160:163], v[168:171], v[52:55]
	v_mfma_f32_16x16x32_bf16 v[40:43], v[152:155], v[176:179], v[40:43]
	v_mfma_f32_16x16x32_bf16 v[36:39], v[160:163], v[176:179], v[36:39]
	v_mfma_f32_16x16x32_bf16 v[24:27], v[152:155], v[184:187], v[24:27]
	v_mfma_f32_16x16x32_bf16 v[20:23], v[160:163], v[184:187], v[20:23]
	v_mfma_f32_16x16x32_bf16 v[8:11], v[152:155], v[222:225], v[8:11]
	v_mfma_f32_16x16x32_bf16 v[2:5], v[160:163], v[222:225], v[2:5]
	s_setprio 0
	s_barrier
	s_add_i32 s81, 0, 0x18000
	v_add_u32_e32 v1, s81, v214
	s_add_i32 s82, 0, 0x1c000
	ds_read_b128 v[132:135], v1
	ds_read_b128 v[136:139], v1 offset:1024
	ds_read_b128 v[140:143], v1 offset:2048
	ds_read_b128 v[144:147], v1 offset:3072
	v_add_u32_e32 v1, s82, v214
	ds_read_b128 v[148:151], v1
	ds_read_b128 v[152:155], v1 offset:1024
	ds_read_b128 v[156:159], v1 offset:2048
	ds_read_b128 v[160:163], v1 offset:3072
	s_add_u32 s0, s50, 0x40000
	s_addc_u32 s1, s51, 0
	s_mov_b32 m0, s60
	v_lshl_add_u64 v[6:7], s[0:1], 0, v[188:189]
	ds_read_b128 v[164:167], v216 offset:32768
	ds_read_b128 v[168:171], v216 offset:33792
	ds_read_b128 v[172:175], v216 offset:34816
	ds_read_b128 v[176:179], v216 offset:35840
	ds_read_b128 v[180:183], v216 offset:36864
	ds_read_b128 v[184:187], v216 offset:37888
	ds_read_b128 v[218:221], v216 offset:38912
	ds_read_b128 v[222:225], v216 offset:39936
	global_load_lds_dwordx4 v[6:7], off
	v_lshl_add_u64 v[6:7], s[0:1], 0, v[192:193]
	s_mov_b32 m0, s61
	s_nop 0
	global_load_lds_dwordx4 v[6:7], off
	s_waitcnt vmcnt(8)
	s_waitcnt lgkmcnt(0)
	s_barrier
	s_setprio 1
	v_mfma_f32_16x16x32_bf16 v[128:131], v[132:135], v[164:167], v[128:131]
	v_mfma_f32_16x16x32_bf16 v[124:127], v[140:143], v[164:167], v[124:127]
	v_mfma_f32_16x16x32_bf16 v[112:115], v[132:135], v[172:175], v[112:115]
	v_mfma_f32_16x16x32_bf16 v[108:111], v[140:143], v[172:175], v[108:111]
	v_mfma_f32_16x16x32_bf16 v[96:99], v[132:135], v[180:183], v[96:99]
	v_mfma_f32_16x16x32_bf16 v[92:95], v[140:143], v[180:183], v[92:95]
	v_mfma_f32_16x16x32_bf16 v[80:83], v[132:135], v[218:221], v[80:83]
	v_mfma_f32_16x16x32_bf16 v[76:79], v[140:143], v[218:221], v[76:79]
	v_mfma_f32_16x16x32_bf16 v[128:131], v[136:139], v[168:171], v[128:131]
	v_mfma_f32_16x16x32_bf16 v[124:127], v[144:147], v[168:171], v[124:127]
	v_mfma_f32_16x16x32_bf16 v[112:115], v[136:139], v[176:179], v[112:115]
	v_mfma_f32_16x16x32_bf16 v[108:111], v[144:147], v[176:179], v[108:111]
	v_mfma_f32_16x16x32_bf16 v[96:99], v[136:139], v[184:187], v[96:99]
	v_mfma_f32_16x16x32_bf16 v[92:95], v[144:147], v[184:187], v[92:95]
	v_mfma_f32_16x16x32_bf16 v[80:83], v[136:139], v[222:225], v[80:83]
	v_mfma_f32_16x16x32_bf16 v[76:79], v[144:147], v[222:225], v[76:79]
	s_setprio 0
	s_setprio 1
	v_mfma_f32_16x16x32_bf16 v[120:123], v[148:151], v[164:167], v[120:123]
	v_mfma_f32_16x16x32_bf16 v[116:119], v[156:159], v[164:167], v[116:119]
	v_mfma_f32_16x16x32_bf16 v[104:107], v[148:151], v[172:175], v[104:107]
	v_mfma_f32_16x16x32_bf16 v[100:103], v[156:159], v[172:175], v[100:103]
	v_mfma_f32_16x16x32_bf16 v[88:91], v[148:151], v[180:183], v[88:91]
	v_mfma_f32_16x16x32_bf16 v[84:87], v[156:159], v[180:183], v[84:87]
	v_mfma_f32_16x16x32_bf16 v[72:75], v[148:151], v[218:221], v[72:75]
	v_mfma_f32_16x16x32_bf16 v[68:71], v[156:159], v[218:221], v[68:71]
	v_mfma_f32_16x16x32_bf16 v[120:123], v[152:155], v[168:171], v[120:123]
	v_mfma_f32_16x16x32_bf16 v[116:119], v[160:163], v[168:171], v[116:119]
	v_mfma_f32_16x16x32_bf16 v[104:107], v[152:155], v[176:179], v[104:107]
	v_mfma_f32_16x16x32_bf16 v[100:103], v[160:163], v[176:179], v[100:103]
	v_mfma_f32_16x16x32_bf16 v[88:91], v[152:155], v[184:187], v[88:91]
	v_mfma_f32_16x16x32_bf16 v[84:87], v[160:163], v[184:187], v[84:87]
	v_mfma_f32_16x16x32_bf16 v[72:75], v[152:155], v[222:225], v[72:75]
	v_mfma_f32_16x16x32_bf16 v[68:71], v[160:163], v[222:225], v[68:71]
	s_setprio 0
	s_barrier
; #define PG8_STAGE(bufoff, gbase, voff) do { _Pragma("unroll") for (int _i = 0; _i < 2; ++_i) \
;         __builtin_amdgcn_global_load_lds((const unsigned*)((const char*)(gbase) + (voff)[_i]), (PG8_LAS unsigned*)(lds + (bufoff) + ldsw + _i * 8192), 16, 0, 0); } while (0)
; #define PG8_LDA(dst, b, h) do { _Pragma("unroll") for (int m = 0; m < 4; ++m) _Pragma("unroll") for (int k = 0; k < 2; ++k) dst[m][k] = *(const PG8_LAS bf16x8*)(lds + PG8_SA(b, h) + aoff + m * 2048 + k * 1024); } while (0)
; #define PG8_MMA(ai, bj, At, Bt) do { __builtin_amdgcn_s_setprio(1); _Pragma("unroll") for (int m = 0; m < 4; ++m) _Pragma("unroll") for (int n = 0; n < 2; ++n) _Pragma("unroll") for (int k = 0; k < 2; ++k) \
;         acc[ai][bj][m][n] = __builtin_amdgcn_mfma_f32_16x16x32_bf16(Bt[n][k], At[m][k], acc[ai][bj][m][n], 0, 0, 0); __builtin_amdgcn_s_setprio(0); } while (0)
; #define PG8_WAIT_V(n) asm volatile("s_waitcnt vmcnt(" #n ")" ::: "memory")
; #define PG8_WAIT_L(n) asm volatile("s_waitcnt lgkmcnt(" #n ")" ::: "memory")
; #define PG8_BAR __builtin_amdgcn_s_barrier()
; #define PG8_SCHED __builtin_amdgcn_sched_barrier(0)
; template <class Epi, class Sched, bool ALIGN_EPI = false, bool SP2 = false>
; __device__ __forceinline__ void gemm_phase(PG8_LAS unsigned char* lds, const Gemm g, const Sched& S, const Epi& E, int tid_in) {
;     ...
;             PG8_LDA(At, 1, 1); PG8_STAGE(PG8_SB(1, 0), b3, voffB); PG8_STAGE(PG8_SB(1, 1), b3 + hstep, voffB); PG8_STAGE(PG8_SA(1, 0), a3, voffA);
;             PG8_WAIT_V(8); PG8_WAIT_L(0); PG8_BAR; PG8_MMA(1, 0, At, B0); PG8_MMA(1, 1, At, B1); PG8_BAR; PG8_SCHED;
	s_add_i32 s0, s81, s57
	v_lshl_add_u64 v[6:7], v[226:227], 0, s[12:13]
	s_mov_b32 m0, s0
	ds_read_b128 v[164:167], v216 offset:49152
	ds_read_b128 v[168:171], v216 offset:50176
	ds_read_b128 v[172:175], v216 offset:51200
	ds_read_b128 v[176:179], v216 offset:52224
	ds_read_b128 v[180:183], v216 offset:53248
	ds_read_b128 v[184:187], v216 offset:54272
	ds_read_b128 v[218:221], v216 offset:55296
	ds_read_b128 v[222:225], v216 offset:56320
	global_load_lds_dwordx4 v[6:7], off
	s_add_i32 m0, s0, 0x2000
	s_add_u32 s0, s48, 0x40080
	v_lshl_add_u64 v[6:7], v[228:229], 0, s[12:13]
	s_addc_u32 s1, s49, 0
	s_add_i32 s48, s82, s57
	global_load_lds_dwordx4 v[6:7], off
	v_lshl_add_u64 v[6:7], s[0:1], 0, v[190:191]
	s_mov_b32 m0, s48
	s_nop 0
	global_load_lds_dwordx4 v[6:7], off
	v_lshl_add_u64 v[6:7], s[0:1], 0, v[194:195]
	s_add_i32 m0, s48, 0x2000
	s_nop 0
	global_load_lds_dwordx4 v[6:7], off
	v_lshl_add_u64 v[6:7], v[232:233], 0, s[12:13]
	s_mov_b32 m0, s64
	s_nop 0
	global_load_lds_dwordx4 v[6:7], off
	v_lshl_add_u64 v[6:7], v[234:235], 0, s[12:13]
	s_mov_b32 m0, s65
	s_nop 0
	global_load_lds_dwordx4 v[6:7], off
	s_waitcnt vmcnt(8)
	s_waitcnt lgkmcnt(0)
	s_barrier
	s_setprio 1
	v_mfma_f32_16x16x32_bf16 v[64:67], v[132:135], v[164:167], v[64:67]
	v_mfma_f32_16x16x32_bf16 v[60:63], v[140:143], v[164:167], v[60:63]
	v_mfma_f32_16x16x32_bf16 v[48:51], v[132:135], v[172:175], v[48:51]
	v_mfma_f32_16x16x32_bf16 v[44:47], v[140:143], v[172:175], v[44:47]
	v_mfma_f32_16x16x32_bf16 v[32:35], v[132:135], v[180:183], v[32:35]
	v_mfma_f32_16x16x32_bf16 v[28:31], v[140:143], v[180:183], v[28:31]
	v_mfma_f32_16x16x32_bf16 v[16:19], v[132:135], v[218:221], v[16:19]
	v_mfma_f32_16x16x32_bf16 v[12:15], v[140:143], v[218:221], v[12:15]
	v_mfma_f32_16x16x32_bf16 v[64:67], v[136:139], v[168:171], v[64:67]
	v_mfma_f32_16x16x32_bf16 v[60:63], v[144:147], v[168:171], v[60:63]
	v_mfma_f32_16x16x32_bf16 v[48:51], v[136:139], v[176:179], v[48:51]
	v_mfma_f32_16x16x32_bf16 v[44:47], v[144:147], v[176:179], v[44:47]
	v_mfma_f32_16x16x32_bf16 v[32:35], v[136:139], v[184:187], v[32:35]
	v_mfma_f32_16x16x32_bf16 v[28:31], v[144:147], v[184:187], v[28:31]
	v_mfma_f32_16x16x32_bf16 v[16:19], v[136:139], v[222:225], v[16:19]
	v_mfma_f32_16x16x32_bf16 v[12:15], v[144:147], v[222:225], v[12:15]
	s_setprio 0
	s_setprio 1
	v_mfma_f32_16x16x32_bf16 v[56:59], v[148:151], v[164:167], v[56:59]
	v_mfma_f32_16x16x32_bf16 v[52:55], v[156:159], v[164:167], v[52:55]
	v_mfma_f32_16x16x32_bf16 v[40:43], v[148:151], v[172:175], v[40:43]
	v_mfma_f32_16x16x32_bf16 v[36:39], v[156:159], v[172:175], v[36:39]
	v_mfma_f32_16x16x32_bf16 v[24:27], v[148:151], v[180:183], v[24:27]
	v_mfma_f32_16x16x32_bf16 v[20:23], v[156:159], v[180:183], v[20:23]
	v_mfma_f32_16x16x32_bf16 v[6:9], v[148:151], v[218:221], v[8:11]
	v_mfma_f32_16x16x32_bf16 v[2:5], v[156:159], v[218:221], v[2:5]
	v_mfma_f32_16x16x32_bf16 v[56:59], v[152:155], v[168:171], v[56:59]
	v_mfma_f32_16x16x32_bf16 v[52:55], v[160:163], v[168:171], v[52:55]
	v_mfma_f32_16x16x32_bf16 v[40:43], v[152:155], v[176:179], v[40:43]
	v_mfma_f32_16x16x32_bf16 v[36:39], v[160:163], v[176:179], v[36:39]
	v_mfma_f32_16x16x32_bf16 v[24:27], v[152:155], v[184:187], v[24:27]
	v_mfma_f32_16x16x32_bf16 v[20:23], v[160:163], v[184:187], v[20:23]
	v_mfma_f32_16x16x32_bf16 v[8:11], v[152:155], v[222:225], v[6:9]
	v_mfma_f32_16x16x32_bf16 v[4:7], v[160:163], v[222:225], v[2:5]
	s_setprio 0
	s_barrier
	s_add_i32 s80, s80, 2
	s_add_u32 s46, s46, 0x100
	s_addc_u32 s47, s47, 0
	s_cmp_gt_u32 s80, 13
	s_cbranch_scc1 .LBB0_1068

; #define PG8_STAGE(bufoff, gbase, voff) do { _Pragma("unroll") for (int _i = 0; _i < 2; ++_i) \
;         __builtin_amdgcn_global_load_lds((const unsigned*)((const char*)(gbase) + (voff)[_i]), (PG8_LAS unsigned*)(lds + (bufoff) + ldsw + _i * 8192), 16, 0, 0); } while (0)
; #define PG8_LDA(dst, b, h) do { _Pragma("unroll") for (int m = 0; m < 4; ++m) _Pragma("unroll") for (int k = 0; k < 2; ++k) dst[m][k] = *(const PG8_LAS bf16x8*)(lds + PG8_SA(b, h) + aoff + m * 2048 + k * 1024); } while (0)
; #define PG8_LDB(dst, b, h) do { _Pragma("unroll") for (int n = 0; n < 2; ++n) _Pragma("unroll") for (int k = 0; k < 2; ++k) dst[n][k] = *(const PG8_LAS bf16x8*)(lds + PG8_SB(b, h) + boff + n * 2048 + k * 1024); } while (0)
; #define PG8_MMA(ai, bj, At, Bt) do { __builtin_amdgcn_s_setprio(1); _Pragma("unroll") for (int m = 0; m < 4; ++m) _Pragma("unroll") for (int n = 0; n < 2; ++n) _Pragma("unroll") for (int k = 0; k < 2; ++k) \
;         acc[ai][bj][m][n] = __builtin_amdgcn_mfma_f32_16x16x32_bf16(Bt[n][k], At[m][k], acc[ai][bj][m][n], 0, 0, 0); __builtin_amdgcn_s_setprio(0); } while (0)
; #define PG8_WAIT_V(n) asm volatile("s_waitcnt vmcnt(" #n ")" ::: "memory")
; #define PG8_WAIT_L(n) asm volatile("s_waitcnt lgkmcnt(" #n ")" ::: "memory")
; template <class Epi, class Sched, bool ALIGN_EPI = false, bool SP2 = false>
; __device__ __forceinline__ void gemm_phase(PG8_LAS unsigned char* lds, const Gemm g, const Sched& S, const Epi& E, int tid_in) {
;     ...
;             const bool last = (t == nt - 2);
;             const char* a1 = cA + (size_t)(t + 1) * kstep;
;             const char* a2 = last ? nA : cA + (size_t)(t + 2) * kstep; const char* b2 = last ? nB : cB + (size_t)(t + 2) * kstep;
;             const char* a3 = a2 + kstep; const char* b3 = b2 + kstep;
;             if (last && has_next) S.a_ready(nxt);
;             if constexpr (SP2) {
;             PG8_LDB(B0, 0, 0); PG8_LDB(B1, 0, 1); PG8_SCHED; PG8_LDA(At, 0, 0); PG8_STAGE(PG8_SA(1, 1), a1 + hstep, voffA);
;             PG8_WAIT_V(8); PG8_WAIT_L(0); PG8_BAR; PG8_MMA(0, 0, At, B0); PG8_MMA(0, 1, At, B1); PG8_BAR; PG8_SCHED;
;             PG8_LDA(At, 0, 1); PG8_STAGE(PG8_SB(0, 0), b2, voffB); PG8_STAGE(PG8_SB(0, 1), b2 + hstep, voffB); PG8_STAGE(PG8_SA(0, 0), a2, voffA);
;             PG8_WAIT_V(8); PG8_WAIT_L(0); PG8_BAR; PG8_MMA(1, 0, At, B0); PG8_MMA(1, 1, At, B1); PG8_BAR; PG8_SCHED;
.LBB0_1148:
	s_add_u32 s34, s30, 0xfffc0080
	s_addc_u32 s35, s31, -1
	s_cmp_eq_u32 s60, 12
	s_cselect_b32 s37, s23, s35
	s_cselect_b32 s36, s29, s34
	s_cselect_b32 s35, s21, s59
	s_cselect_b32 s34, s57, s58
	s_add_i32 m0, s1, 0xc000
	ds_read_b128 v[128:131], v191
	global_load_lds_dwordx4 v160, s[30:31]
	s_add_i32 m0, s1, 0xe000
	ds_read_b128 v[132:135], v191 offset:1024
	global_load_lds_dwordx4 v162, s[30:31]
	ds_read_b128 v[136:139], v191 offset:2048
	ds_read_b128 v[140:143], v191 offset:3072
	ds_read_b128 v[144:147], v192
	ds_read_b128 v[148:151], v192 offset:1024
	ds_read_b128 v[168:171], v192 offset:2048
	ds_read_b128 v[172:175], v192 offset:3072
	ds_read_b128 v[176:179], v193
	ds_read_b128 v[180:183], v193 offset:1024
	ds_read_b128 v[194:197], v193 offset:2048
	ds_read_b128 v[198:201], v193 offset:3072
	ds_read_b128 v[202:205], v193 offset:4096
	ds_read_b128 v[206:209], v193 offset:5120
	ds_read_b128 v[210:213], v193 offset:6144
	ds_read_b128 v[214:217], v193 offset:7168
	s_waitcnt vmcnt(8)
	s_waitcnt lgkmcnt(0)
	s_barrier
	s_setprio 1
	v_mfma_f32_16x16x32_bf16 v[124:127], v[128:131], v[176:179], v[124:127]
	v_mfma_f32_16x16x32_bf16 v[120:123], v[136:139], v[176:179], v[120:123]
	v_mfma_f32_16x16x32_bf16 v[108:111], v[128:131], v[194:197], v[108:111]
	v_mfma_f32_16x16x32_bf16 v[104:107], v[136:139], v[194:197], v[104:107]
	v_mfma_f32_16x16x32_bf16 v[92:95], v[128:131], v[202:205], v[92:95]
	v_mfma_f32_16x16x32_bf16 v[88:91], v[136:139], v[202:205], v[88:91]
	v_mfma_f32_16x16x32_bf16 v[76:79], v[128:131], v[210:213], v[76:79]
	v_mfma_f32_16x16x32_bf16 v[72:75], v[136:139], v[210:213], v[72:75]
	v_mfma_f32_16x16x32_bf16 v[124:127], v[132:135], v[180:183], v[124:127]
	v_mfma_f32_16x16x32_bf16 v[120:123], v[140:143], v[180:183], v[120:123]
	v_mfma_f32_16x16x32_bf16 v[108:111], v[132:135], v[198:201], v[108:111]
	v_mfma_f32_16x16x32_bf16 v[104:107], v[140:143], v[198:201], v[104:107]
	v_mfma_f32_16x16x32_bf16 v[92:95], v[132:135], v[206:209], v[92:95]
	v_mfma_f32_16x16x32_bf16 v[88:91], v[140:143], v[206:209], v[88:91]
	v_mfma_f32_16x16x32_bf16 v[76:79], v[132:135], v[214:217], v[76:79]
	v_mfma_f32_16x16x32_bf16 v[72:75], v[140:143], v[214:217], v[72:75]
	s_setprio 0
	s_setprio 1
	v_mfma_f32_16x16x32_bf16 v[116:119], v[144:147], v[176:179], v[116:119]
	v_mfma_f32_16x16x32_bf16 v[112:115], v[168:171], v[176:179], v[112:115]
	v_mfma_f32_16x16x32_bf16 v[100:103], v[144:147], v[194:197], v[100:103]
	v_mfma_f32_16x16x32_bf16 v[96:99], v[168:171], v[194:197], v[96:99]
	v_mfma_f32_16x16x32_bf16 v[84:87], v[144:147], v[202:205], v[84:87]
	v_mfma_f32_16x16x32_bf16 v[80:83], v[168:171], v[202:205], v[80:83]
	v_mfma_f32_16x16x32_bf16 v[68:71], v[144:147], v[210:213], v[68:71]
	v_mfma_f32_16x16x32_bf16 v[64:67], v[168:171], v[210:213], v[64:67]
	v_mfma_f32_16x16x32_bf16 v[116:119], v[148:151], v[180:183], v[116:119]
	v_mfma_f32_16x16x32_bf16 v[112:115], v[172:175], v[180:183], v[112:115]
	v_mfma_f32_16x16x32_bf16 v[100:103], v[148:151], v[198:201], v[100:103]
	v_mfma_f32_16x16x32_bf16 v[96:99], v[172:175], v[198:201], v[96:99]
	v_mfma_f32_16x16x32_bf16 v[84:87], v[148:151], v[206:209], v[84:87]
	v_mfma_f32_16x16x32_bf16 v[80:83], v[172:175], v[206:209], v[80:83]
	v_mfma_f32_16x16x32_bf16 v[68:71], v[148:151], v[214:217], v[68:71]
	v_mfma_f32_16x16x32_bf16 v[64:67], v[172:175], v[214:217], v[64:67]
	s_setprio 0
	s_barrier
	s_add_u32 s98, s34, s16
	s_addc_u32 s99, s35, s17
	s_add_u32 s100, s36, s16
	s_addc_u32 s101, s37, s17
	s_add_i32 s61, s54, s0
	s_mov_b32 m0, s61
	ds_read_b128 v[176:179], v193 offset:16384
	global_load_lds_dwordx4 v154, s[34:35]
	s_add_i32 m0, s61, 0x2000
	s_add_u32 s62, s34, 0x40000
	s_addc_u32 s63, s35, 0
	s_add_i32 s61, s55, s0
	global_load_lds_dwordx4 v158, s[34:35]
	s_mov_b32 m0, s61
	ds_read_b128 v[180:183], v193 offset:17408
	global_load_lds_dwordx4 v154, s[62:63]
	s_add_i32 m0, s61, 0x2000
	ds_read_b128 v[194:197], v193 offset:18432
	global_load_lds_dwordx4 v158, s[62:63]
	s_mov_b32 m0, s1
	ds_read_b128 v[198:201], v193 offset:19456
	global_load_lds_dwordx4 v152, s[36:37]
	s_mov_b32 m0, s46
	ds_read_b128 v[202:205], v193 offset:20480
	global_load_lds_dwordx4 v156, s[36:37]
	ds_read_b128 v[206:209], v193 offset:21504
	ds_read_b128 v[210:213], v193 offset:22528
	ds_read_b128 v[214:217], v193 offset:23552
	s_waitcnt vmcnt(8)
	s_waitcnt lgkmcnt(0)
	s_barrier
	s_setprio 1
	v_mfma_f32_16x16x32_bf16 v[60:63], v[128:131], v[176:179], v[60:63]
	v_mfma_f32_16x16x32_bf16 v[56:59], v[136:139], v[176:179], v[56:59]
	v_mfma_f32_16x16x32_bf16 v[44:47], v[128:131], v[194:197], v[44:47]
	v_mfma_f32_16x16x32_bf16 v[40:43], v[136:139], v[194:197], v[40:43]
	v_mfma_f32_16x16x32_bf16 v[28:31], v[128:131], v[202:205], v[28:31]
	v_mfma_f32_16x16x32_bf16 v[24:27], v[136:139], v[202:205], v[24:27]
	v_mfma_f32_16x16x32_bf16 v[12:15], v[128:131], v[210:213], v[12:15]
	v_mfma_f32_16x16x32_bf16 v[8:11], v[136:139], v[210:213], v[8:11]
	v_mfma_f32_16x16x32_bf16 v[60:63], v[132:135], v[180:183], v[60:63]
	v_mfma_f32_16x16x32_bf16 v[56:59], v[140:143], v[180:183], v[56:59]
	v_mfma_f32_16x16x32_bf16 v[44:47], v[132:135], v[198:201], v[44:47]
	v_mfma_f32_16x16x32_bf16 v[40:43], v[140:143], v[198:201], v[40:43]
	v_mfma_f32_16x16x32_bf16 v[28:31], v[132:135], v[206:209], v[28:31]
	v_mfma_f32_16x16x32_bf16 v[24:27], v[140:143], v[206:209], v[24:27]
	v_mfma_f32_16x16x32_bf16 v[12:15], v[132:135], v[214:217], v[12:15]
	v_mfma_f32_16x16x32_bf16 v[8:11], v[140:143], v[214:217], v[8:11]
	s_setprio 0
	s_setprio 1
	v_mfma_f32_16x16x32_bf16 v[52:55], v[144:147], v[176:179], v[52:55]
	v_mfma_f32_16x16x32_bf16 v[48:51], v[168:171], v[176:179], v[48:51]
	v_mfma_f32_16x16x32_bf16 v[36:39], v[144:147], v[194:197], v[36:39]
	v_mfma_f32_16x16x32_bf16 v[32:35], v[168:171], v[194:197], v[32:35]
	v_mfma_f32_16x16x32_bf16 v[20:23], v[144:147], v[202:205], v[20:23]
	v_mfma_f32_16x16x32_bf16 v[16:19], v[168:171], v[202:205], v[16:19]
	v_mfma_f32_16x16x32_bf16 v[4:7], v[144:147], v[210:213], v[4:7]
	v_mfma_f32_16x16x32_bf16 v[0:3], v[168:171], v[210:213], v[0:3]
	v_mfma_f32_16x16x32_bf16 v[52:55], v[148:151], v[180:183], v[52:55]
	v_mfma_f32_16x16x32_bf16 v[48:51], v[172:175], v[180:183], v[48:51]
	v_mfma_f32_16x16x32_bf16 v[36:39], v[148:151], v[198:201], v[36:39]
	v_mfma_f32_16x16x32_bf16 v[32:35], v[172:175], v[198:201], v[32:35]
	v_mfma_f32_16x16x32_bf16 v[20:23], v[148:151], v[206:209], v[20:23]
	v_mfma_f32_16x16x32_bf16 v[16:19], v[172:175], v[206:209], v[16:19]
	v_mfma_f32_16x16x32_bf16 v[4:7], v[148:151], v[214:217], v[4:7]
	v_mfma_f32_16x16x32_bf16 v[0:3], v[172:175], v[214:217], v[0:3]
	s_setprio 0
	s_barrier
; #define PG8_STAGE(bufoff, gbase, voff) do { _Pragma("unroll") for (int _i = 0; _i < 2; ++_i) \
;         __builtin_amdgcn_global_load_lds((const unsigned*)((const char*)(gbase) + (voff)[_i]), (PG8_LAS unsigned*)(lds + (bufoff) + ldsw + _i * 8192), 16, 0, 0); } while (0)
; #define PG8_LDA(dst, b, h) do { _Pragma("unroll") for (int m = 0; m < 4; ++m) _Pragma("unroll") for (int k = 0; k < 2; ++k) dst[m][k] = *(const PG8_LAS bf16x8*)(lds + PG8_SA(b, h) + aoff + m * 2048 + k * 1024); } while (0)
; #define PG8_LDB(dst, b, h) do { _Pragma("unroll") for (int n = 0; n < 2; ++n) _Pragma("unroll") for (int k = 0; k < 2; ++k) dst[n][k] = *(const PG8_LAS bf16x8*)(lds + PG8_SB(b, h) + boff + n * 2048 + k * 1024); } while (0)
; #define PG8_MMA(ai, bj, At, Bt) do { __builtin_amdgcn_s_setprio(1); _Pragma("unroll") for (int m = 0; m < 4; ++m) _Pragma("unroll") for (int n = 0; n < 2; ++n) _Pragma("unroll") for (int k = 0; k < 2; ++k) \
;         acc[ai][bj][m][n] = __builtin_amdgcn_mfma_f32_16x16x32_bf16(Bt[n][k], At[m][k], acc[ai][bj][m][n], 0, 0, 0); __builtin_amdgcn_s_setprio(0); } while (0)
; #define PG8_WAIT_V(n) asm volatile("s_waitcnt vmcnt(" #n ")" ::: "memory")
; #define PG8_WAIT_L(n) asm volatile("s_waitcnt lgkmcnt(" #n ")" ::: "memory")
; #define PG8_BAR __builtin_amdgcn_s_barrier()
; #define PG8_SCHED __builtin_amdgcn_sched_barrier(0)
; template <class Epi, class Sched, bool ALIGN_EPI = false, bool SP2 = false>
; __device__ __forceinline__ void gemm_phase(PG8_LAS unsigned char* lds, const Gemm g, const Sched& S, const Epi& E, int tid_in) {
;     ...
;             PG8_LDB(B0, 1, 0); PG8_LDB(B1, 1, 1); PG8_SCHED; PG8_LDA(At, 1, 0); PG8_STAGE(PG8_SA(0, 1), a2 + hstep, voffA);
;             PG8_WAIT_V(8); PG8_WAIT_L(0); PG8_BAR; PG8_MMA(0, 0, At, B0); PG8_MMA(0, 1, At, B1); PG8_BAR; PG8_SCHED;
;             PG8_LDA(At, 1, 1); PG8_STAGE(PG8_SB(1, 0), b3, voffB); PG8_STAGE(PG8_SB(1, 1), b3 + hstep, voffB); PG8_STAGE(PG8_SA(1, 0), a3, voffA);
;             PG8_WAIT_V(8); PG8_WAIT_L(0); PG8_BAR; PG8_MMA(1, 0, At, B0); PG8_MMA(1, 1, At, B1); PG8_BAR; PG8_SCHED;
	s_add_i32 s61, 0, 0x18000
	s_add_i32 s62, 0, 0x1c000
	s_add_u32 s36, s36, 0x40000
	s_addc_u32 s37, s37, 0
	s_mov_b32 m0, s47
	s_nop 0
	global_load_lds_dwordx4 v152, s[36:37]
	s_mov_b32 m0, s48
	s_nop 0
	global_load_lds_dwordx4 v156, s[36:37]
	v_add_u32_e32 v140, s61, v187
	v_add_u32_e32 v172, s62, v187
	ds_read_b128 v[128:131], v140
	ds_read_b128 v[132:135], v140 offset:1024
	ds_read_b128 v[136:139], v140 offset:2048
	ds_read_b128 v[140:143], v140 offset:3072
	ds_read_b128 v[144:147], v172
	ds_read_b128 v[148:151], v172 offset:1024
	ds_read_b128 v[168:171], v172 offset:2048
	ds_read_b128 v[172:175], v172 offset:3072
	ds_read_b128 v[176:179], v193 offset:32768
	ds_read_b128 v[180:183], v193 offset:33792
	ds_read_b128 v[194:197], v193 offset:34816
	ds_read_b128 v[198:201], v193 offset:35840
	ds_read_b128 v[202:205], v193 offset:36864
	ds_read_b128 v[206:209], v193 offset:37888
	ds_read_b128 v[210:213], v193 offset:38912
	ds_read_b128 v[214:217], v193 offset:39936
	s_waitcnt vmcnt(8)
	s_waitcnt lgkmcnt(0)
	s_barrier
	s_setprio 1
	v_mfma_f32_16x16x32_bf16 v[124:127], v[128:131], v[176:179], v[124:127]
	v_mfma_f32_16x16x32_bf16 v[120:123], v[136:139], v[176:179], v[120:123]
	v_mfma_f32_16x16x32_bf16 v[108:111], v[128:131], v[194:197], v[108:111]
	v_mfma_f32_16x16x32_bf16 v[104:107], v[136:139], v[194:197], v[104:107]
	v_mfma_f32_16x16x32_bf16 v[92:95], v[128:131], v[202:205], v[92:95]
	v_mfma_f32_16x16x32_bf16 v[88:91], v[136:139], v[202:205], v[88:91]
	v_mfma_f32_16x16x32_bf16 v[76:79], v[128:131], v[210:213], v[76:79]
	v_mfma_f32_16x16x32_bf16 v[72:75], v[136:139], v[210:213], v[72:75]
	v_mfma_f32_16x16x32_bf16 v[124:127], v[132:135], v[180:183], v[124:127]
	v_mfma_f32_16x16x32_bf16 v[120:123], v[140:143], v[180:183], v[120:123]
	v_mfma_f32_16x16x32_bf16 v[108:111], v[132:135], v[198:201], v[108:111]
	v_mfma_f32_16x16x32_bf16 v[104:107], v[140:143], v[198:201], v[104:107]
	v_mfma_f32_16x16x32_bf16 v[92:95], v[132:135], v[206:209], v[92:95]
	v_mfma_f32_16x16x32_bf16 v[88:91], v[140:143], v[206:209], v[88:91]
	v_mfma_f32_16x16x32_bf16 v[76:79], v[132:135], v[214:217], v[76:79]
	v_mfma_f32_16x16x32_bf16 v[72:75], v[140:143], v[214:217], v[72:75]
	s_setprio 0
	s_setprio 1
	v_mfma_f32_16x16x32_bf16 v[116:119], v[144:147], v[176:179], v[116:119]
	v_mfma_f32_16x16x32_bf16 v[112:115], v[168:171], v[176:179], v[112:115]
	v_mfma_f32_16x16x32_bf16 v[100:103], v[144:147], v[194:197], v[100:103]
	v_mfma_f32_16x16x32_bf16 v[96:99], v[168:171], v[194:197], v[96:99]
	v_mfma_f32_16x16x32_bf16 v[84:87], v[144:147], v[202:205], v[84:87]
	v_mfma_f32_16x16x32_bf16 v[80:83], v[168:171], v[202:205], v[80:83]
	v_mfma_f32_16x16x32_bf16 v[68:71], v[144:147], v[210:213], v[68:71]
	v_mfma_f32_16x16x32_bf16 v[64:67], v[168:171], v[210:213], v[64:67]
	v_mfma_f32_16x16x32_bf16 v[116:119], v[148:151], v[180:183], v[116:119]
	v_mfma_f32_16x16x32_bf16 v[112:115], v[172:175], v[180:183], v[112:115]
	v_mfma_f32_16x16x32_bf16 v[100:103], v[148:151], v[198:201], v[100:103]
	v_mfma_f32_16x16x32_bf16 v[96:99], v[172:175], v[198:201], v[96:99]
	v_mfma_f32_16x16x32_bf16 v[84:87], v[148:151], v[206:209], v[84:87]
	v_mfma_f32_16x16x32_bf16 v[80:83], v[172:175], v[206:209], v[80:83]
	v_mfma_f32_16x16x32_bf16 v[68:71], v[148:151], v[214:217], v[68:71]
	v_mfma_f32_16x16x32_bf16 v[64:67], v[172:175], v[214:217], v[64:67]
	s_setprio 0
	s_barrier
	s_add_i32 s36, s61, s0
	s_mov_b32 m0, s36
	ds_read_b128 v[176:179], v193 offset:49152
	global_load_lds_dwordx4 v154, s[98:99]
	s_add_i32 m0, s36, 0x2000
	s_add_u32 s34, s34, 0x40080
	s_addc_u32 s35, s35, 0
	s_add_i32 s36, s62, s0
	global_load_lds_dwordx4 v158, s[98:99]
	s_mov_b32 m0, s36
	ds_read_b128 v[180:183], v193 offset:50176
	global_load_lds_dwordx4 v154, s[34:35]
	s_add_i32 m0, s36, 0x2000
	ds_read_b128 v[194:197], v193 offset:51200
	global_load_lds_dwordx4 v158, s[34:35]
	s_mov_b32 m0, s50
	ds_read_b128 v[198:201], v193 offset:52224
	global_load_lds_dwordx4 v152, s[100:101]
	s_mov_b32 m0, s51
	ds_read_b128 v[202:205], v193 offset:53248
	global_load_lds_dwordx4 v156, s[100:101]
	ds_read_b128 v[206:209], v193 offset:54272
	ds_read_b128 v[210:213], v193 offset:55296
	ds_read_b128 v[214:217], v193 offset:56320
	s_waitcnt vmcnt(8)
	s_waitcnt lgkmcnt(0)
	s_barrier
	s_setprio 1
	v_mfma_f32_16x16x32_bf16 v[60:63], v[128:131], v[176:179], v[60:63]
	v_mfma_f32_16x16x32_bf16 v[56:59], v[136:139], v[176:179], v[56:59]
	v_mfma_f32_16x16x32_bf16 v[44:47], v[128:131], v[194:197], v[44:47]
	v_mfma_f32_16x16x32_bf16 v[40:43], v[136:139], v[194:197], v[40:43]
	v_mfma_f32_16x16x32_bf16 v[28:31], v[128:131], v[202:205], v[28:31]
	v_mfma_f32_16x16x32_bf16 v[24:27], v[136:139], v[202:205], v[24:27]
	v_mfma_f32_16x16x32_bf16 v[12:15], v[128:131], v[210:213], v[12:15]
	v_mfma_f32_16x16x32_bf16 v[8:11], v[136:139], v[210:213], v[8:11]
	v_mfma_f32_16x16x32_bf16 v[60:63], v[132:135], v[180:183], v[60:63]
	v_mfma_f32_16x16x32_bf16 v[56:59], v[140:143], v[180:183], v[56:59]
	v_mfma_f32_16x16x32_bf16 v[44:47], v[132:135], v[198:201], v[44:47]
	v_mfma_f32_16x16x32_bf16 v[40:43], v[140:143], v[198:201], v[40:43]
	v_mfma_f32_16x16x32_bf16 v[28:31], v[132:135], v[206:209], v[28:31]
	v_mfma_f32_16x16x32_bf16 v[24:27], v[140:143], v[206:209], v[24:27]
	v_mfma_f32_16x16x32_bf16 v[12:15], v[132:135], v[214:217], v[12:15]
	v_mfma_f32_16x16x32_bf16 v[8:11], v[140:143], v[214:217], v[8:11]
	s_setprio 0
	s_setprio 1
	v_mfma_f32_16x16x32_bf16 v[52:55], v[144:147], v[176:179], v[52:55]
	v_mfma_f32_16x16x32_bf16 v[48:51], v[168:171], v[176:179], v[48:51]
	v_mfma_f32_16x16x32_bf16 v[36:39], v[144:147], v[194:197], v[36:39]
	v_mfma_f32_16x16x32_bf16 v[32:35], v[168:171], v[194:197], v[32:35]
	v_mfma_f32_16x16x32_bf16 v[20:23], v[144:147], v[202:205], v[20:23]
	v_mfma_f32_16x16x32_bf16 v[16:19], v[168:171], v[202:205], v[16:19]
	v_mfma_f32_16x16x32_bf16 v[4:7], v[144:147], v[210:213], v[4:7]
	v_mfma_f32_16x16x32_bf16 v[0:3], v[168:171], v[210:213], v[0:3]
	v_mfma_f32_16x16x32_bf16 v[52:55], v[148:151], v[180:183], v[52:55]
	v_mfma_f32_16x16x32_bf16 v[48:51], v[172:175], v[180:183], v[48:51]
	v_mfma_f32_16x16x32_bf16 v[36:39], v[148:151], v[198:201], v[36:39]
	v_mfma_f32_16x16x32_bf16 v[32:35], v[172:175], v[198:201], v[32:35]
	v_mfma_f32_16x16x32_bf16 v[20:23], v[148:151], v[206:209], v[20:23]
	v_mfma_f32_16x16x32_bf16 v[16:19], v[172:175], v[206:209], v[16:19]
	v_mfma_f32_16x16x32_bf16 v[4:7], v[148:151], v[214:217], v[4:7]
	v_mfma_f32_16x16x32_bf16 v[0:3], v[172:175], v[214:217], v[0:3]
	s_setprio 0
	s_barrier
	s_add_i32 s60, s60, 2
	s_add_u32 s30, s30, 0x100
	s_addc_u32 s31, s31, 0
	s_add_u32 s58, s58, 0x100
	s_addc_u32 s59, s59, 0
	s_cmp_gt_u32 s60, 13
	s_cbranch_scc0 .LBB0_1148
	s_and_b64 vcc, exec, s[18:19]
	s_cbranch_vccz .LBB0_1151
	s_barrier

; #define PG8_STAGE(bufoff, gbase, voff) do { _Pragma("unroll") for (int _i = 0; _i < 2; ++_i) \
;         __builtin_amdgcn_global_load_lds((const unsigned*)((const char*)(gbase) + (voff)[_i]), (PG8_LAS unsigned*)(lds + (bufoff) + ldsw + _i * 8192), 16, 0, 0); } while (0)
; #define PG8_LDA(dst, b, h) do { _Pragma("unroll") for (int m = 0; m < 4; ++m) _Pragma("unroll") for (int k = 0; k < 2; ++k) dst[m][k] = *(const PG8_LAS bf16x8*)(lds + PG8_SA(b, h) + aoff + m * 2048 + k * 1024); } while (0)
; #define PG8_LDB(dst, b, h) do { _Pragma("unroll") for (int n = 0; n < 2; ++n) _Pragma("unroll") for (int k = 0; k < 2; ++k) dst[n][k] = *(const PG8_LAS bf16x8*)(lds + PG8_SB(b, h) + boff + n * 2048 + k * 1024); } while (0)
; #define PG8_MMA(ai, bj, At, Bt) do { __builtin_amdgcn_s_setprio(1); _Pragma("unroll") for (int m = 0; m < 4; ++m) _Pragma("unroll") for (int n = 0; n < 2; ++n) _Pragma("unroll") for (int k = 0; k < 2; ++k) \
;         acc[ai][bj][m][n] = __builtin_amdgcn_mfma_f32_16x16x32_bf16(Bt[n][k], At[m][k], acc[ai][bj][m][n], 0, 0, 0); __builtin_amdgcn_s_setprio(0); } while (0)
; #define PG8_WAIT_V(n) asm volatile("s_waitcnt vmcnt(" #n ")" ::: "memory")
; #define PG8_WAIT_L(n) asm volatile("s_waitcnt lgkmcnt(" #n ")" ::: "memory")
; template <class Epi, class Sched, bool ALIGN_EPI = false, bool SP2 = false>
; __device__ __forceinline__ void gemm_phase(PG8_LAS unsigned char* lds, const Gemm g, const Sched& S, const Epi& E, int tid_in) {
;     ...
;             const bool last = (t == nt - 2);
;             const char* a1 = cA + (size_t)(t + 1) * kstep;
;             const char* a2 = last ? nA : cA + (size_t)(t + 2) * kstep; const char* b2 = last ? nB : cB + (size_t)(t + 2) * kstep;
;             const char* a3 = a2 + kstep; const char* b3 = b2 + kstep;
;             if (last && has_next) S.a_ready(nxt);
;             if constexpr (SP2) {
;             PG8_LDB(B0, 0, 0); PG8_LDB(B1, 0, 1); PG8_SCHED; PG8_LDA(At, 0, 0); PG8_STAGE(PG8_SA(1, 1), a1 + hstep, voffA);
;             PG8_WAIT_V(8); PG8_WAIT_L(0); PG8_BAR; PG8_MMA(0, 0, At, B0); PG8_MMA(0, 1, At, B1); PG8_BAR; PG8_SCHED;
;             PG8_LDA(At, 0, 1); PG8_STAGE(PG8_SB(0, 0), b2, voffB); PG8_STAGE(PG8_SB(0, 1), b2 + hstep, voffB); PG8_STAGE(PG8_SA(0, 0), a2, voffA);
;             PG8_WAIT_V(8); PG8_WAIT_L(0); PG8_BAR; PG8_MMA(1, 0, At, B0); PG8_MMA(1, 1, At, B1); PG8_BAR; PG8_SCHED;
.LBB0_1238:
	s_add_u32 s26, s24, 0xfffc0080
	s_addc_u32 s27, s25, -1
	s_cmp_eq_u32 s58, 12
	s_cselect_b32 s29, s17, s27
	s_cselect_b32 s28, s54, s26
	s_cselect_b32 s27, s15, s57
	s_cselect_b32 s26, s55, s56
	s_add_i32 m0, s23, 0xc000
	ds_read_b128 v[144:147], v154
	global_load_lds_dwordx4 v136, s[24:25]
	s_add_i32 m0, s23, 0xe000
	ds_read_b128 v[158:161], v154 offset:1024
	global_load_lds_dwordx4 v138, s[24:25]
	ds_read_b128 v[162:165], v154 offset:2048
	ds_read_b128 v[166:169], v154 offset:3072
	ds_read_b128 v[170:173], v155
	ds_read_b128 v[174:177], v155 offset:1024
	ds_read_b128 v[178:181], v155 offset:2048
	ds_read_b128 v[182:185], v155 offset:3072
	ds_read_b128 v[186:189], v156
	ds_read_b128 v[190:193], v156 offset:1024
	ds_read_b128 v[194:197], v156 offset:2048
	ds_read_b128 v[198:201], v156 offset:3072
	ds_read_b128 v[202:205], v156 offset:4096
	ds_read_b128 v[206:209], v156 offset:5120
	ds_read_b128 v[210:213], v156 offset:6144
	ds_read_b128 v[214:217], v156 offset:7168
	s_waitcnt vmcnt(8)
	s_waitcnt lgkmcnt(0)
	s_barrier
	s_setprio 1
	v_mfma_f32_16x16x32_bf16 v[124:127], v[144:147], v[186:189], v[124:127]
	v_mfma_f32_16x16x32_bf16 v[120:123], v[162:165], v[186:189], v[120:123]
	v_mfma_f32_16x16x32_bf16 v[108:111], v[144:147], v[194:197], v[108:111]
	v_mfma_f32_16x16x32_bf16 v[104:107], v[162:165], v[194:197], v[104:107]
	v_mfma_f32_16x16x32_bf16 v[92:95], v[144:147], v[202:205], v[92:95]
	v_mfma_f32_16x16x32_bf16 v[88:91], v[162:165], v[202:205], v[88:91]
	v_mfma_f32_16x16x32_bf16 v[76:79], v[144:147], v[210:213], v[76:79]
	v_mfma_f32_16x16x32_bf16 v[72:75], v[162:165], v[210:213], v[72:75]
	v_mfma_f32_16x16x32_bf16 v[124:127], v[158:161], v[190:193], v[124:127]
	v_mfma_f32_16x16x32_bf16 v[120:123], v[166:169], v[190:193], v[120:123]
	v_mfma_f32_16x16x32_bf16 v[108:111], v[158:161], v[198:201], v[108:111]
	v_mfma_f32_16x16x32_bf16 v[104:107], v[166:169], v[198:201], v[104:107]
	v_mfma_f32_16x16x32_bf16 v[92:95], v[158:161], v[206:209], v[92:95]
	v_mfma_f32_16x16x32_bf16 v[88:91], v[166:169], v[206:209], v[88:91]
	v_mfma_f32_16x16x32_bf16 v[76:79], v[158:161], v[214:217], v[76:79]
	v_mfma_f32_16x16x32_bf16 v[72:75], v[166:169], v[214:217], v[72:75]
	s_setprio 0
	s_setprio 1
	v_mfma_f32_16x16x32_bf16 v[116:119], v[170:173], v[186:189], v[116:119]
	v_mfma_f32_16x16x32_bf16 v[112:115], v[178:181], v[186:189], v[112:115]
	v_mfma_f32_16x16x32_bf16 v[100:103], v[170:173], v[194:197], v[100:103]
	v_mfma_f32_16x16x32_bf16 v[96:99], v[178:181], v[194:197], v[96:99]
	v_mfma_f32_16x16x32_bf16 v[84:87], v[170:173], v[202:205], v[84:87]
	v_mfma_f32_16x16x32_bf16 v[80:83], v[178:181], v[202:205], v[80:83]
	v_mfma_f32_16x16x32_bf16 v[68:71], v[170:173], v[210:213], v[68:71]
	v_mfma_f32_16x16x32_bf16 v[64:67], v[178:181], v[210:213], v[64:67]
	v_mfma_f32_16x16x32_bf16 v[116:119], v[174:177], v[190:193], v[116:119]
	v_mfma_f32_16x16x32_bf16 v[112:115], v[182:185], v[190:193], v[112:115]
	v_mfma_f32_16x16x32_bf16 v[100:103], v[174:177], v[198:201], v[100:103]
	v_mfma_f32_16x16x32_bf16 v[96:99], v[182:185], v[198:201], v[96:99]
	v_mfma_f32_16x16x32_bf16 v[84:87], v[174:177], v[206:209], v[84:87]
	v_mfma_f32_16x16x32_bf16 v[80:83], v[182:185], v[206:209], v[80:83]
	v_mfma_f32_16x16x32_bf16 v[68:71], v[174:177], v[214:217], v[68:71]
	v_mfma_f32_16x16x32_bf16 v[64:67], v[182:185], v[214:217], v[64:67]
	s_setprio 0
	s_barrier
	s_add_u32 s98, s26, s10
	s_addc_u32 s99, s27, s11
	s_add_u32 s100, s28, s10
	s_addc_u32 s101, s29, s11
	s_add_i32 s59, s47, s0
	s_mov_b32 m0, s59
	ds_read_b128 v[186:189], v156 offset:16384
	global_load_lds_dwordx4 v132, s[26:27]
	s_add_i32 m0, s59, 0x2000
	s_add_u32 s60, s26, 0x40000
	s_addc_u32 s61, s27, 0
	s_add_i32 s59, s48, s0
	global_load_lds_dwordx4 v128, s[26:27]
	s_mov_b32 m0, s59
	ds_read_b128 v[190:193], v156 offset:17408
	global_load_lds_dwordx4 v132, s[60:61]
	s_add_i32 m0, s59, 0x2000
	ds_read_b128 v[194:197], v156 offset:18432
	global_load_lds_dwordx4 v128, s[60:61]
	s_mov_b32 m0, s23
	ds_read_b128 v[198:201], v156 offset:19456
	global_load_lds_dwordx4 v134, s[28:29]
	s_mov_b32 m0, s37
	ds_read_b128 v[202:205], v156 offset:20480
	global_load_lds_dwordx4 v130, s[28:29]
	ds_read_b128 v[206:209], v156 offset:21504
	ds_read_b128 v[210:213], v156 offset:22528
	ds_read_b128 v[214:217], v156 offset:23552
	s_waitcnt vmcnt(8)
	s_waitcnt lgkmcnt(0)
	s_barrier
	s_setprio 1
	v_mfma_f32_16x16x32_bf16 v[60:63], v[144:147], v[186:189], v[60:63]
	v_mfma_f32_16x16x32_bf16 v[56:59], v[162:165], v[186:189], v[56:59]
	v_mfma_f32_16x16x32_bf16 v[44:47], v[144:147], v[194:197], v[44:47]
	v_mfma_f32_16x16x32_bf16 v[40:43], v[162:165], v[194:197], v[40:43]
	v_mfma_f32_16x16x32_bf16 v[28:31], v[144:147], v[202:205], v[28:31]
	v_mfma_f32_16x16x32_bf16 v[24:27], v[162:165], v[202:205], v[24:27]
	v_mfma_f32_16x16x32_bf16 v[12:15], v[144:147], v[210:213], v[12:15]
	v_mfma_f32_16x16x32_bf16 v[8:11], v[162:165], v[210:213], v[8:11]
	v_mfma_f32_16x16x32_bf16 v[60:63], v[158:161], v[190:193], v[60:63]
	v_mfma_f32_16x16x32_bf16 v[56:59], v[166:169], v[190:193], v[56:59]
	v_mfma_f32_16x16x32_bf16 v[44:47], v[158:161], v[198:201], v[44:47]
	v_mfma_f32_16x16x32_bf16 v[40:43], v[166:169], v[198:201], v[40:43]
	v_mfma_f32_16x16x32_bf16 v[28:31], v[158:161], v[206:209], v[28:31]
	v_mfma_f32_16x16x32_bf16 v[24:27], v[166:169], v[206:209], v[24:27]
	v_mfma_f32_16x16x32_bf16 v[12:15], v[158:161], v[214:217], v[12:15]
	v_mfma_f32_16x16x32_bf16 v[8:11], v[166:169], v[214:217], v[8:11]
	s_setprio 0
	s_setprio 1
	v_mfma_f32_16x16x32_bf16 v[52:55], v[170:173], v[186:189], v[52:55]
	v_mfma_f32_16x16x32_bf16 v[48:51], v[178:181], v[186:189], v[48:51]
	v_mfma_f32_16x16x32_bf16 v[36:39], v[170:173], v[194:197], v[36:39]
	v_mfma_f32_16x16x32_bf16 v[32:35], v[178:181], v[194:197], v[32:35]
	v_mfma_f32_16x16x32_bf16 v[20:23], v[170:173], v[202:205], v[20:23]
	v_mfma_f32_16x16x32_bf16 v[16:19], v[178:181], v[202:205], v[16:19]
	v_mfma_f32_16x16x32_bf16 v[4:7], v[170:173], v[210:213], v[4:7]
	v_mfma_f32_16x16x32_bf16 v[0:3], v[178:181], v[210:213], v[0:3]
	v_mfma_f32_16x16x32_bf16 v[52:55], v[174:177], v[190:193], v[52:55]
	v_mfma_f32_16x16x32_bf16 v[48:51], v[182:185], v[190:193], v[48:51]
	v_mfma_f32_16x16x32_bf16 v[36:39], v[174:177], v[198:201], v[36:39]
	v_mfma_f32_16x16x32_bf16 v[32:35], v[182:185], v[198:201], v[32:35]
	v_mfma_f32_16x16x32_bf16 v[20:23], v[174:177], v[206:209], v[20:23]
	v_mfma_f32_16x16x32_bf16 v[16:19], v[182:185], v[206:209], v[16:19]
	v_mfma_f32_16x16x32_bf16 v[4:7], v[174:177], v[214:217], v[4:7]
	v_mfma_f32_16x16x32_bf16 v[0:3], v[182:185], v[214:217], v[0:3]
	s_setprio 0
	s_barrier
; #define PG8_STAGE(bufoff, gbase, voff) do { _Pragma("unroll") for (int _i = 0; _i < 2; ++_i) \
;         __builtin_amdgcn_global_load_lds((const unsigned*)((const char*)(gbase) + (voff)[_i]), (PG8_LAS unsigned*)(lds + (bufoff) + ldsw + _i * 8192), 16, 0, 0); } while (0)
; #define PG8_LDA(dst, b, h) do { _Pragma("unroll") for (int m = 0; m < 4; ++m) _Pragma("unroll") for (int k = 0; k < 2; ++k) dst[m][k] = *(const PG8_LAS bf16x8*)(lds + PG8_SA(b, h) + aoff + m * 2048 + k * 1024); } while (0)
; #define PG8_LDB(dst, b, h) do { _Pragma("unroll") for (int n = 0; n < 2; ++n) _Pragma("unroll") for (int k = 0; k < 2; ++k) dst[n][k] = *(const PG8_LAS bf16x8*)(lds + PG8_SB(b, h) + boff + n * 2048 + k * 1024); } while (0)
; #define PG8_MMA(ai, bj, At, Bt) do { __builtin_amdgcn_s_setprio(1); _Pragma("unroll") for (int m = 0; m < 4; ++m) _Pragma("unroll") for (int n = 0; n < 2; ++n) _Pragma("unroll") for (int k = 0; k < 2; ++k) \
;         acc[ai][bj][m][n] = __builtin_amdgcn_mfma_f32_16x16x32_bf16(Bt[n][k], At[m][k], acc[ai][bj][m][n], 0, 0, 0); __builtin_amdgcn_s_setprio(0); } while (0)
; #define PG8_WAIT_V(n) asm volatile("s_waitcnt vmcnt(" #n ")" ::: "memory")
; #define PG8_WAIT_L(n) asm volatile("s_waitcnt lgkmcnt(" #n ")" ::: "memory")
; #define PG8_BAR __builtin_amdgcn_s_barrier()
; #define PG8_SCHED __builtin_amdgcn_sched_barrier(0)
; template <class Epi, class Sched, bool ALIGN_EPI = false, bool SP2 = false>
; __device__ __forceinline__ void gemm_phase(PG8_LAS unsigned char* lds, const Gemm g, const Sched& S, const Epi& E, int tid_in) {
;     ...
;             PG8_LDB(B0, 1, 0); PG8_LDB(B1, 1, 1); PG8_SCHED; PG8_LDA(At, 1, 0); PG8_STAGE(PG8_SA(0, 1), a2 + hstep, voffA);
;             PG8_WAIT_V(8); PG8_WAIT_L(0); PG8_BAR; PG8_MMA(0, 0, At, B0); PG8_MMA(0, 1, At, B1); PG8_BAR; PG8_SCHED;
;             PG8_LDA(At, 1, 1); PG8_STAGE(PG8_SB(1, 0), b3, voffB); PG8_STAGE(PG8_SB(1, 1), b3 + hstep, voffB); PG8_STAGE(PG8_SA(1, 0), a3, voffA);
;             PG8_WAIT_V(8); PG8_WAIT_L(0); PG8_BAR; PG8_MMA(1, 0, At, B0); PG8_MMA(1, 1, At, B1); PG8_BAR; PG8_SCHED;
	s_add_i32 s59, 0, 0x18000
	s_add_i32 s60, 0, 0x1c000
	s_add_u32 s28, s28, 0x40000
	s_addc_u32 s29, s29, 0
	s_mov_b32 m0, s38
	v_add_u32_e32 v157, s59, v151
	global_load_lds_dwordx4 v134, s[28:29]
	s_mov_b32 m0, s39
	ds_read_b128 v[144:147], v157
	global_load_lds_dwordx4 v130, s[28:29]
	ds_read_b128 v[158:161], v157 offset:1024
	ds_read_b128 v[162:165], v157 offset:2048
	ds_read_b128 v[166:169], v157 offset:3072
	v_add_u32_e32 v157, s60, v151
	ds_read_b128 v[170:173], v157
	ds_read_b128 v[174:177], v157 offset:1024
	ds_read_b128 v[178:181], v157 offset:2048
	ds_read_b128 v[182:185], v157 offset:3072
	ds_read_b128 v[186:189], v156 offset:32768
	ds_read_b128 v[190:193], v156 offset:33792
	ds_read_b128 v[194:197], v156 offset:34816
	ds_read_b128 v[198:201], v156 offset:35840
	ds_read_b128 v[202:205], v156 offset:36864
	ds_read_b128 v[206:209], v156 offset:37888
	ds_read_b128 v[210:213], v156 offset:38912
	ds_read_b128 v[214:217], v156 offset:39936
	s_waitcnt vmcnt(8)
	s_waitcnt lgkmcnt(0)
	s_barrier
	s_setprio 1
	v_mfma_f32_16x16x32_bf16 v[124:127], v[144:147], v[186:189], v[124:127]
	v_mfma_f32_16x16x32_bf16 v[120:123], v[162:165], v[186:189], v[120:123]
	v_mfma_f32_16x16x32_bf16 v[108:111], v[144:147], v[194:197], v[108:111]
	v_mfma_f32_16x16x32_bf16 v[104:107], v[162:165], v[194:197], v[104:107]
	v_mfma_f32_16x16x32_bf16 v[92:95], v[144:147], v[202:205], v[92:95]
	v_mfma_f32_16x16x32_bf16 v[88:91], v[162:165], v[202:205], v[88:91]
	v_mfma_f32_16x16x32_bf16 v[76:79], v[144:147], v[210:213], v[76:79]
	v_mfma_f32_16x16x32_bf16 v[72:75], v[162:165], v[210:213], v[72:75]
	v_mfma_f32_16x16x32_bf16 v[124:127], v[158:161], v[190:193], v[124:127]
	v_mfma_f32_16x16x32_bf16 v[120:123], v[166:169], v[190:193], v[120:123]
	v_mfma_f32_16x16x32_bf16 v[108:111], v[158:161], v[198:201], v[108:111]
	v_mfma_f32_16x16x32_bf16 v[104:107], v[166:169], v[198:201], v[104:107]
	v_mfma_f32_16x16x32_bf16 v[92:95], v[158:161], v[206:209], v[92:95]
	v_mfma_f32_16x16x32_bf16 v[88:91], v[166:169], v[206:209], v[88:91]
	v_mfma_f32_16x16x32_bf16 v[76:79], v[158:161], v[214:217], v[76:79]
	v_mfma_f32_16x16x32_bf16 v[72:75], v[166:169], v[214:217], v[72:75]
	s_setprio 0
	s_setprio 1
	v_mfma_f32_16x16x32_bf16 v[116:119], v[170:173], v[186:189], v[116:119]
	v_mfma_f32_16x16x32_bf16 v[112:115], v[178:181], v[186:189], v[112:115]
	v_mfma_f32_16x16x32_bf16 v[100:103], v[170:173], v[194:197], v[100:103]
	v_mfma_f32_16x16x32_bf16 v[96:99], v[178:181], v[194:197], v[96:99]
	v_mfma_f32_16x16x32_bf16 v[84:87], v[170:173], v[202:205], v[84:87]
	v_mfma_f32_16x16x32_bf16 v[80:83], v[178:181], v[202:205], v[80:83]
	v_mfma_f32_16x16x32_bf16 v[68:71], v[170:173], v[210:213], v[68:71]
	v_mfma_f32_16x16x32_bf16 v[64:67], v[178:181], v[210:213], v[64:67]
	v_mfma_f32_16x16x32_bf16 v[116:119], v[174:177], v[190:193], v[116:119]
	v_mfma_f32_16x16x32_bf16 v[112:115], v[182:185], v[190:193], v[112:115]
	v_mfma_f32_16x16x32_bf16 v[100:103], v[174:177], v[198:201], v[100:103]
	v_mfma_f32_16x16x32_bf16 v[96:99], v[182:185], v[198:201], v[96:99]
	v_mfma_f32_16x16x32_bf16 v[84:87], v[174:177], v[206:209], v[84:87]
	v_mfma_f32_16x16x32_bf16 v[80:83], v[182:185], v[206:209], v[80:83]
	v_mfma_f32_16x16x32_bf16 v[68:71], v[174:177], v[214:217], v[68:71]
	v_mfma_f32_16x16x32_bf16 v[64:67], v[182:185], v[214:217], v[64:67]
	s_setprio 0
	s_barrier
	s_add_i32 s28, s59, s0
	s_mov_b32 m0, s28
	ds_read_b128 v[186:189], v156 offset:49152
	global_load_lds_dwordx4 v132, s[98:99]
	s_add_i32 m0, s28, 0x2000
	s_add_u32 s26, s26, 0x40080
	s_addc_u32 s27, s27, 0
	s_add_i32 s28, s60, s0
	global_load_lds_dwordx4 v128, s[98:99]
	s_mov_b32 m0, s28
	ds_read_b128 v[190:193], v156 offset:50176
	global_load_lds_dwordx4 v132, s[26:27]
	s_add_i32 m0, s28, 0x2000
	ds_read_b128 v[194:197], v156 offset:51200
	global_load_lds_dwordx4 v128, s[26:27]
	s_mov_b32 m0, s44
	ds_read_b128 v[198:201], v156 offset:52224
	global_load_lds_dwordx4 v134, s[100:101]
	s_mov_b32 m0, s45
	ds_read_b128 v[202:205], v156 offset:53248
	global_load_lds_dwordx4 v130, s[100:101]
	ds_read_b128 v[206:209], v156 offset:54272
	ds_read_b128 v[210:213], v156 offset:55296
	ds_read_b128 v[214:217], v156 offset:56320
	s_waitcnt vmcnt(8)
	s_waitcnt lgkmcnt(0)
	s_barrier
	s_setprio 1
	v_mfma_f32_16x16x32_bf16 v[60:63], v[144:147], v[186:189], v[60:63]
	v_mfma_f32_16x16x32_bf16 v[56:59], v[162:165], v[186:189], v[56:59]
	v_mfma_f32_16x16x32_bf16 v[44:47], v[144:147], v[194:197], v[44:47]
	v_mfma_f32_16x16x32_bf16 v[40:43], v[162:165], v[194:197], v[40:43]
	v_mfma_f32_16x16x32_bf16 v[28:31], v[144:147], v[202:205], v[28:31]
	v_mfma_f32_16x16x32_bf16 v[24:27], v[162:165], v[202:205], v[24:27]
	v_mfma_f32_16x16x32_bf16 v[12:15], v[144:147], v[210:213], v[12:15]
	v_mfma_f32_16x16x32_bf16 v[8:11], v[162:165], v[210:213], v[8:11]
	v_mfma_f32_16x16x32_bf16 v[60:63], v[158:161], v[190:193], v[60:63]
	v_mfma_f32_16x16x32_bf16 v[56:59], v[166:169], v[190:193], v[56:59]
	v_mfma_f32_16x16x32_bf16 v[44:47], v[158:161], v[198:201], v[44:47]
	v_mfma_f32_16x16x32_bf16 v[40:43], v[166:169], v[198:201], v[40:43]
	v_mfma_f32_16x16x32_bf16 v[28:31], v[158:161], v[206:209], v[28:31]
	v_mfma_f32_16x16x32_bf16 v[24:27], v[166:169], v[206:209], v[24:27]
	v_mfma_f32_16x16x32_bf16 v[12:15], v[158:161], v[214:217], v[12:15]
	v_mfma_f32_16x16x32_bf16 v[8:11], v[166:169], v[214:217], v[8:11]
	s_setprio 0
	s_setprio 1
	v_mfma_f32_16x16x32_bf16 v[52:55], v[170:173], v[186:189], v[52:55]
	v_mfma_f32_16x16x32_bf16 v[48:51], v[178:181], v[186:189], v[48:51]
	v_mfma_f32_16x16x32_bf16 v[36:39], v[170:173], v[194:197], v[36:39]
	v_mfma_f32_16x16x32_bf16 v[32:35], v[178:181], v[194:197], v[32:35]
	v_mfma_f32_16x16x32_bf16 v[20:23], v[170:173], v[202:205], v[20:23]
	v_mfma_f32_16x16x32_bf16 v[16:19], v[178:181], v[202:205], v[16:19]
	v_mfma_f32_16x16x32_bf16 v[4:7], v[170:173], v[210:213], v[4:7]
	v_mfma_f32_16x16x32_bf16 v[0:3], v[178:181], v[210:213], v[0:3]
	v_mfma_f32_16x16x32_bf16 v[52:55], v[174:177], v[190:193], v[52:55]
	v_mfma_f32_16x16x32_bf16 v[48:51], v[182:185], v[190:193], v[48:51]
	v_mfma_f32_16x16x32_bf16 v[36:39], v[174:177], v[198:201], v[36:39]
	v_mfma_f32_16x16x32_bf16 v[32:35], v[182:185], v[198:201], v[32:35]
	v_mfma_f32_16x16x32_bf16 v[20:23], v[174:177], v[206:209], v[20:23]
	v_mfma_f32_16x16x32_bf16 v[16:19], v[182:185], v[206:209], v[16:19]
	v_mfma_f32_16x16x32_bf16 v[4:7], v[174:177], v[214:217], v[4:7]
	v_mfma_f32_16x16x32_bf16 v[0:3], v[182:185], v[214:217], v[0:3]
	s_setprio 0
	s_barrier
	s_add_i32 s58, s58, 2
	s_add_u32 s24, s24, 0x100
	s_addc_u32 s25, s25, 0
	s_add_u32 s56, s56, 0x100
	s_addc_u32 s57, s57, 0
	s_cmp_gt_u32 s58, 13
	s_cbranch_scc0 .LBB0_1238
	s_and_b64 vcc, exec, s[12:13]
	s_cbranch_vccz .LBB0_1241
	s_barrier

; #define PG8_STAGE(bufoff, gbase, voff) do { _Pragma("unroll") for (int _i = 0; _i < 2; ++_i) \
;         __builtin_amdgcn_global_load_lds((const unsigned*)((const char*)(gbase) + (voff)[_i]), (PG8_LAS unsigned*)(lds + (bufoff) + ldsw + _i * 8192), 16, 0, 0); } while (0)
; #define PG8_LDA(dst, b, h) do { _Pragma("unroll") for (int m = 0; m < 4; ++m) _Pragma("unroll") for (int k = 0; k < 2; ++k) dst[m][k] = *(const PG8_LAS bf16x8*)(lds + PG8_SA(b, h) + aoff + m * 2048 + k * 1024); } while (0)
; #define PG8_LDB(dst, b, h) do { _Pragma("unroll") for (int n = 0; n < 2; ++n) _Pragma("unroll") for (int k = 0; k < 2; ++k) dst[n][k] = *(const PG8_LAS bf16x8*)(lds + PG8_SB(b, h) + boff + n * 2048 + k * 1024); } while (0)
; #define PG8_MMA(ai, bj, At, Bt) do { __builtin_amdgcn_s_setprio(1); _Pragma("unroll") for (int m = 0; m < 4; ++m) _Pragma("unroll") for (int n = 0; n < 2; ++n) _Pragma("unroll") for (int k = 0; k < 2; ++k) \
;         acc[ai][bj][m][n] = __builtin_amdgcn_mfma_f32_16x16x32_bf16(Bt[n][k], At[m][k], acc[ai][bj][m][n], 0, 0, 0); __builtin_amdgcn_s_setprio(0); } while (0)
; #define PG8_WAIT_V(n) asm volatile("s_waitcnt vmcnt(" #n ")" ::: "memory")
; #define PG8_WAIT_L(n) asm volatile("s_waitcnt lgkmcnt(" #n ")" ::: "memory")
; #define PG8_BAR __builtin_amdgcn_s_barrier()
; #define PG8_SCHED __builtin_amdgcn_sched_barrier(0)
; template <class Epi, class Sched, bool ALIGN_EPI = false, bool SP2 = false>
; __device__ __forceinline__ void gemm_phase(PG8_LAS unsigned char* lds, const Gemm g, const Sched& S, const Epi& E, int tid_in) {
;     ...
;             PG8_LDB(B0, 0, 0); PG8_LDB(B1, 0, 1); PG8_SCHED; PG8_LDA(At, 0, 0); PG8_STAGE(PG8_SA(1, 1), a1 + hstep, voffA);
;             PG8_WAIT_V(8); PG8_WAIT_L(0); PG8_BAR; PG8_MMA(0, 0, At, B0); PG8_MMA(0, 1, At, B1); PG8_BAR; PG8_SCHED;
;             PG8_LDA(At, 0, 1); PG8_STAGE(PG8_SB(0, 0), b2, voffB); PG8_STAGE(PG8_SB(0, 1), b2 + hstep, voffB); PG8_STAGE(PG8_SA(0, 0), a2, voffA);
;             PG8_WAIT_V(8); PG8_WAIT_L(0); PG8_BAR; PG8_MMA(1, 0, At, B0); PG8_MMA(1, 1, At, B1); PG8_BAR; PG8_SCHED;
.LBB0_1321:
	s_add_u32 s2, s20, 0x100
	s_addc_u32 s3, s21, 0
	s_cmp_eq_u32 s50, 40
	s_cselect_b32 s25, s17, s3
	s_cselect_b32 s24, s16, s2
	s_cselect_b32 s23, s19, s49
	s_cselect_b32 s22, s18, s48
	s_add_i32 m0, s34, 0xc000
	ds_read_b128 v[128:131], v195
	global_load_lds_dwordx4 v168, s[20:21]
	s_add_i32 m0, s34, 0xe000
	ds_read_b128 v[132:135], v195 offset:1024
	global_load_lds_dwordx4 v170, s[20:21]
	ds_read_b128 v[136:139], v195 offset:2048
	ds_read_b128 v[140:143], v195 offset:3072
	ds_read_b128 v[144:147], v196
	ds_read_b128 v[148:151], v196 offset:1024
	ds_read_b128 v[152:155], v196 offset:2048
	ds_read_b128 v[156:159], v196 offset:3072
	ds_read_b128 v[176:179], v197
	ds_read_b128 v[180:183], v197 offset:1024
	ds_read_b128 v[184:187], v197 offset:2048
	ds_read_b128 v[188:191], v197 offset:3072
	ds_read_b128 v[198:201], v197 offset:4096
	ds_read_b128 v[202:205], v197 offset:5120
	ds_read_b128 v[206:209], v197 offset:6144
	ds_read_b128 v[210:213], v197 offset:7168
	s_waitcnt vmcnt(8)
	s_waitcnt lgkmcnt(0)
	s_barrier
	s_setprio 1
	v_mfma_f32_16x16x32_bf16 v[120:123], v[128:131], v[176:179], v[120:123]
	v_mfma_f32_16x16x32_bf16 v[124:127], v[136:139], v[176:179], v[124:127]
	v_mfma_f32_16x16x32_bf16 v[104:107], v[128:131], v[184:187], v[104:107]
	v_mfma_f32_16x16x32_bf16 v[108:111], v[136:139], v[184:187], v[108:111]
	v_mfma_f32_16x16x32_bf16 v[88:91], v[128:131], v[198:201], v[88:91]
	v_mfma_f32_16x16x32_bf16 v[92:95], v[136:139], v[198:201], v[92:95]
	v_mfma_f32_16x16x32_bf16 v[72:75], v[128:131], v[206:209], v[72:75]
	v_mfma_f32_16x16x32_bf16 v[76:79], v[136:139], v[206:209], v[76:79]
	v_mfma_f32_16x16x32_bf16 v[120:123], v[132:135], v[180:183], v[120:123]
	v_mfma_f32_16x16x32_bf16 v[124:127], v[140:143], v[180:183], v[124:127]
	v_mfma_f32_16x16x32_bf16 v[104:107], v[132:135], v[188:191], v[104:107]
	v_mfma_f32_16x16x32_bf16 v[108:111], v[140:143], v[188:191], v[108:111]
	v_mfma_f32_16x16x32_bf16 v[88:91], v[132:135], v[202:205], v[88:91]
	v_mfma_f32_16x16x32_bf16 v[92:95], v[140:143], v[202:205], v[92:95]
	v_mfma_f32_16x16x32_bf16 v[72:75], v[132:135], v[210:213], v[72:75]
	v_mfma_f32_16x16x32_bf16 v[76:79], v[140:143], v[210:213], v[76:79]
	s_setprio 0
	s_setprio 1
	v_mfma_f32_16x16x32_bf16 v[112:115], v[144:147], v[176:179], v[112:115]
	v_mfma_f32_16x16x32_bf16 v[116:119], v[152:155], v[176:179], v[116:119]
	v_mfma_f32_16x16x32_bf16 v[96:99], v[144:147], v[184:187], v[96:99]
	v_mfma_f32_16x16x32_bf16 v[100:103], v[152:155], v[184:187], v[100:103]
	v_mfma_f32_16x16x32_bf16 v[80:83], v[144:147], v[198:201], v[80:83]
	v_mfma_f32_16x16x32_bf16 v[84:87], v[152:155], v[198:201], v[84:87]
	v_mfma_f32_16x16x32_bf16 v[64:67], v[144:147], v[206:209], v[64:67]
	v_mfma_f32_16x16x32_bf16 v[68:71], v[152:155], v[206:209], v[68:71]
	v_mfma_f32_16x16x32_bf16 v[112:115], v[148:151], v[180:183], v[112:115]
	v_mfma_f32_16x16x32_bf16 v[116:119], v[156:159], v[180:183], v[116:119]
	v_mfma_f32_16x16x32_bf16 v[96:99], v[148:151], v[188:191], v[96:99]
	v_mfma_f32_16x16x32_bf16 v[100:103], v[156:159], v[188:191], v[100:103]
	v_mfma_f32_16x16x32_bf16 v[80:83], v[148:151], v[202:205], v[80:83]
	v_mfma_f32_16x16x32_bf16 v[84:87], v[156:159], v[202:205], v[84:87]
	v_mfma_f32_16x16x32_bf16 v[64:67], v[148:151], v[210:213], v[64:67]
	v_mfma_f32_16x16x32_bf16 v[68:71], v[156:159], v[210:213], v[68:71]
	s_setprio 0
	s_barrier
	s_add_u32 s98, s22, s10
	s_addc_u32 s99, s23, s11
	s_add_u32 s100, s24, s10
	s_addc_u32 s101, s25, s11
	s_add_i32 s20, s42, s31
	s_mov_b32 m0, s20
	ds_read_b128 v[176:179], v197 offset:16384
	global_load_lds_dwordx4 v162, s[22:23]
	s_add_i32 m0, s20, 0x2000
	s_add_u32 s20, s22, 0xb0000
	s_addc_u32 s21, s23, 0
	s_add_i32 s51, s43, s31
	global_load_lds_dwordx4 v166, s[22:23]
	s_mov_b32 m0, s51
	ds_read_b128 v[180:183], v197 offset:17408
	global_load_lds_dwordx4 v162, s[20:21]
	s_add_i32 m0, s51, 0x2000
	ds_read_b128 v[184:187], v197 offset:18432
	global_load_lds_dwordx4 v166, s[20:21]
	s_mov_b32 m0, s34
	ds_read_b128 v[188:191], v197 offset:19456
	global_load_lds_dwordx4 v160, s[24:25]
	s_mov_b32 m0, s35
	ds_read_b128 v[198:201], v197 offset:20480
	global_load_lds_dwordx4 v164, s[24:25]
	ds_read_b128 v[202:205], v197 offset:21504
	ds_read_b128 v[206:209], v197 offset:22528
	ds_read_b128 v[210:213], v197 offset:23552
	s_waitcnt vmcnt(8)
	s_waitcnt lgkmcnt(0)
	s_barrier
	s_setprio 1
	v_mfma_f32_16x16x32_bf16 v[56:59], v[128:131], v[176:179], v[56:59]
	v_mfma_f32_16x16x32_bf16 v[60:63], v[136:139], v[176:179], v[60:63]
	v_mfma_f32_16x16x32_bf16 v[40:43], v[128:131], v[184:187], v[40:43]
	v_mfma_f32_16x16x32_bf16 v[44:47], v[136:139], v[184:187], v[44:47]
	v_mfma_f32_16x16x32_bf16 v[24:27], v[128:131], v[198:201], v[24:27]
	v_mfma_f32_16x16x32_bf16 v[28:31], v[136:139], v[198:201], v[28:31]
	v_mfma_f32_16x16x32_bf16 v[8:11], v[128:131], v[206:209], v[8:11]
	v_mfma_f32_16x16x32_bf16 v[12:15], v[136:139], v[206:209], v[12:15]
	v_mfma_f32_16x16x32_bf16 v[56:59], v[132:135], v[180:183], v[56:59]
	v_mfma_f32_16x16x32_bf16 v[60:63], v[140:143], v[180:183], v[60:63]
	v_mfma_f32_16x16x32_bf16 v[40:43], v[132:135], v[188:191], v[40:43]
	v_mfma_f32_16x16x32_bf16 v[44:47], v[140:143], v[188:191], v[44:47]
	v_mfma_f32_16x16x32_bf16 v[24:27], v[132:135], v[202:205], v[24:27]
	v_mfma_f32_16x16x32_bf16 v[28:31], v[140:143], v[202:205], v[28:31]
	v_mfma_f32_16x16x32_bf16 v[8:11], v[132:135], v[210:213], v[8:11]
	v_mfma_f32_16x16x32_bf16 v[12:15], v[140:143], v[210:213], v[12:15]
	s_setprio 0
	s_setprio 1
	v_mfma_f32_16x16x32_bf16 v[48:51], v[144:147], v[176:179], v[48:51]
	v_mfma_f32_16x16x32_bf16 v[52:55], v[152:155], v[176:179], v[52:55]
	v_mfma_f32_16x16x32_bf16 v[32:35], v[144:147], v[184:187], v[32:35]
	v_mfma_f32_16x16x32_bf16 v[36:39], v[152:155], v[184:187], v[36:39]
	v_mfma_f32_16x16x32_bf16 v[16:19], v[144:147], v[198:201], v[16:19]
	v_mfma_f32_16x16x32_bf16 v[20:23], v[152:155], v[198:201], v[20:23]
	v_mfma_f32_16x16x32_bf16 v[4:7], v[144:147], v[206:209], v[4:7]
	v_mfma_f32_16x16x32_bf16 v[0:3], v[152:155], v[206:209], v[0:3]
	v_mfma_f32_16x16x32_bf16 v[48:51], v[148:151], v[180:183], v[48:51]
	v_mfma_f32_16x16x32_bf16 v[52:55], v[156:159], v[180:183], v[52:55]
	v_mfma_f32_16x16x32_bf16 v[32:35], v[148:151], v[188:191], v[32:35]
	v_mfma_f32_16x16x32_bf16 v[36:39], v[156:159], v[188:191], v[36:39]
	v_mfma_f32_16x16x32_bf16 v[16:19], v[148:151], v[202:205], v[16:19]
	v_mfma_f32_16x16x32_bf16 v[20:23], v[156:159], v[202:205], v[20:23]
	v_mfma_f32_16x16x32_bf16 v[4:7], v[148:151], v[210:213], v[4:7]
	v_mfma_f32_16x16x32_bf16 v[0:3], v[156:159], v[210:213], v[0:3]
	s_setprio 0
	s_barrier
; #define PG8_STAGE(bufoff, gbase, voff) do { _Pragma("unroll") for (int _i = 0; _i < 2; ++_i) \
;         __builtin_amdgcn_global_load_lds((const unsigned*)((const char*)(gbase) + (voff)[_i]), (PG8_LAS unsigned*)(lds + (bufoff) + ldsw + _i * 8192), 16, 0, 0); } while (0)
; #define PG8_LDA(dst, b, h) do { _Pragma("unroll") for (int m = 0; m < 4; ++m) _Pragma("unroll") for (int k = 0; k < 2; ++k) dst[m][k] = *(const PG8_LAS bf16x8*)(lds + PG8_SA(b, h) + aoff + m * 2048 + k * 1024); } while (0)
; #define PG8_LDB(dst, b, h) do { _Pragma("unroll") for (int n = 0; n < 2; ++n) _Pragma("unroll") for (int k = 0; k < 2; ++k) dst[n][k] = *(const PG8_LAS bf16x8*)(lds + PG8_SB(b, h) + boff + n * 2048 + k * 1024); } while (0)
; #define PG8_MMA(ai, bj, At, Bt) do { __builtin_amdgcn_s_setprio(1); _Pragma("unroll") for (int m = 0; m < 4; ++m) _Pragma("unroll") for (int n = 0; n < 2; ++n) _Pragma("unroll") for (int k = 0; k < 2; ++k) \
;         acc[ai][bj][m][n] = __builtin_amdgcn_mfma_f32_16x16x32_bf16(Bt[n][k], At[m][k], acc[ai][bj][m][n], 0, 0, 0); __builtin_amdgcn_s_setprio(0); } while (0)
; #define PG8_WAIT_V(n) asm volatile("s_waitcnt vmcnt(" #n ")" ::: "memory")
; #define PG8_WAIT_L(n) asm volatile("s_waitcnt lgkmcnt(" #n ")" ::: "memory")
; #define PG8_BAR __builtin_amdgcn_s_barrier()
; #define PG8_SCHED __builtin_amdgcn_sched_barrier(0)
; template <class Epi, class Sched, bool ALIGN_EPI = false, bool SP2 = false>
; __device__ __forceinline__ void gemm_phase(PG8_LAS unsigned char* lds, const Gemm g, const Sched& S, const Epi& E, int tid_in) {
;     ...
;             PG8_LDB(B0, 1, 0); PG8_LDB(B1, 1, 1); PG8_SCHED; PG8_LDA(At, 1, 0); PG8_STAGE(PG8_SA(0, 1), a2 + hstep, voffA);
;             PG8_WAIT_V(8); PG8_WAIT_L(0); PG8_BAR; PG8_MMA(0, 0, At, B0); PG8_MMA(0, 1, At, B1); PG8_BAR; PG8_SCHED;
;             PG8_LDA(At, 1, 1); PG8_STAGE(PG8_SB(1, 0), b3, voffB); PG8_STAGE(PG8_SB(1, 1), b3 + hstep, voffB); PG8_STAGE(PG8_SA(1, 0), a3, voffA);
;             PG8_WAIT_V(8); PG8_WAIT_L(0); PG8_BAR; PG8_MMA(1, 0, At, B0); PG8_MMA(1, 1, At, B1); PG8_BAR; PG8_SCHED;
	s_add_i32 s51, 0, 0x18000
	s_add_i32 s52, 0, 0x1c000
	s_add_u32 s20, s24, 0xb0000
	s_addc_u32 s21, s25, 0
	s_mov_b32 m0, s36
	s_nop 0
	global_load_lds_dwordx4 v160, s[20:21]
	s_mov_b32 m0, s37
	s_nop 0
	global_load_lds_dwordx4 v164, s[20:21]
	v_add_u32_e32 v140, s51, v193
	v_add_u32_e32 v156, s52, v193
	ds_read_b128 v[128:131], v140
	ds_read_b128 v[132:135], v140 offset:1024
	ds_read_b128 v[136:139], v140 offset:2048
	ds_read_b128 v[140:143], v140 offset:3072
	ds_read_b128 v[144:147], v156
	ds_read_b128 v[148:151], v156 offset:1024
	ds_read_b128 v[152:155], v156 offset:2048
	ds_read_b128 v[156:159], v156 offset:3072
	ds_read_b128 v[176:179], v197 offset:32768
	ds_read_b128 v[180:183], v197 offset:33792
	ds_read_b128 v[184:187], v197 offset:34816
	ds_read_b128 v[188:191], v197 offset:35840
	ds_read_b128 v[198:201], v197 offset:36864
	ds_read_b128 v[202:205], v197 offset:37888
	ds_read_b128 v[206:209], v197 offset:38912
	ds_read_b128 v[210:213], v197 offset:39936
	s_waitcnt vmcnt(8)
	s_waitcnt lgkmcnt(0)
	s_barrier
	s_setprio 1
	v_mfma_f32_16x16x32_bf16 v[120:123], v[128:131], v[176:179], v[120:123]
	v_mfma_f32_16x16x32_bf16 v[124:127], v[136:139], v[176:179], v[124:127]
	v_mfma_f32_16x16x32_bf16 v[104:107], v[128:131], v[184:187], v[104:107]
	v_mfma_f32_16x16x32_bf16 v[108:111], v[136:139], v[184:187], v[108:111]
	v_mfma_f32_16x16x32_bf16 v[88:91], v[128:131], v[198:201], v[88:91]
	v_mfma_f32_16x16x32_bf16 v[92:95], v[136:139], v[198:201], v[92:95]
	v_mfma_f32_16x16x32_bf16 v[72:75], v[128:131], v[206:209], v[72:75]
	v_mfma_f32_16x16x32_bf16 v[76:79], v[136:139], v[206:209], v[76:79]
	v_mfma_f32_16x16x32_bf16 v[120:123], v[132:135], v[180:183], v[120:123]
	v_mfma_f32_16x16x32_bf16 v[124:127], v[140:143], v[180:183], v[124:127]
	v_mfma_f32_16x16x32_bf16 v[104:107], v[132:135], v[188:191], v[104:107]
	v_mfma_f32_16x16x32_bf16 v[108:111], v[140:143], v[188:191], v[108:111]
	v_mfma_f32_16x16x32_bf16 v[88:91], v[132:135], v[202:205], v[88:91]
	v_mfma_f32_16x16x32_bf16 v[92:95], v[140:143], v[202:205], v[92:95]
	v_mfma_f32_16x16x32_bf16 v[72:75], v[132:135], v[210:213], v[72:75]
	v_mfma_f32_16x16x32_bf16 v[76:79], v[140:143], v[210:213], v[76:79]
	s_setprio 0
	s_setprio 1
	v_mfma_f32_16x16x32_bf16 v[112:115], v[144:147], v[176:179], v[112:115]
	v_mfma_f32_16x16x32_bf16 v[116:119], v[152:155], v[176:179], v[116:119]
	v_mfma_f32_16x16x32_bf16 v[96:99], v[144:147], v[184:187], v[96:99]
	v_mfma_f32_16x16x32_bf16 v[100:103], v[152:155], v[184:187], v[100:103]
	v_mfma_f32_16x16x32_bf16 v[80:83], v[144:147], v[198:201], v[80:83]
	v_mfma_f32_16x16x32_bf16 v[84:87], v[152:155], v[198:201], v[84:87]
	v_mfma_f32_16x16x32_bf16 v[64:67], v[144:147], v[206:209], v[64:67]
	v_mfma_f32_16x16x32_bf16 v[68:71], v[152:155], v[206:209], v[68:71]
	v_mfma_f32_16x16x32_bf16 v[112:115], v[148:151], v[180:183], v[112:115]
	v_mfma_f32_16x16x32_bf16 v[116:119], v[156:159], v[180:183], v[116:119]
	v_mfma_f32_16x16x32_bf16 v[96:99], v[148:151], v[188:191], v[96:99]
	v_mfma_f32_16x16x32_bf16 v[100:103], v[156:159], v[188:191], v[100:103]
	v_mfma_f32_16x16x32_bf16 v[80:83], v[148:151], v[202:205], v[80:83]
	v_mfma_f32_16x16x32_bf16 v[84:87], v[156:159], v[202:205], v[84:87]
	v_mfma_f32_16x16x32_bf16 v[64:67], v[148:151], v[210:213], v[64:67]
	v_mfma_f32_16x16x32_bf16 v[68:71], v[156:159], v[210:213], v[68:71]
	s_setprio 0
	s_barrier
	s_add_i32 s20, s51, s31
	s_mov_b32 m0, s20
	ds_read_b128 v[176:179], v197 offset:49152
	global_load_lds_dwordx4 v162, s[98:99]
	s_add_i32 m0, s20, 0x2000
	s_add_u32 s20, s22, 0xb0080
	s_addc_u32 s21, s23, 0
	s_add_i32 s22, s52, s31
	global_load_lds_dwordx4 v166, s[98:99]
	s_mov_b32 m0, s22
	ds_read_b128 v[180:183], v197 offset:50176
	global_load_lds_dwordx4 v162, s[20:21]
	s_add_i32 m0, s22, 0x2000
	ds_read_b128 v[184:187], v197 offset:51200
	global_load_lds_dwordx4 v166, s[20:21]
	s_mov_b32 m0, s39
	ds_read_b128 v[188:191], v197 offset:52224
	global_load_lds_dwordx4 v160, s[100:101]
	s_mov_b32 m0, s40
	ds_read_b128 v[198:201], v197 offset:53248
	global_load_lds_dwordx4 v164, s[100:101]
	ds_read_b128 v[202:205], v197 offset:54272
	ds_read_b128 v[206:209], v197 offset:55296
	ds_read_b128 v[210:213], v197 offset:56320
	s_waitcnt vmcnt(8)
	s_waitcnt lgkmcnt(0)
	s_barrier
	s_setprio 1
	v_mfma_f32_16x16x32_bf16 v[56:59], v[128:131], v[176:179], v[56:59]
	v_mfma_f32_16x16x32_bf16 v[60:63], v[136:139], v[176:179], v[60:63]
	v_mfma_f32_16x16x32_bf16 v[40:43], v[128:131], v[184:187], v[40:43]
	v_mfma_f32_16x16x32_bf16 v[44:47], v[136:139], v[184:187], v[44:47]
	v_mfma_f32_16x16x32_bf16 v[24:27], v[128:131], v[198:201], v[24:27]
	v_mfma_f32_16x16x32_bf16 v[28:31], v[136:139], v[198:201], v[28:31]
	v_mfma_f32_16x16x32_bf16 v[8:11], v[128:131], v[206:209], v[8:11]
	v_mfma_f32_16x16x32_bf16 v[12:15], v[136:139], v[206:209], v[12:15]
	v_mfma_f32_16x16x32_bf16 v[56:59], v[132:135], v[180:183], v[56:59]
	v_mfma_f32_16x16x32_bf16 v[60:63], v[140:143], v[180:183], v[60:63]
	v_mfma_f32_16x16x32_bf16 v[40:43], v[132:135], v[188:191], v[40:43]
	v_mfma_f32_16x16x32_bf16 v[44:47], v[140:143], v[188:191], v[44:47]
	v_mfma_f32_16x16x32_bf16 v[24:27], v[132:135], v[202:205], v[24:27]
	v_mfma_f32_16x16x32_bf16 v[28:31], v[140:143], v[202:205], v[28:31]
	v_mfma_f32_16x16x32_bf16 v[8:11], v[132:135], v[210:213], v[8:11]
	v_mfma_f32_16x16x32_bf16 v[12:15], v[140:143], v[210:213], v[12:15]
	s_setprio 0
	s_setprio 1
	v_mfma_f32_16x16x32_bf16 v[48:51], v[144:147], v[176:179], v[48:51]
	v_mfma_f32_16x16x32_bf16 v[52:55], v[152:155], v[176:179], v[52:55]
	v_mfma_f32_16x16x32_bf16 v[32:35], v[144:147], v[184:187], v[32:35]
	v_mfma_f32_16x16x32_bf16 v[36:39], v[152:155], v[184:187], v[36:39]
	v_mfma_f32_16x16x32_bf16 v[16:19], v[144:147], v[198:201], v[16:19]
	v_mfma_f32_16x16x32_bf16 v[20:23], v[152:155], v[198:201], v[20:23]
	v_mfma_f32_16x16x32_bf16 v[4:7], v[144:147], v[206:209], v[4:7]
	v_mfma_f32_16x16x32_bf16 v[0:3], v[152:155], v[206:209], v[0:3]
	v_mfma_f32_16x16x32_bf16 v[48:51], v[148:151], v[180:183], v[48:51]
	v_mfma_f32_16x16x32_bf16 v[52:55], v[156:159], v[180:183], v[52:55]
	v_mfma_f32_16x16x32_bf16 v[32:35], v[148:151], v[188:191], v[32:35]
	v_mfma_f32_16x16x32_bf16 v[36:39], v[156:159], v[188:191], v[36:39]
	v_mfma_f32_16x16x32_bf16 v[16:19], v[148:151], v[202:205], v[16:19]
	v_mfma_f32_16x16x32_bf16 v[20:23], v[156:159], v[202:205], v[20:23]
	v_mfma_f32_16x16x32_bf16 v[4:7], v[148:151], v[210:213], v[4:7]
	v_mfma_f32_16x16x32_bf16 v[0:3], v[156:159], v[210:213], v[0:3]
	s_setprio 0
	s_barrier
	s_add_i32 s50, s50, 2
	s_add_u32 s48, s48, 0x100
	s_addc_u32 s49, s49, 0
	s_cmp_gt_u32 s50, 41
	s_mov_b64 s[20:21], s[2:3]
	s_cbranch_scc0 .LBB0_1321
	s_and_b64 vcc, exec, s[12:13]
	s_cbranch_vccz .LBB0_1324
	s_barrier
